# chain order + s_setprio 1 only during the load segments (ds_read + LDS-DMA issue), priority 0 during MFMA blocks
# baseline (speedup 1.0000x reference)
; #define PG8_LDA(dst, b, h) do { _Pragma("unroll") for (int m = 0; m < 4; ++m) _Pragma("unroll") for (int k = 0; k < 2; ++k) dst[m][k] = *(const PG8_LAS bf16x8*)(lds + PG8_SA(b, h) + aoff + m * 2048 + k * 1024); } while (0)
; #define PG8_LDB(dst, b, h) do { _Pragma("unroll") for (int n = 0; n < 2; ++n) _Pragma("unroll") for (int k = 0; k < 2; ++k) dst[n][k] = *(const PG8_LAS bf16x8*)(lds + PG8_SB(b, h) + boff + n * 2048 + k * 1024); } while (0)
; #define PG8_MMA(ai, bj, At, Bt) do { __builtin_amdgcn_s_setprio(1); _Pragma("unroll") for (int m = 0; m < 4; ++m) _Pragma("unroll") for (int n = 0; n < 2; ++n) _Pragma("unroll") for (int k = 0; k < 2; ++k) \
;         acc[ai][bj][m][n] = __builtin_amdgcn_mfma_f32_16x16x32_bf16(Bt[n][k], At[m][k], acc[ai][bj][m][n], 0, 0, 0); __builtin_amdgcn_s_setprio(0); } while (0)
; #define PG8_WAIT_V(n) asm volatile("s_waitcnt vmcnt(" #n ")" ::: "memory")
; #define PG8_WAIT_L(n) asm volatile("s_waitcnt lgkmcnt(" #n ")" ::: "memory")
; #define PG8_BAR __builtin_amdgcn_s_barrier()
; #define PG8_SCHED __builtin_amdgcn_sched_barrier(0)
; template <class Epi, class Sched, bool ALIGN_EPI = false, bool SP2 = false>
; __device__ __forceinline__ void gemm_phase(PG8_LAS unsigned char* lds, const Gemm g, const Sched& S, const Epi& E, const int tid) {
;     ...
;             PG8_LDB(B0, 0, 0); PG8_LDB(B1, 0, 1); PG8_SCHED; PG8_LDA(At, 0, 0); PG8_STAGE(PG8_SA(1, 1), a1 + hstepA, voffA);
;             PG8_WAIT_V(8); PG8_WAIT_L(0); PG8_BAR; PG8_MMA(0, 0, At, B0); PG8_MMA(0, 1, At, B1); PG8_BAR; PG8_SCHED;
;             PG8_LDA(At, 0, 1); PG8_STAGE(PG8_SB(0, 0), b2, voffB); PG8_STAGE(PG8_SB(0, 1), b2 + hstepB, voffB); PG8_STAGE(PG8_SA(0, 0), a2, voffA);
;             PG8_WAIT_V(8); PG8_WAIT_L(0); PG8_BAR; PG8_MMA(1, 0, At, B0); PG8_MMA(1, 1, At, B1); PG8_BAR; PG8_SCHED;
.LBB0_380:
	s_or_b64 exec, exec, s[34:35]
	v_add_u32_e32 v145, 0x10000, v154
	s_setprio 1
	ds_read_b128 v[156:159], v145
	ds_read_b128 v[160:163], v145 offset:1024
	ds_read_b128 v[164:167], v145 offset:2048
	ds_read_b128 v[168:171], v145 offset:3072
	v_add_u32_e32 v145, 0x14000, v154
	s_add_u32 s34, s28, 0x100
	ds_read_b128 v[172:175], v145
	ds_read_b128 v[176:179], v145 offset:1024
	ds_read_b128 v[180:183], v145 offset:2048
	ds_read_b128 v[184:187], v145 offset:3072
	s_addc_u32 s35, s29, 0
	s_and_b64 s[30:31], s[30:31], exec
	s_cselect_b32 s42, s91, s34
	s_cselect_b32 s43, s17, s35
	s_cselect_b32 s31, s15, s97
	s_cselect_b32 s30, s95, s96
	s_add_u32 s38, s42, 0x80
	s_addc_u32 s39, s43, 0
	s_add_u32 s40, s30, 0x80
	s_addc_u32 s41, s31, 0
	ds_read_b128 v[188:191], v155
	ds_read_b128 v[192:195], v155 offset:1024
	ds_read_b128 v[196:199], v155 offset:2048
	ds_read_b128 v[200:203], v155 offset:3072
	ds_read_b128 v[204:207], v155 offset:4096
	ds_read_b128 v[208:211], v155 offset:5120
	ds_read_b128 v[212:215], v155 offset:6144
	ds_read_b128 v[216:219], v155 offset:7168
	s_add_u32 s28, s28, 0x80080
	s_addc_u32 s29, s29, 0
	s_mov_b32 m0, s69
	s_nop 0
	global_load_lds_dwordx4 v149, s[28:29]
	s_nop 0
	s_mov_b32 m0, s58
	s_nop 0
	global_load_lds_dwordx4 v151, s[28:29]
	s_waitcnt vmcnt(8)
	s_waitcnt lgkmcnt(0)
	s_setprio 0
	s_barrier
	v_mfma_f32_16x16x32_bf16 v[126:129], v[156:159], v[188:191], v[126:129]
	v_mfma_f32_16x16x32_bf16 v[126:129], v[160:163], v[192:195], v[126:129]
	v_mfma_f32_16x16x32_bf16 v[122:125], v[164:167], v[188:191], v[122:125]
	v_mfma_f32_16x16x32_bf16 v[122:125], v[168:171], v[192:195], v[122:125]
	v_mfma_f32_16x16x32_bf16 v[110:113], v[156:159], v[196:199], v[110:113]
	v_mfma_f32_16x16x32_bf16 v[110:113], v[160:163], v[200:203], v[110:113]
	v_mfma_f32_16x16x32_bf16 v[106:109], v[164:167], v[196:199], v[106:109]
	v_mfma_f32_16x16x32_bf16 v[106:109], v[168:171], v[200:203], v[106:109]
	v_mfma_f32_16x16x32_bf16 v[94:97], v[156:159], v[204:207], v[94:97]
	v_mfma_f32_16x16x32_bf16 v[94:97], v[160:163], v[208:211], v[94:97]
	v_mfma_f32_16x16x32_bf16 v[90:93], v[164:167], v[204:207], v[90:93]
	v_mfma_f32_16x16x32_bf16 v[90:93], v[168:171], v[208:211], v[90:93]
	v_mfma_f32_16x16x32_bf16 v[78:81], v[156:159], v[212:215], v[78:81]
	v_mfma_f32_16x16x32_bf16 v[78:81], v[160:163], v[216:219], v[78:81]
	v_mfma_f32_16x16x32_bf16 v[74:77], v[164:167], v[212:215], v[74:77]
	v_mfma_f32_16x16x32_bf16 v[74:77], v[168:171], v[216:219], v[74:77]
	v_mfma_f32_16x16x32_bf16 v[118:121], v[172:175], v[188:191], v[118:121]
	v_mfma_f32_16x16x32_bf16 v[118:121], v[176:179], v[192:195], v[118:121]
	v_mfma_f32_16x16x32_bf16 v[114:117], v[180:183], v[188:191], v[114:117]
	v_mfma_f32_16x16x32_bf16 v[114:117], v[184:187], v[192:195], v[114:117]
	v_mfma_f32_16x16x32_bf16 v[102:105], v[172:175], v[196:199], v[102:105]
	v_mfma_f32_16x16x32_bf16 v[102:105], v[176:179], v[200:203], v[102:105]
	v_mfma_f32_16x16x32_bf16 v[98:101], v[180:183], v[196:199], v[98:101]
	v_mfma_f32_16x16x32_bf16 v[98:101], v[184:187], v[200:203], v[98:101]
	v_mfma_f32_16x16x32_bf16 v[86:89], v[172:175], v[204:207], v[86:89]
	v_mfma_f32_16x16x32_bf16 v[86:89], v[176:179], v[208:211], v[86:89]
	v_mfma_f32_16x16x32_bf16 v[82:85], v[180:183], v[204:207], v[82:85]
	v_mfma_f32_16x16x32_bf16 v[82:85], v[184:187], v[208:211], v[82:85]
	v_mfma_f32_16x16x32_bf16 v[70:73], v[172:175], v[212:215], v[70:73]
	v_mfma_f32_16x16x32_bf16 v[70:73], v[176:179], v[216:219], v[70:73]
	v_mfma_f32_16x16x32_bf16 v[66:69], v[180:183], v[212:215], v[66:69]
	v_mfma_f32_16x16x32_bf16 v[66:69], v[184:187], v[216:219], v[66:69]
	s_barrier
	s_setprio 1
	ds_read_b128 v[188:191], v155 offset:16384
	ds_read_b128 v[192:195], v155 offset:17408
	ds_read_b128 v[196:199], v155 offset:18432
	ds_read_b128 v[200:203], v155 offset:19456
	ds_read_b128 v[204:207], v155 offset:20480
	ds_read_b128 v[208:211], v155 offset:21504
	ds_read_b128 v[212:215], v155 offset:22528
	ds_read_b128 v[216:219], v155 offset:23552
	s_mov_b32 m0, s23
	s_nop 0
	global_load_lds_dwordx4 v150, s[30:31]
	s_add_u32 s28, s30, 0x80000
	s_mov_b32 m0, s25
	s_nop 0
	global_load_lds_dwordx4 v152, s[30:31]
	s_addc_u32 s29, s31, 0
	s_mov_b32 m0, s48
	s_nop 0
	global_load_lds_dwordx4 v150, s[28:29]
	s_nop 0
	s_mov_b32 m0, s49
	s_nop 0
	global_load_lds_dwordx4 v152, s[28:29]
	s_nop 0
	s_mov_b32 m0, s10
	s_nop 0
	global_load_lds_dwordx4 v149, s[42:43]
	s_nop 0
	s_mov_b32 m0, s50
	s_nop 0
	global_load_lds_dwordx4 v151, s[42:43]
	s_waitcnt vmcnt(8)
	s_waitcnt lgkmcnt(0)
	s_setprio 0
	s_barrier
; #define PG8_LDA(dst, b, h) do { _Pragma("unroll") for (int m = 0; m < 4; ++m) _Pragma("unroll") for (int k = 0; k < 2; ++k) dst[m][k] = *(const PG8_LAS bf16x8*)(lds + PG8_SA(b, h) + aoff + m * 2048 + k * 1024); } while (0)
; #define PG8_LDB(dst, b, h) do { _Pragma("unroll") for (int n = 0; n < 2; ++n) _Pragma("unroll") for (int k = 0; k < 2; ++k) dst[n][k] = *(const PG8_LAS bf16x8*)(lds + PG8_SB(b, h) + boff + n * 2048 + k * 1024); } while (0)
; #define PG8_MMA(ai, bj, At, Bt) do { __builtin_amdgcn_s_setprio(1); _Pragma("unroll") for (int m = 0; m < 4; ++m) _Pragma("unroll") for (int n = 0; n < 2; ++n) _Pragma("unroll") for (int k = 0; k < 2; ++k) \
;         acc[ai][bj][m][n] = __builtin_amdgcn_mfma_f32_16x16x32_bf16(Bt[n][k], At[m][k], acc[ai][bj][m][n], 0, 0, 0); __builtin_amdgcn_s_setprio(0); } while (0)
; #define PG8_WAIT_V(n) asm volatile("s_waitcnt vmcnt(" #n ")" ::: "memory")
; #define PG8_WAIT_L(n) asm volatile("s_waitcnt lgkmcnt(" #n ")" ::: "memory")
; #define PG8_BAR __builtin_amdgcn_s_barrier()
; #define PG8_SCHED __builtin_amdgcn_sched_barrier(0)
; template <class Epi, class Sched, bool ALIGN_EPI = false, bool SP2 = false>
; __device__ __forceinline__ void gemm_phase(PG8_LAS unsigned char* lds, const Gemm g, const Sched& S, const Epi& E, const int tid) {
;     ...
;             PG8_WAIT_V(8); PG8_WAIT_L(0); PG8_BAR; PG8_MMA(1, 0, At, B0); PG8_MMA(1, 1, At, B1); PG8_BAR; PG8_SCHED;
;             PG8_LDB(B0, 1, 0); PG8_LDB(B1, 1, 1); PG8_SCHED; PG8_LDA(At, 1, 0); PG8_STAGE(PG8_SA(0, 1), a2 + hstepA, voffA);
;             PG8_WAIT_V(8); PG8_WAIT_L(0); PG8_BAR; PG8_MMA(0, 0, At, B0); PG8_MMA(0, 1, At, B1); PG8_BAR; PG8_SCHED;
	v_mfma_f32_16x16x32_bf16 v[62:65], v[156:159], v[188:191], v[62:65]
	v_mfma_f32_16x16x32_bf16 v[62:65], v[160:163], v[192:195], v[62:65]
	v_mfma_f32_16x16x32_bf16 v[58:61], v[164:167], v[188:191], v[58:61]
	v_mfma_f32_16x16x32_bf16 v[58:61], v[168:171], v[192:195], v[58:61]
	v_mfma_f32_16x16x32_bf16 v[46:49], v[156:159], v[196:199], v[46:49]
	v_mfma_f32_16x16x32_bf16 v[46:49], v[160:163], v[200:203], v[46:49]
	v_mfma_f32_16x16x32_bf16 v[42:45], v[164:167], v[196:199], v[42:45]
	v_mfma_f32_16x16x32_bf16 v[42:45], v[168:171], v[200:203], v[42:45]
	v_mfma_f32_16x16x32_bf16 v[30:33], v[156:159], v[204:207], v[30:33]
	v_mfma_f32_16x16x32_bf16 v[30:33], v[160:163], v[208:211], v[30:33]
	v_mfma_f32_16x16x32_bf16 v[26:29], v[164:167], v[204:207], v[26:29]
	v_mfma_f32_16x16x32_bf16 v[26:29], v[168:171], v[208:211], v[26:29]
	v_mfma_f32_16x16x32_bf16 v[14:17], v[156:159], v[212:215], v[14:17]
	v_mfma_f32_16x16x32_bf16 v[14:17], v[160:163], v[216:219], v[14:17]
	v_mfma_f32_16x16x32_bf16 v[10:13], v[164:167], v[212:215], v[10:13]
	v_mfma_f32_16x16x32_bf16 v[10:13], v[168:171], v[216:219], v[10:13]
	v_mfma_f32_16x16x32_bf16 v[54:57], v[172:175], v[188:191], v[54:57]
	v_mfma_f32_16x16x32_bf16 v[54:57], v[176:179], v[192:195], v[54:57]
	v_mfma_f32_16x16x32_bf16 v[50:53], v[180:183], v[188:191], v[50:53]
	v_mfma_f32_16x16x32_bf16 v[50:53], v[184:187], v[192:195], v[50:53]
	v_mfma_f32_16x16x32_bf16 v[38:41], v[172:175], v[196:199], v[38:41]
	v_mfma_f32_16x16x32_bf16 v[38:41], v[176:179], v[200:203], v[38:41]
	v_mfma_f32_16x16x32_bf16 v[34:37], v[180:183], v[196:199], v[34:37]
	v_mfma_f32_16x16x32_bf16 v[34:37], v[184:187], v[200:203], v[34:37]
	v_mfma_f32_16x16x32_bf16 v[22:25], v[172:175], v[204:207], v[22:25]
	v_mfma_f32_16x16x32_bf16 v[22:25], v[176:179], v[208:211], v[22:25]
	v_mfma_f32_16x16x32_bf16 v[18:21], v[180:183], v[204:207], v[18:21]
	v_mfma_f32_16x16x32_bf16 v[18:21], v[184:187], v[208:211], v[18:21]
	v_mfma_f32_16x16x32_bf16 v[6:9], v[172:175], v[212:215], v[6:9]
	v_mfma_f32_16x16x32_bf16 v[6:9], v[176:179], v[216:219], v[6:9]
	v_mfma_f32_16x16x32_bf16 v[2:5], v[180:183], v[212:215], v[2:5]
	v_mfma_f32_16x16x32_bf16 v[2:5], v[184:187], v[216:219], v[2:5]
	s_barrier
	v_add_u32_e32 v145, 0x18000, v154
	s_setprio 1
	ds_read_b128 v[156:159], v145
	ds_read_b128 v[160:163], v145 offset:1024
	ds_read_b128 v[164:167], v145 offset:2048
	ds_read_b128 v[168:171], v145 offset:3072
	v_add_u32_e32 v145, 0x1c000, v154
	ds_read_b128 v[172:175], v145
	ds_read_b128 v[176:179], v145 offset:1024
	ds_read_b128 v[180:183], v145 offset:2048
	ds_read_b128 v[184:187], v145 offset:3072
	ds_read_b128 v[188:191], v155 offset:32768
	ds_read_b128 v[192:195], v155 offset:33792
	ds_read_b128 v[196:199], v155 offset:34816
	ds_read_b128 v[200:203], v155 offset:35840
	ds_read_b128 v[204:207], v155 offset:36864
	ds_read_b128 v[208:211], v155 offset:37888
	ds_read_b128 v[212:215], v155 offset:38912
	ds_read_b128 v[216:219], v155 offset:39936
	s_add_u32 s28, s42, 0x80000
	s_addc_u32 s29, s43, 0
	s_mov_b32 m0, s51
	s_nop 0
	global_load_lds_dwordx4 v149, s[28:29]
	s_nop 0
	s_mov_b32 m0, s54
	s_nop 0
	global_load_lds_dwordx4 v151, s[28:29]
	s_waitcnt vmcnt(8)
	s_waitcnt lgkmcnt(0)
	s_setprio 0
	s_barrier
	v_mfma_f32_16x16x32_bf16 v[126:129], v[156:159], v[188:191], v[126:129]
	v_mfma_f32_16x16x32_bf16 v[126:129], v[160:163], v[192:195], v[126:129]
	v_mfma_f32_16x16x32_bf16 v[122:125], v[164:167], v[188:191], v[122:125]
	v_mfma_f32_16x16x32_bf16 v[122:125], v[168:171], v[192:195], v[122:125]
	v_mfma_f32_16x16x32_bf16 v[110:113], v[156:159], v[196:199], v[110:113]
	v_mfma_f32_16x16x32_bf16 v[110:113], v[160:163], v[200:203], v[110:113]
	v_mfma_f32_16x16x32_bf16 v[106:109], v[164:167], v[196:199], v[106:109]
	v_mfma_f32_16x16x32_bf16 v[106:109], v[168:171], v[200:203], v[106:109]
	v_mfma_f32_16x16x32_bf16 v[94:97], v[156:159], v[204:207], v[94:97]
	v_mfma_f32_16x16x32_bf16 v[94:97], v[160:163], v[208:211], v[94:97]
	v_mfma_f32_16x16x32_bf16 v[90:93], v[164:167], v[204:207], v[90:93]
	v_mfma_f32_16x16x32_bf16 v[90:93], v[168:171], v[208:211], v[90:93]
	v_mfma_f32_16x16x32_bf16 v[78:81], v[156:159], v[212:215], v[78:81]
	v_mfma_f32_16x16x32_bf16 v[78:81], v[160:163], v[216:219], v[78:81]
	v_mfma_f32_16x16x32_bf16 v[74:77], v[164:167], v[212:215], v[74:77]
	v_mfma_f32_16x16x32_bf16 v[74:77], v[168:171], v[216:219], v[74:77]
	v_mfma_f32_16x16x32_bf16 v[118:121], v[172:175], v[188:191], v[118:121]
	v_mfma_f32_16x16x32_bf16 v[118:121], v[176:179], v[192:195], v[118:121]
	v_mfma_f32_16x16x32_bf16 v[114:117], v[180:183], v[188:191], v[114:117]
	v_mfma_f32_16x16x32_bf16 v[114:117], v[184:187], v[192:195], v[114:117]
	v_mfma_f32_16x16x32_bf16 v[102:105], v[172:175], v[196:199], v[102:105]
	v_mfma_f32_16x16x32_bf16 v[102:105], v[176:179], v[200:203], v[102:105]
	v_mfma_f32_16x16x32_bf16 v[98:101], v[180:183], v[196:199], v[98:101]
	v_mfma_f32_16x16x32_bf16 v[98:101], v[184:187], v[200:203], v[98:101]
	v_mfma_f32_16x16x32_bf16 v[86:89], v[172:175], v[204:207], v[86:89]
	v_mfma_f32_16x16x32_bf16 v[86:89], v[176:179], v[208:211], v[86:89]
	v_mfma_f32_16x16x32_bf16 v[82:85], v[180:183], v[204:207], v[82:85]
	v_mfma_f32_16x16x32_bf16 v[82:85], v[184:187], v[208:211], v[82:85]
	v_mfma_f32_16x16x32_bf16 v[70:73], v[172:175], v[212:215], v[70:73]
	v_mfma_f32_16x16x32_bf16 v[70:73], v[176:179], v[216:219], v[70:73]
	v_mfma_f32_16x16x32_bf16 v[66:69], v[180:183], v[212:215], v[66:69]
	v_mfma_f32_16x16x32_bf16 v[66:69], v[184:187], v[216:219], v[66:69]
	s_barrier
; #define PG8_LDA(dst, b, h) do { _Pragma("unroll") for (int m = 0; m < 4; ++m) _Pragma("unroll") for (int k = 0; k < 2; ++k) dst[m][k] = *(const PG8_LAS bf16x8*)(lds + PG8_SA(b, h) + aoff + m * 2048 + k * 1024); } while (0)
; #define PG8_MMA(ai, bj, At, Bt) do { __builtin_amdgcn_s_setprio(1); _Pragma("unroll") for (int m = 0; m < 4; ++m) _Pragma("unroll") for (int n = 0; n < 2; ++n) _Pragma("unroll") for (int k = 0; k < 2; ++k) \
;         acc[ai][bj][m][n] = __builtin_amdgcn_mfma_f32_16x16x32_bf16(Bt[n][k], At[m][k], acc[ai][bj][m][n], 0, 0, 0); __builtin_amdgcn_s_setprio(0); } while (0)
; #define PG8_WAIT_V(n) asm volatile("s_waitcnt vmcnt(" #n ")" ::: "memory")
; #define PG8_WAIT_L(n) asm volatile("s_waitcnt lgkmcnt(" #n ")" ::: "memory")
; #define PG8_BAR __builtin_amdgcn_s_barrier()
; #define PG8_SCHED __builtin_amdgcn_sched_barrier(0)
; template <class Epi, class Sched, bool ALIGN_EPI = false, bool SP2 = false>
; __device__ __forceinline__ void gemm_phase(PG8_LAS unsigned char* lds, const Gemm g, const Sched& S, const Epi& E, const int tid) {
;     ...
;         for (int t = 0; t < nt; t += 2) {
;     ...
;             PG8_LDA(At, 1, 1); PG8_STAGE(PG8_SB(1, 0), b3, voffB); PG8_STAGE(PG8_SB(1, 1), b3 + hstepB, voffB); PG8_STAGE(PG8_SA(1, 0), a3, voffA);
;             PG8_WAIT_V(8); PG8_WAIT_L(0); PG8_BAR; PG8_MMA(1, 0, At, B0); PG8_MMA(1, 1, At, B1); PG8_BAR; PG8_SCHED;
	s_setprio 1
	ds_read_b128 v[188:191], v155 offset:49152
	ds_read_b128 v[192:195], v155 offset:50176
	ds_read_b128 v[196:199], v155 offset:51200
	ds_read_b128 v[200:203], v155 offset:52224
	ds_read_b128 v[204:207], v155 offset:53248
	ds_read_b128 v[208:211], v155 offset:54272
	ds_read_b128 v[212:215], v155 offset:55296
	ds_read_b128 v[216:219], v155 offset:56320
	s_mov_b32 m0, s55
	s_nop 0
	global_load_lds_dwordx4 v150, s[40:41]
	s_add_u32 s28, s30, 0x80080
	s_mov_b32 m0, s56
	s_nop 0
	global_load_lds_dwordx4 v152, s[40:41]
	s_addc_u32 s29, s31, 0
	s_mov_b32 m0, s64
	s_nop 0
	global_load_lds_dwordx4 v150, s[28:29]
	s_nop 0
	s_mov_b32 m0, s65
	s_nop 0
	global_load_lds_dwordx4 v152, s[28:29]
	s_nop 0
	s_mov_b32 m0, s57
	s_nop 0
	global_load_lds_dwordx4 v149, s[38:39]
	s_nop 0
	s_mov_b32 m0, s61
	s_nop 0
	global_load_lds_dwordx4 v151, s[38:39]
	s_waitcnt vmcnt(8)
	s_waitcnt lgkmcnt(0)
	s_setprio 0
	s_barrier
	v_mfma_f32_16x16x32_bf16 v[62:65], v[156:159], v[188:191], v[62:65]
	v_mfma_f32_16x16x32_bf16 v[62:65], v[160:163], v[192:195], v[62:65]
	v_mfma_f32_16x16x32_bf16 v[58:61], v[164:167], v[188:191], v[58:61]
	v_mfma_f32_16x16x32_bf16 v[58:61], v[168:171], v[192:195], v[58:61]
	v_mfma_f32_16x16x32_bf16 v[46:49], v[156:159], v[196:199], v[46:49]
	v_mfma_f32_16x16x32_bf16 v[46:49], v[160:163], v[200:203], v[46:49]
	v_mfma_f32_16x16x32_bf16 v[42:45], v[164:167], v[196:199], v[42:45]
	v_mfma_f32_16x16x32_bf16 v[42:45], v[168:171], v[200:203], v[42:45]
	v_mfma_f32_16x16x32_bf16 v[30:33], v[156:159], v[204:207], v[30:33]
	v_mfma_f32_16x16x32_bf16 v[30:33], v[160:163], v[208:211], v[30:33]
	v_mfma_f32_16x16x32_bf16 v[26:29], v[164:167], v[204:207], v[26:29]
	v_mfma_f32_16x16x32_bf16 v[26:29], v[168:171], v[208:211], v[26:29]
	v_mfma_f32_16x16x32_bf16 v[14:17], v[156:159], v[212:215], v[14:17]
	v_mfma_f32_16x16x32_bf16 v[14:17], v[160:163], v[216:219], v[14:17]
	v_mfma_f32_16x16x32_bf16 v[10:13], v[164:167], v[212:215], v[10:13]
	v_mfma_f32_16x16x32_bf16 v[10:13], v[168:171], v[216:219], v[10:13]
	v_mfma_f32_16x16x32_bf16 v[54:57], v[172:175], v[188:191], v[54:57]
	v_mfma_f32_16x16x32_bf16 v[54:57], v[176:179], v[192:195], v[54:57]
	v_mfma_f32_16x16x32_bf16 v[50:53], v[180:183], v[188:191], v[50:53]
	v_mfma_f32_16x16x32_bf16 v[50:53], v[184:187], v[192:195], v[50:53]
	v_mfma_f32_16x16x32_bf16 v[38:41], v[172:175], v[196:199], v[38:41]
	v_mfma_f32_16x16x32_bf16 v[38:41], v[176:179], v[200:203], v[38:41]
	v_mfma_f32_16x16x32_bf16 v[34:37], v[180:183], v[196:199], v[34:37]
	v_mfma_f32_16x16x32_bf16 v[34:37], v[184:187], v[200:203], v[34:37]
	v_mfma_f32_16x16x32_bf16 v[22:25], v[172:175], v[204:207], v[22:25]
	v_mfma_f32_16x16x32_bf16 v[22:25], v[176:179], v[208:211], v[22:25]
	v_mfma_f32_16x16x32_bf16 v[18:21], v[180:183], v[204:207], v[18:21]
	v_mfma_f32_16x16x32_bf16 v[18:21], v[184:187], v[208:211], v[18:21]
	v_mfma_f32_16x16x32_bf16 v[6:9], v[172:175], v[212:215], v[6:9]
	v_mfma_f32_16x16x32_bf16 v[6:9], v[176:179], v[216:219], v[6:9]
	v_mfma_f32_16x16x32_bf16 v[2:5], v[180:183], v[212:215], v[2:5]
	v_mfma_f32_16x16x32_bf16 v[2:5], v[184:187], v[216:219], v[2:5]
	s_barrier
	s_add_i32 s59, s59, 2
	s_add_u32 s96, s96, 0x100
	s_addc_u32 s97, s97, 0
	s_cmp_gt_u32 s59, 29
	s_mov_b64 s[28:29], s[34:35]
	s_cbranch_scc1 .LBB0_383

; #define PG8_LDA(dst, b, h) do { _Pragma("unroll") for (int m = 0; m < 4; ++m) _Pragma("unroll") for (int k = 0; k < 2; ++k) dst[m][k] = *(const PG8_LAS bf16x8*)(lds + PG8_SA(b, h) + aoff + m * 2048 + k * 1024); } while (0)
; #define PG8_LDB(dst, b, h) do { _Pragma("unroll") for (int n = 0; n < 2; ++n) _Pragma("unroll") for (int k = 0; k < 2; ++k) dst[n][k] = *(const PG8_LAS bf16x8*)(lds + PG8_SB(b, h) + boff + n * 2048 + k * 1024); } while (0)
; #define PG8_MMA(ai, bj, At, Bt) do { __builtin_amdgcn_s_setprio(1); _Pragma("unroll") for (int m = 0; m < 4; ++m) _Pragma("unroll") for (int n = 0; n < 2; ++n) _Pragma("unroll") for (int k = 0; k < 2; ++k) \
;         acc[ai][bj][m][n] = __builtin_amdgcn_mfma_f32_16x16x32_bf16(Bt[n][k], At[m][k], acc[ai][bj][m][n], 0, 0, 0); __builtin_amdgcn_s_setprio(0); } while (0)
; #define PG8_WAIT_V(n) asm volatile("s_waitcnt vmcnt(" #n ")" ::: "memory")
; #define PG8_WAIT_L(n) asm volatile("s_waitcnt lgkmcnt(" #n ")" ::: "memory")
; #define PG8_BAR __builtin_amdgcn_s_barrier()
; #define PG8_SCHED __builtin_amdgcn_sched_barrier(0)
; template <class Epi, class Sched, bool ALIGN_EPI = false, bool SP2 = false>
; __device__ __forceinline__ void gemm_phase(PG8_LAS unsigned char* lds, const Gemm g, const Sched& S, const Epi& E, const int tid) {
;     ...
;             const char* a2 = last ? nA : cA + (size_t)(t + 2) * kstepA; const char* b2 = last ? nB : cB + (size_t)(t + 2) * kstepB;
;             const char* a3 = a2 + kstepA; const char* b3 = b2 + kstepB;
;             if (last && has_next) S.a_ready(nxt);
;             if constexpr (SP2) {
;             PG8_LDB(B0, 0, 0); PG8_LDB(B1, 0, 1); PG8_SCHED; PG8_LDA(At, 0, 0); PG8_STAGE(PG8_SA(1, 1), a1 + hstepA, voffA);
;             PG8_WAIT_V(8); PG8_WAIT_L(0); PG8_BAR; PG8_MMA(0, 0, At, B0); PG8_MMA(0, 1, At, B1); PG8_BAR; PG8_SCHED;
;             PG8_LDA(At, 0, 1); PG8_STAGE(PG8_SB(0, 0), b2, voffB); PG8_STAGE(PG8_SB(0, 1), b2 + hstepB, voffB); PG8_STAGE(PG8_SA(0, 0), a2, voffA);
;             PG8_WAIT_V(8); PG8_WAIT_L(0); PG8_BAR; PG8_MMA(1, 0, At, B0); PG8_MMA(1, 1, At, B1); PG8_BAR; PG8_SCHED;
.LBB0_462:
	v_add_u32_e32 v142, 0x10000, v181
	v_add_u32_e32 v158, 0x14000, v181
	s_setprio 1
	ds_read_b128 v[130:133], v142
	ds_read_b128 v[134:137], v142 offset:1024
	ds_read_b128 v[138:141], v142 offset:2048
	ds_read_b128 v[142:145], v142 offset:3072
	ds_read_b128 v[146:149], v158
	ds_read_b128 v[150:153], v158 offset:1024
	ds_read_b128 v[154:157], v158 offset:2048
	ds_read_b128 v[158:161], v158 offset:3072
	s_cmpk_eq_i32 s67, 0x54
	s_cselect_b32 s26, s6, s64
	s_cselect_b32 s27, s7, s65
	s_cselect_b32 s24, s18, s11
	s_cselect_b32 s25, s19, s59
	s_add_u32 s22, s26, 0x8000
	s_addc_u32 s23, s27, 0
	ds_read_b128 v[162:165], v182
	ds_read_b128 v[166:169], v182 offset:1024
	ds_read_b128 v[170:173], v182 offset:2048
	ds_read_b128 v[184:187], v182 offset:3072
	ds_read_b128 v[188:191], v182 offset:4096
	ds_read_b128 v[192:195], v182 offset:5120
	ds_read_b128 v[196:199], v182 offset:6144
	ds_read_b128 v[200:203], v182 offset:7168
	s_mov_b32 m0, s50
	s_nop 0
	global_load_lds_dwordx4 v0, s[20:21]
	s_nop 0
	s_mov_b32 m0, s54
	s_nop 0
	global_load_lds_dwordx4 v177, s[20:21]
	s_waitcnt vmcnt(8)
	s_waitcnt lgkmcnt(0)
	s_setprio 0
	s_barrier
	v_mfma_f32_16x16x32_bf16 v[126:129], v[130:133], v[162:165], v[126:129]
	v_mfma_f32_16x16x32_bf16 v[126:129], v[134:137], v[166:169], v[126:129]
	v_mfma_f32_16x16x32_bf16 v[122:125], v[138:141], v[162:165], v[122:125]
	v_mfma_f32_16x16x32_bf16 v[122:125], v[142:145], v[166:169], v[122:125]
	v_mfma_f32_16x16x32_bf16 v[110:113], v[130:133], v[170:173], v[110:113]
	v_mfma_f32_16x16x32_bf16 v[110:113], v[134:137], v[184:187], v[110:113]
	v_mfma_f32_16x16x32_bf16 v[106:109], v[138:141], v[170:173], v[106:109]
	v_mfma_f32_16x16x32_bf16 v[106:109], v[142:145], v[184:187], v[106:109]
	v_mfma_f32_16x16x32_bf16 v[94:97], v[130:133], v[188:191], v[94:97]
	v_mfma_f32_16x16x32_bf16 v[94:97], v[134:137], v[192:195], v[94:97]
	v_mfma_f32_16x16x32_bf16 v[90:93], v[138:141], v[188:191], v[90:93]
	v_mfma_f32_16x16x32_bf16 v[90:93], v[142:145], v[192:195], v[90:93]
	v_mfma_f32_16x16x32_bf16 v[78:81], v[130:133], v[196:199], v[78:81]
	v_mfma_f32_16x16x32_bf16 v[78:81], v[134:137], v[200:203], v[78:81]
	v_mfma_f32_16x16x32_bf16 v[74:77], v[138:141], v[196:199], v[74:77]
	v_mfma_f32_16x16x32_bf16 v[74:77], v[142:145], v[200:203], v[74:77]
	v_mfma_f32_16x16x32_bf16 v[118:121], v[146:149], v[162:165], v[118:121]
	v_mfma_f32_16x16x32_bf16 v[118:121], v[150:153], v[166:169], v[118:121]
	v_mfma_f32_16x16x32_bf16 v[114:117], v[154:157], v[162:165], v[114:117]
	v_mfma_f32_16x16x32_bf16 v[114:117], v[158:161], v[166:169], v[114:117]
	v_mfma_f32_16x16x32_bf16 v[102:105], v[146:149], v[170:173], v[102:105]
	v_mfma_f32_16x16x32_bf16 v[102:105], v[150:153], v[184:187], v[102:105]
	v_mfma_f32_16x16x32_bf16 v[98:101], v[154:157], v[170:173], v[98:101]
	v_mfma_f32_16x16x32_bf16 v[98:101], v[158:161], v[184:187], v[98:101]
	v_mfma_f32_16x16x32_bf16 v[86:89], v[146:149], v[188:191], v[86:89]
	v_mfma_f32_16x16x32_bf16 v[86:89], v[150:153], v[192:195], v[86:89]
	v_mfma_f32_16x16x32_bf16 v[82:85], v[154:157], v[188:191], v[82:85]
	v_mfma_f32_16x16x32_bf16 v[82:85], v[158:161], v[192:195], v[82:85]
	v_mfma_f32_16x16x32_bf16 v[70:73], v[146:149], v[196:199], v[70:73]
	v_mfma_f32_16x16x32_bf16 v[70:73], v[150:153], v[200:203], v[70:73]
	v_mfma_f32_16x16x32_bf16 v[66:69], v[154:157], v[196:199], v[66:69]
	v_mfma_f32_16x16x32_bf16 v[66:69], v[158:161], v[200:203], v[66:69]
	s_barrier
	s_setprio 1
	ds_read_b128 v[162:165], v182 offset:16384
	ds_read_b128 v[166:169], v182 offset:17408
	ds_read_b128 v[170:173], v182 offset:18432
	ds_read_b128 v[184:187], v182 offset:19456
	ds_read_b128 v[188:191], v182 offset:20480
	ds_read_b128 v[192:195], v182 offset:21504
	ds_read_b128 v[196:199], v182 offset:22528
	ds_read_b128 v[200:203], v182 offset:23552
	s_mov_b32 m0, s35
	s_nop 0
	global_load_lds_dwordx4 v176, s[24:25]
	s_add_u32 s90, s24, 0x4000
	s_mov_b32 m0, s37
	s_nop 0
	global_load_lds_dwordx4 v178, s[24:25]
	s_addc_u32 s91, s25, 0
	s_mov_b32 m0, s38
	s_nop 0
	global_load_lds_dwordx4 v176, s[90:91]
	s_nop 0
	s_mov_b32 m0, s39
	s_nop 0
	global_load_lds_dwordx4 v178, s[90:91]
	s_nop 0
	s_mov_b32 m0, s10
	s_nop 0
	global_load_lds_dwordx4 v0, s[26:27]
	s_nop 0
	s_mov_b32 m0, s40
	s_nop 0
	global_load_lds_dwordx4 v177, s[26:27]
	s_waitcnt vmcnt(8)
	s_waitcnt lgkmcnt(0)
	s_setprio 0
	s_barrier
	v_mfma_f32_16x16x32_bf16 v[62:65], v[130:133], v[162:165], v[62:65]
	v_mfma_f32_16x16x32_bf16 v[62:65], v[134:137], v[166:169], v[62:65]
	v_mfma_f32_16x16x32_bf16 v[58:61], v[138:141], v[162:165], v[58:61]
	v_mfma_f32_16x16x32_bf16 v[58:61], v[142:145], v[166:169], v[58:61]
	v_mfma_f32_16x16x32_bf16 v[46:49], v[130:133], v[170:173], v[46:49]
	v_mfma_f32_16x16x32_bf16 v[46:49], v[134:137], v[184:187], v[46:49]
	v_mfma_f32_16x16x32_bf16 v[42:45], v[138:141], v[170:173], v[42:45]
	v_mfma_f32_16x16x32_bf16 v[42:45], v[142:145], v[184:187], v[42:45]
	v_mfma_f32_16x16x32_bf16 v[30:33], v[130:133], v[188:191], v[30:33]
	v_mfma_f32_16x16x32_bf16 v[30:33], v[134:137], v[192:195], v[30:33]
	v_mfma_f32_16x16x32_bf16 v[26:29], v[138:141], v[188:191], v[26:29]
	v_mfma_f32_16x16x32_bf16 v[26:29], v[142:145], v[192:195], v[26:29]
	v_mfma_f32_16x16x32_bf16 v[14:17], v[130:133], v[196:199], v[14:17]
	v_mfma_f32_16x16x32_bf16 v[14:17], v[134:137], v[200:203], v[14:17]
	v_mfma_f32_16x16x32_bf16 v[10:13], v[138:141], v[196:199], v[10:13]
	v_mfma_f32_16x16x32_bf16 v[10:13], v[142:145], v[200:203], v[10:13]
	v_mfma_f32_16x16x32_bf16 v[54:57], v[146:149], v[162:165], v[54:57]
	v_mfma_f32_16x16x32_bf16 v[54:57], v[150:153], v[166:169], v[54:57]
	v_mfma_f32_16x16x32_bf16 v[50:53], v[154:157], v[162:165], v[50:53]
	v_mfma_f32_16x16x32_bf16 v[50:53], v[158:161], v[166:169], v[50:53]
	v_mfma_f32_16x16x32_bf16 v[38:41], v[146:149], v[170:173], v[38:41]
	v_mfma_f32_16x16x32_bf16 v[38:41], v[150:153], v[184:187], v[38:41]
	v_mfma_f32_16x16x32_bf16 v[34:37], v[154:157], v[170:173], v[34:37]
	v_mfma_f32_16x16x32_bf16 v[34:37], v[158:161], v[184:187], v[34:37]
	v_mfma_f32_16x16x32_bf16 v[22:25], v[146:149], v[188:191], v[22:25]
	v_mfma_f32_16x16x32_bf16 v[22:25], v[150:153], v[192:195], v[22:25]
	v_mfma_f32_16x16x32_bf16 v[18:21], v[154:157], v[188:191], v[18:21]
	v_mfma_f32_16x16x32_bf16 v[18:21], v[158:161], v[192:195], v[18:21]
	v_mfma_f32_16x16x32_bf16 v[6:9], v[146:149], v[196:199], v[6:9]
	v_mfma_f32_16x16x32_bf16 v[6:9], v[150:153], v[200:203], v[6:9]
	v_mfma_f32_16x16x32_bf16 v[2:5], v[154:157], v[196:199], v[2:5]
	v_mfma_f32_16x16x32_bf16 v[2:5], v[158:161], v[200:203], v[2:5]
	s_barrier
; #define PG8_LDA(dst, b, h) do { _Pragma("unroll") for (int m = 0; m < 4; ++m) _Pragma("unroll") for (int k = 0; k < 2; ++k) dst[m][k] = *(const PG8_LAS bf16x8*)(lds + PG8_SA(b, h) + aoff + m * 2048 + k * 1024); } while (0)
; #define PG8_LDB(dst, b, h) do { _Pragma("unroll") for (int n = 0; n < 2; ++n) _Pragma("unroll") for (int k = 0; k < 2; ++k) dst[n][k] = *(const PG8_LAS bf16x8*)(lds + PG8_SB(b, h) + boff + n * 2048 + k * 1024); } while (0)
; #define PG8_MMA(ai, bj, At, Bt) do { __builtin_amdgcn_s_setprio(1); _Pragma("unroll") for (int m = 0; m < 4; ++m) _Pragma("unroll") for (int n = 0; n < 2; ++n) _Pragma("unroll") for (int k = 0; k < 2; ++k) \
;         acc[ai][bj][m][n] = __builtin_amdgcn_mfma_f32_16x16x32_bf16(Bt[n][k], At[m][k], acc[ai][bj][m][n], 0, 0, 0); __builtin_amdgcn_s_setprio(0); } while (0)
; #define PG8_WAIT_V(n) asm volatile("s_waitcnt vmcnt(" #n ")" ::: "memory")
; #define PG8_WAIT_L(n) asm volatile("s_waitcnt lgkmcnt(" #n ")" ::: "memory")
; #define PG8_BAR __builtin_amdgcn_s_barrier()
; #define PG8_SCHED __builtin_amdgcn_sched_barrier(0)
; template <class Epi, class Sched, bool ALIGN_EPI = false, bool SP2 = false>
; __device__ __forceinline__ void gemm_phase(PG8_LAS unsigned char* lds, const Gemm g, const Sched& S, const Epi& E, const int tid) {
;     ...
;         for (int t = 0; t < nt; t += 2) {
;     ...
;             PG8_LDB(B0, 1, 0); PG8_LDB(B1, 1, 1); PG8_SCHED; PG8_LDA(At, 1, 0); PG8_STAGE(PG8_SA(0, 1), a2 + hstepA, voffA);
;             PG8_WAIT_V(8); PG8_WAIT_L(0); PG8_BAR; PG8_MMA(0, 0, At, B0); PG8_MMA(0, 1, At, B1); PG8_BAR; PG8_SCHED;
;             PG8_LDA(At, 1, 1); PG8_STAGE(PG8_SB(1, 0), b3, voffB); PG8_STAGE(PG8_SB(1, 1), b3 + hstepB, voffB); PG8_STAGE(PG8_SA(1, 0), a3, voffA);
;             PG8_WAIT_V(8); PG8_WAIT_L(0); PG8_BAR; PG8_MMA(1, 0, At, B0); PG8_MMA(1, 1, At, B1); PG8_BAR; PG8_SCHED;
	v_add_u32_e32 v142, 0x18000, v181
	v_add_u32_e32 v158, 0x1c000, v181
	s_setprio 1
	ds_read_b128 v[130:133], v142
	ds_read_b128 v[134:137], v142 offset:1024
	ds_read_b128 v[138:141], v142 offset:2048
	ds_read_b128 v[142:145], v142 offset:3072
	ds_read_b128 v[146:149], v158
	ds_read_b128 v[150:153], v158 offset:1024
	ds_read_b128 v[154:157], v158 offset:2048
	ds_read_b128 v[158:161], v158 offset:3072
	ds_read_b128 v[162:165], v182 offset:32768
	ds_read_b128 v[166:169], v182 offset:33792
	ds_read_b128 v[170:173], v182 offset:34816
	ds_read_b128 v[184:187], v182 offset:35840
	ds_read_b128 v[188:191], v182 offset:36864
	ds_read_b128 v[192:195], v182 offset:37888
	ds_read_b128 v[196:199], v182 offset:38912
	ds_read_b128 v[200:203], v182 offset:39936
	s_add_u32 s26, s26, 0x4000
	s_addc_u32 s27, s27, 0
	s_mov_b32 m0, s41
	s_nop 0
	global_load_lds_dwordx4 v0, s[26:27]
	s_nop 0
	s_mov_b32 m0, s42
	s_nop 0
	global_load_lds_dwordx4 v177, s[26:27]
	s_waitcnt vmcnt(8)
	s_waitcnt lgkmcnt(0)
	s_setprio 0
	s_barrier
	v_mfma_f32_16x16x32_bf16 v[126:129], v[130:133], v[162:165], v[126:129]
	v_mfma_f32_16x16x32_bf16 v[126:129], v[134:137], v[166:169], v[126:129]
	v_mfma_f32_16x16x32_bf16 v[122:125], v[138:141], v[162:165], v[122:125]
	v_mfma_f32_16x16x32_bf16 v[122:125], v[142:145], v[166:169], v[122:125]
	v_mfma_f32_16x16x32_bf16 v[110:113], v[130:133], v[170:173], v[110:113]
	v_mfma_f32_16x16x32_bf16 v[110:113], v[134:137], v[184:187], v[110:113]
	v_mfma_f32_16x16x32_bf16 v[106:109], v[138:141], v[170:173], v[106:109]
	v_mfma_f32_16x16x32_bf16 v[106:109], v[142:145], v[184:187], v[106:109]
	v_mfma_f32_16x16x32_bf16 v[94:97], v[130:133], v[188:191], v[94:97]
	v_mfma_f32_16x16x32_bf16 v[94:97], v[134:137], v[192:195], v[94:97]
	v_mfma_f32_16x16x32_bf16 v[90:93], v[138:141], v[188:191], v[90:93]
	v_mfma_f32_16x16x32_bf16 v[90:93], v[142:145], v[192:195], v[90:93]
	v_mfma_f32_16x16x32_bf16 v[78:81], v[130:133], v[196:199], v[78:81]
	v_mfma_f32_16x16x32_bf16 v[78:81], v[134:137], v[200:203], v[78:81]
	v_mfma_f32_16x16x32_bf16 v[74:77], v[138:141], v[196:199], v[74:77]
	v_mfma_f32_16x16x32_bf16 v[74:77], v[142:145], v[200:203], v[74:77]
	v_mfma_f32_16x16x32_bf16 v[118:121], v[146:149], v[162:165], v[118:121]
	v_mfma_f32_16x16x32_bf16 v[118:121], v[150:153], v[166:169], v[118:121]
	v_mfma_f32_16x16x32_bf16 v[114:117], v[154:157], v[162:165], v[114:117]
	v_mfma_f32_16x16x32_bf16 v[114:117], v[158:161], v[166:169], v[114:117]
	v_mfma_f32_16x16x32_bf16 v[102:105], v[146:149], v[170:173], v[102:105]
	v_mfma_f32_16x16x32_bf16 v[102:105], v[150:153], v[184:187], v[102:105]
	v_mfma_f32_16x16x32_bf16 v[98:101], v[154:157], v[170:173], v[98:101]
	v_mfma_f32_16x16x32_bf16 v[98:101], v[158:161], v[184:187], v[98:101]
	v_mfma_f32_16x16x32_bf16 v[86:89], v[146:149], v[188:191], v[86:89]
	v_mfma_f32_16x16x32_bf16 v[86:89], v[150:153], v[192:195], v[86:89]
	v_mfma_f32_16x16x32_bf16 v[82:85], v[154:157], v[188:191], v[82:85]
	v_mfma_f32_16x16x32_bf16 v[82:85], v[158:161], v[192:195], v[82:85]
	v_mfma_f32_16x16x32_bf16 v[70:73], v[146:149], v[196:199], v[70:73]
	v_mfma_f32_16x16x32_bf16 v[70:73], v[150:153], v[200:203], v[70:73]
	v_mfma_f32_16x16x32_bf16 v[66:69], v[154:157], v[196:199], v[66:69]
	v_mfma_f32_16x16x32_bf16 v[66:69], v[158:161], v[200:203], v[66:69]
	s_barrier
	s_setprio 1
	ds_read_b128 v[162:165], v182 offset:49152
	ds_read_b128 v[166:169], v182 offset:50176
	ds_read_b128 v[170:173], v182 offset:51200
	ds_read_b128 v[184:187], v182 offset:52224
	ds_read_b128 v[188:191], v182 offset:53248
	ds_read_b128 v[192:195], v182 offset:54272
	ds_read_b128 v[196:199], v182 offset:55296
	ds_read_b128 v[200:203], v182 offset:56320
	s_add_u32 s26, s24, 0x8000
	s_addc_u32 s27, s25, 0
	s_mov_b32 m0, s44
	s_nop 0
	global_load_lds_dwordx4 v176, s[26:27]
	s_add_u32 s24, s24, 0xc000
	s_mov_b32 m0, s45
	s_nop 0
	global_load_lds_dwordx4 v178, s[26:27]
	s_addc_u32 s25, s25, 0
	s_mov_b32 m0, s48
	s_nop 0
	global_load_lds_dwordx4 v176, s[24:25]
	s_nop 0
	s_mov_b32 m0, s49
	s_nop 0
	global_load_lds_dwordx4 v178, s[24:25]
	s_mov_b32 m0, s46
	s_nop 0
	global_load_lds_dwordx4 v0, s[22:23]
	s_nop 0
	s_mov_b32 m0, s47
	s_nop 0
	global_load_lds_dwordx4 v177, s[22:23]
	s_waitcnt vmcnt(8)
	s_waitcnt lgkmcnt(0)
	s_setprio 0
	s_barrier
	v_mfma_f32_16x16x32_bf16 v[62:65], v[130:133], v[162:165], v[62:65]
	v_mfma_f32_16x16x32_bf16 v[62:65], v[134:137], v[166:169], v[62:65]
	v_mfma_f32_16x16x32_bf16 v[58:61], v[138:141], v[162:165], v[58:61]
	v_mfma_f32_16x16x32_bf16 v[58:61], v[142:145], v[166:169], v[58:61]
	v_mfma_f32_16x16x32_bf16 v[46:49], v[130:133], v[170:173], v[46:49]
	v_mfma_f32_16x16x32_bf16 v[46:49], v[134:137], v[184:187], v[46:49]
	v_mfma_f32_16x16x32_bf16 v[42:45], v[138:141], v[170:173], v[42:45]
	v_mfma_f32_16x16x32_bf16 v[42:45], v[142:145], v[184:187], v[42:45]
	v_mfma_f32_16x16x32_bf16 v[30:33], v[130:133], v[188:191], v[30:33]
	v_mfma_f32_16x16x32_bf16 v[30:33], v[134:137], v[192:195], v[30:33]
	v_mfma_f32_16x16x32_bf16 v[26:29], v[138:141], v[188:191], v[26:29]
	v_mfma_f32_16x16x32_bf16 v[26:29], v[142:145], v[192:195], v[26:29]
	v_mfma_f32_16x16x32_bf16 v[14:17], v[130:133], v[196:199], v[14:17]
	v_mfma_f32_16x16x32_bf16 v[14:17], v[134:137], v[200:203], v[14:17]
	v_mfma_f32_16x16x32_bf16 v[10:13], v[138:141], v[196:199], v[10:13]
	v_mfma_f32_16x16x32_bf16 v[10:13], v[142:145], v[200:203], v[10:13]
	v_mfma_f32_16x16x32_bf16 v[54:57], v[146:149], v[162:165], v[54:57]
	v_mfma_f32_16x16x32_bf16 v[54:57], v[150:153], v[166:169], v[54:57]
	v_mfma_f32_16x16x32_bf16 v[50:53], v[154:157], v[162:165], v[50:53]
	v_mfma_f32_16x16x32_bf16 v[50:53], v[158:161], v[166:169], v[50:53]
	v_mfma_f32_16x16x32_bf16 v[38:41], v[146:149], v[170:173], v[38:41]
	v_mfma_f32_16x16x32_bf16 v[38:41], v[150:153], v[184:187], v[38:41]
	v_mfma_f32_16x16x32_bf16 v[34:37], v[154:157], v[170:173], v[34:37]
	v_mfma_f32_16x16x32_bf16 v[34:37], v[158:161], v[184:187], v[34:37]
	v_mfma_f32_16x16x32_bf16 v[22:25], v[146:149], v[188:191], v[22:25]
	v_mfma_f32_16x16x32_bf16 v[22:25], v[150:153], v[192:195], v[22:25]
	v_mfma_f32_16x16x32_bf16 v[18:21], v[154:157], v[188:191], v[18:21]
	v_mfma_f32_16x16x32_bf16 v[18:21], v[158:161], v[192:195], v[18:21]
	v_mfma_f32_16x16x32_bf16 v[6:9], v[146:149], v[196:199], v[6:9]
	v_mfma_f32_16x16x32_bf16 v[6:9], v[150:153], v[200:203], v[6:9]
	v_mfma_f32_16x16x32_bf16 v[2:5], v[154:157], v[196:199], v[2:5]
	v_mfma_f32_16x16x32_bf16 v[2:5], v[158:161], v[200:203], v[2:5]
	s_barrier
	s_add_i32 s67, s67, 2
	s_add_u32 s11, s11, 0x10000
	s_addc_u32 s59, s59, 0
	s_add_u32 s64, s64, 0x10000
	s_addc_u32 s65, s65, 0
	s_add_u32 s20, s20, 0x10000
	s_addc_u32 s21, s21, 0
	s_cmpk_gt_u32 s67, 0x55
	s_cbranch_scc0 .LBB0_462
	s_and_b64 vcc, exec, s[16:17]
	s_cbranch_vccz .LBB0_465
	s_barrier

; #define PG8_LDA(dst, b, h) do { _Pragma("unroll") for (int m = 0; m < 4; ++m) _Pragma("unroll") for (int k = 0; k < 2; ++k) dst[m][k] = *(const PG8_LAS bf16x8*)(lds + PG8_SA(b, h) + aoff + m * 2048 + k * 1024); } while (0)
; #define PG8_LDB(dst, b, h) do { _Pragma("unroll") for (int n = 0; n < 2; ++n) _Pragma("unroll") for (int k = 0; k < 2; ++k) dst[n][k] = *(const PG8_LAS bf16x8*)(lds + PG8_SB(b, h) + boff + n * 2048 + k * 1024); } while (0)
; #define PG8_MMA(ai, bj, At, Bt) do { __builtin_amdgcn_s_setprio(1); _Pragma("unroll") for (int m = 0; m < 4; ++m) _Pragma("unroll") for (int n = 0; n < 2; ++n) _Pragma("unroll") for (int k = 0; k < 2; ++k) \
;         acc[ai][bj][m][n] = __builtin_amdgcn_mfma_f32_16x16x32_bf16(Bt[n][k], At[m][k], acc[ai][bj][m][n], 0, 0, 0); __builtin_amdgcn_s_setprio(0); } while (0)
; #define PG8_WAIT_V(n) asm volatile("s_waitcnt vmcnt(" #n ")" ::: "memory")
; #define PG8_WAIT_L(n) asm volatile("s_waitcnt lgkmcnt(" #n ")" ::: "memory")
; #define PG8_BAR __builtin_amdgcn_s_barrier()
; #define PG8_SCHED __builtin_amdgcn_sched_barrier(0)
; template <class Epi, class Sched, bool ALIGN_EPI = false, bool SP2 = false>
; __device__ __forceinline__ void gemm_phase(PG8_LAS unsigned char* lds, const Gemm g, const Sched& S, const Epi& E, const int tid) {
;     ...
;             const char* a2 = last ? nA : cA + (size_t)(t + 2) * kstepA; const char* b2 = last ? nB : cB + (size_t)(t + 2) * kstepB;
;             const char* a3 = a2 + kstepA; const char* b3 = b2 + kstepB;
;             if (last && has_next) S.a_ready(nxt);
;             if constexpr (SP2) {
;             PG8_LDB(B0, 0, 0); PG8_LDB(B1, 0, 1); PG8_SCHED; PG8_LDA(At, 0, 0); PG8_STAGE(PG8_SA(1, 1), a1 + hstepA, voffA);
;             PG8_WAIT_V(8); PG8_WAIT_L(0); PG8_BAR; PG8_MMA(0, 0, At, B0); PG8_MMA(0, 1, At, B1); PG8_BAR; PG8_SCHED;
;             PG8_LDA(At, 0, 1); PG8_STAGE(PG8_SB(0, 0), b2, voffB); PG8_STAGE(PG8_SB(0, 1), b2 + hstepB, voffB); PG8_STAGE(PG8_SA(0, 0), a2, voffA);
.LBB0_546:
	s_or_b64 exec, exec, s[34:35]
	v_add_u32_e32 v133, 0x10000, v144
	s_setprio 1
	ds_read_b128 v[146:149], v133
	ds_read_b128 v[150:153], v133 offset:1024
	ds_read_b128 v[154:157], v133 offset:2048
	ds_read_b128 v[158:161], v133 offset:3072
	v_add_u32_e32 v133, 0x14000, v144
	s_add_u32 s34, s28, 0x100
	ds_read_b128 v[162:165], v133
	ds_read_b128 v[166:169], v133 offset:1024
	ds_read_b128 v[170:173], v133 offset:2048
	ds_read_b128 v[174:177], v133 offset:3072
	s_addc_u32 s35, s29, 0
	s_and_b64 s[30:31], s[30:31], exec
	s_cselect_b32 s42, s95, s34
	s_cselect_b32 s43, s21, s35
	s_cselect_b32 s31, s19, s59
	s_cselect_b32 s30, s96, s97
	s_add_u32 s38, s42, 0x80
	s_addc_u32 s39, s43, 0
	s_add_u32 s40, s30, 0x80
	s_addc_u32 s41, s31, 0
	ds_read_b128 v[178:181], v145
	ds_read_b128 v[182:185], v145 offset:1024
	ds_read_b128 v[186:189], v145 offset:2048
	ds_read_b128 v[190:193], v145 offset:3072
	ds_read_b128 v[194:197], v145 offset:4096
	ds_read_b128 v[198:201], v145 offset:5120
	ds_read_b128 v[202:205], v145 offset:6144
	ds_read_b128 v[206:209], v145 offset:7168
	s_add_u32 s28, s28, 0x80080
	s_addc_u32 s29, s29, 0
	s_mov_b32 m0, s70
	s_nop 0
	global_load_lds_dwordx4 v136, s[28:29]
	s_nop 0
	s_mov_b32 m0, s78
	s_nop 0
	global_load_lds_dwordx4 v138, s[28:29]
	s_waitcnt vmcnt(8)
	s_waitcnt lgkmcnt(0)
	s_setprio 0
	s_barrier
	v_mfma_f32_16x16x32_bf16 v[126:129], v[146:149], v[178:181], v[126:129]
	v_mfma_f32_16x16x32_bf16 v[126:129], v[150:153], v[182:185], v[126:129]
	v_mfma_f32_16x16x32_bf16 v[122:125], v[154:157], v[178:181], v[122:125]
	v_mfma_f32_16x16x32_bf16 v[122:125], v[158:161], v[182:185], v[122:125]
	v_mfma_f32_16x16x32_bf16 v[118:121], v[146:149], v[186:189], v[118:121]
	v_mfma_f32_16x16x32_bf16 v[118:121], v[150:153], v[190:193], v[118:121]
	v_mfma_f32_16x16x32_bf16 v[110:113], v[154:157], v[186:189], v[110:113]
	v_mfma_f32_16x16x32_bf16 v[110:113], v[158:161], v[190:193], v[110:113]
	v_mfma_f32_16x16x32_bf16 v[102:105], v[146:149], v[194:197], v[102:105]
	v_mfma_f32_16x16x32_bf16 v[102:105], v[150:153], v[198:201], v[102:105]
	v_mfma_f32_16x16x32_bf16 v[94:97], v[154:157], v[194:197], v[94:97]
	v_mfma_f32_16x16x32_bf16 v[94:97], v[158:161], v[198:201], v[94:97]
	v_mfma_f32_16x16x32_bf16 v[86:89], v[146:149], v[202:205], v[86:89]
	v_mfma_f32_16x16x32_bf16 v[86:89], v[150:153], v[206:209], v[86:89]
	v_mfma_f32_16x16x32_bf16 v[78:81], v[154:157], v[202:205], v[78:81]
	v_mfma_f32_16x16x32_bf16 v[78:81], v[158:161], v[206:209], v[78:81]
	v_mfma_f32_16x16x32_bf16 v[114:117], v[162:165], v[178:181], v[114:117]
	v_mfma_f32_16x16x32_bf16 v[114:117], v[166:169], v[182:185], v[114:117]
	v_mfma_f32_16x16x32_bf16 v[106:109], v[170:173], v[178:181], v[106:109]
	v_mfma_f32_16x16x32_bf16 v[106:109], v[174:177], v[182:185], v[106:109]
	v_mfma_f32_16x16x32_bf16 v[98:101], v[162:165], v[186:189], v[98:101]
	v_mfma_f32_16x16x32_bf16 v[98:101], v[166:169], v[190:193], v[98:101]
	v_mfma_f32_16x16x32_bf16 v[90:93], v[170:173], v[186:189], v[90:93]
	v_mfma_f32_16x16x32_bf16 v[90:93], v[174:177], v[190:193], v[90:93]
	v_mfma_f32_16x16x32_bf16 v[82:85], v[162:165], v[194:197], v[82:85]
	v_mfma_f32_16x16x32_bf16 v[82:85], v[166:169], v[198:201], v[82:85]
	v_mfma_f32_16x16x32_bf16 v[74:77], v[170:173], v[194:197], v[74:77]
	v_mfma_f32_16x16x32_bf16 v[74:77], v[174:177], v[198:201], v[74:77]
	v_mfma_f32_16x16x32_bf16 v[70:73], v[162:165], v[202:205], v[70:73]
	v_mfma_f32_16x16x32_bf16 v[70:73], v[166:169], v[206:209], v[70:73]
	v_mfma_f32_16x16x32_bf16 v[66:69], v[170:173], v[202:205], v[66:69]
	v_mfma_f32_16x16x32_bf16 v[66:69], v[174:177], v[206:209], v[66:69]
	s_barrier
	s_setprio 1
	ds_read_b128 v[178:181], v145 offset:16384
	ds_read_b128 v[182:185], v145 offset:17408
	ds_read_b128 v[186:189], v145 offset:18432
	ds_read_b128 v[190:193], v145 offset:19456
	ds_read_b128 v[194:197], v145 offset:20480
	ds_read_b128 v[198:201], v145 offset:21504
	ds_read_b128 v[202:205], v145 offset:22528
	ds_read_b128 v[206:209], v145 offset:23552
	s_mov_b32 m0, s9
	s_nop 0
	global_load_lds_dwordx4 v137, s[30:31]
	s_add_u32 s28, s30, 0x80000
	s_mov_b32 m0, s49
	s_nop 0
	global_load_lds_dwordx4 v139, s[30:31]
	s_addc_u32 s29, s31, 0
	s_mov_b32 m0, s50
	s_nop 0
	global_load_lds_dwordx4 v137, s[28:29]
	s_nop 0
	s_mov_b32 m0, s51
	s_nop 0
	global_load_lds_dwordx4 v139, s[28:29]
	s_nop 0
	s_mov_b32 m0, s10
	s_nop 0
	global_load_lds_dwordx4 v136, s[42:43]
	s_nop 0
	s_mov_b32 m0, s54
	s_nop 0
	global_load_lds_dwordx4 v138, s[42:43]
	s_waitcnt vmcnt(8)
	s_waitcnt lgkmcnt(0)
	s_setprio 0
	s_barrier
; #define PG8_LDA(dst, b, h) do { _Pragma("unroll") for (int m = 0; m < 4; ++m) _Pragma("unroll") for (int k = 0; k < 2; ++k) dst[m][k] = *(const PG8_LAS bf16x8*)(lds + PG8_SA(b, h) + aoff + m * 2048 + k * 1024); } while (0)
; #define PG8_LDB(dst, b, h) do { _Pragma("unroll") for (int n = 0; n < 2; ++n) _Pragma("unroll") for (int k = 0; k < 2; ++k) dst[n][k] = *(const PG8_LAS bf16x8*)(lds + PG8_SB(b, h) + boff + n * 2048 + k * 1024); } while (0)
; #define PG8_MMA(ai, bj, At, Bt) do { __builtin_amdgcn_s_setprio(1); _Pragma("unroll") for (int m = 0; m < 4; ++m) _Pragma("unroll") for (int n = 0; n < 2; ++n) _Pragma("unroll") for (int k = 0; k < 2; ++k) \
;         acc[ai][bj][m][n] = __builtin_amdgcn_mfma_f32_16x16x32_bf16(Bt[n][k], At[m][k], acc[ai][bj][m][n], 0, 0, 0); __builtin_amdgcn_s_setprio(0); } while (0)
; #define PG8_WAIT_V(n) asm volatile("s_waitcnt vmcnt(" #n ")" ::: "memory")
; #define PG8_WAIT_L(n) asm volatile("s_waitcnt lgkmcnt(" #n ")" ::: "memory")
; #define PG8_BAR __builtin_amdgcn_s_barrier()
; #define PG8_SCHED __builtin_amdgcn_sched_barrier(0)
; template <class Epi, class Sched, bool ALIGN_EPI = false, bool SP2 = false>
; __device__ __forceinline__ void gemm_phase(PG8_LAS unsigned char* lds, const Gemm g, const Sched& S, const Epi& E, const int tid) {
;     ...
;             PG8_WAIT_V(8); PG8_WAIT_L(0); PG8_BAR; PG8_MMA(1, 0, At, B0); PG8_MMA(1, 1, At, B1); PG8_BAR; PG8_SCHED;
;             PG8_LDB(B0, 1, 0); PG8_LDB(B1, 1, 1); PG8_SCHED; PG8_LDA(At, 1, 0); PG8_STAGE(PG8_SA(0, 1), a2 + hstepA, voffA);
;             PG8_WAIT_V(8); PG8_WAIT_L(0); PG8_BAR; PG8_MMA(0, 0, At, B0); PG8_MMA(0, 1, At, B1); PG8_BAR; PG8_SCHED;
	v_mfma_f32_16x16x32_bf16 v[62:65], v[146:149], v[178:181], v[62:65]
	v_mfma_f32_16x16x32_bf16 v[62:65], v[150:153], v[182:185], v[62:65]
	v_mfma_f32_16x16x32_bf16 v[58:61], v[154:157], v[178:181], v[58:61]
	v_mfma_f32_16x16x32_bf16 v[58:61], v[158:161], v[182:185], v[58:61]
	v_mfma_f32_16x16x32_bf16 v[54:57], v[146:149], v[186:189], v[54:57]
	v_mfma_f32_16x16x32_bf16 v[54:57], v[150:153], v[190:193], v[54:57]
	v_mfma_f32_16x16x32_bf16 v[46:49], v[154:157], v[186:189], v[46:49]
	v_mfma_f32_16x16x32_bf16 v[46:49], v[158:161], v[190:193], v[46:49]
	v_mfma_f32_16x16x32_bf16 v[38:41], v[146:149], v[194:197], v[38:41]
	v_mfma_f32_16x16x32_bf16 v[38:41], v[150:153], v[198:201], v[38:41]
	v_mfma_f32_16x16x32_bf16 v[30:33], v[154:157], v[194:197], v[30:33]
	v_mfma_f32_16x16x32_bf16 v[30:33], v[158:161], v[198:201], v[30:33]
	v_mfma_f32_16x16x32_bf16 v[22:25], v[146:149], v[202:205], v[22:25]
	v_mfma_f32_16x16x32_bf16 v[22:25], v[150:153], v[206:209], v[22:25]
	v_mfma_f32_16x16x32_bf16 v[14:17], v[154:157], v[202:205], v[14:17]
	v_mfma_f32_16x16x32_bf16 v[14:17], v[158:161], v[206:209], v[14:17]
	v_mfma_f32_16x16x32_bf16 v[50:53], v[162:165], v[178:181], v[50:53]
	v_mfma_f32_16x16x32_bf16 v[50:53], v[166:169], v[182:185], v[50:53]
	v_mfma_f32_16x16x32_bf16 v[42:45], v[170:173], v[178:181], v[42:45]
	v_mfma_f32_16x16x32_bf16 v[42:45], v[174:177], v[182:185], v[42:45]
	v_mfma_f32_16x16x32_bf16 v[34:37], v[162:165], v[186:189], v[34:37]
	v_mfma_f32_16x16x32_bf16 v[34:37], v[166:169], v[190:193], v[34:37]
	v_mfma_f32_16x16x32_bf16 v[26:29], v[170:173], v[186:189], v[26:29]
	v_mfma_f32_16x16x32_bf16 v[26:29], v[174:177], v[190:193], v[26:29]
	v_mfma_f32_16x16x32_bf16 v[18:21], v[162:165], v[194:197], v[18:21]
	v_mfma_f32_16x16x32_bf16 v[18:21], v[166:169], v[198:201], v[18:21]
	v_mfma_f32_16x16x32_bf16 v[10:13], v[170:173], v[194:197], v[10:13]
	v_mfma_f32_16x16x32_bf16 v[10:13], v[174:177], v[198:201], v[10:13]
	v_mfma_f32_16x16x32_bf16 v[6:9], v[162:165], v[202:205], v[6:9]
	v_mfma_f32_16x16x32_bf16 v[6:9], v[166:169], v[206:209], v[6:9]
	v_mfma_f32_16x16x32_bf16 v[2:5], v[170:173], v[202:205], v[2:5]
	v_mfma_f32_16x16x32_bf16 v[2:5], v[174:177], v[206:209], v[2:5]
	s_barrier
	v_add_u32_e32 v133, 0x18000, v144
	s_setprio 1
	ds_read_b128 v[146:149], v133
	ds_read_b128 v[150:153], v133 offset:1024
	ds_read_b128 v[154:157], v133 offset:2048
	ds_read_b128 v[158:161], v133 offset:3072
	v_add_u32_e32 v133, 0x1c000, v144
	ds_read_b128 v[162:165], v133
	ds_read_b128 v[166:169], v133 offset:1024
	ds_read_b128 v[170:173], v133 offset:2048
	ds_read_b128 v[174:177], v133 offset:3072
	ds_read_b128 v[178:181], v145 offset:32768
	ds_read_b128 v[182:185], v145 offset:33792
	ds_read_b128 v[186:189], v145 offset:34816
	ds_read_b128 v[190:193], v145 offset:35840
	ds_read_b128 v[194:197], v145 offset:36864
	ds_read_b128 v[198:201], v145 offset:37888
	ds_read_b128 v[202:205], v145 offset:38912
	ds_read_b128 v[206:209], v145 offset:39936
	s_add_u32 s28, s42, 0x80000
	s_addc_u32 s29, s43, 0
	s_mov_b32 m0, s55
	s_nop 0
	global_load_lds_dwordx4 v136, s[28:29]
	s_nop 0
	s_mov_b32 m0, s56
	s_nop 0
	global_load_lds_dwordx4 v138, s[28:29]
	s_waitcnt vmcnt(8)
	s_waitcnt lgkmcnt(0)
	s_setprio 0
	s_barrier
	v_mfma_f32_16x16x32_bf16 v[126:129], v[146:149], v[178:181], v[126:129]
	v_mfma_f32_16x16x32_bf16 v[126:129], v[150:153], v[182:185], v[126:129]
	v_mfma_f32_16x16x32_bf16 v[122:125], v[154:157], v[178:181], v[122:125]
	v_mfma_f32_16x16x32_bf16 v[122:125], v[158:161], v[182:185], v[122:125]
	v_mfma_f32_16x16x32_bf16 v[118:121], v[146:149], v[186:189], v[118:121]
	v_mfma_f32_16x16x32_bf16 v[118:121], v[150:153], v[190:193], v[118:121]
	v_mfma_f32_16x16x32_bf16 v[110:113], v[154:157], v[186:189], v[110:113]
	v_mfma_f32_16x16x32_bf16 v[110:113], v[158:161], v[190:193], v[110:113]
	v_mfma_f32_16x16x32_bf16 v[102:105], v[146:149], v[194:197], v[102:105]
	v_mfma_f32_16x16x32_bf16 v[102:105], v[150:153], v[198:201], v[102:105]
	v_mfma_f32_16x16x32_bf16 v[94:97], v[154:157], v[194:197], v[94:97]
	v_mfma_f32_16x16x32_bf16 v[94:97], v[158:161], v[198:201], v[94:97]
	v_mfma_f32_16x16x32_bf16 v[86:89], v[146:149], v[202:205], v[86:89]
	v_mfma_f32_16x16x32_bf16 v[86:89], v[150:153], v[206:209], v[86:89]
	v_mfma_f32_16x16x32_bf16 v[78:81], v[154:157], v[202:205], v[78:81]
	v_mfma_f32_16x16x32_bf16 v[78:81], v[158:161], v[206:209], v[78:81]
	v_mfma_f32_16x16x32_bf16 v[114:117], v[162:165], v[178:181], v[114:117]
	v_mfma_f32_16x16x32_bf16 v[114:117], v[166:169], v[182:185], v[114:117]
	v_mfma_f32_16x16x32_bf16 v[106:109], v[170:173], v[178:181], v[106:109]
	v_mfma_f32_16x16x32_bf16 v[106:109], v[174:177], v[182:185], v[106:109]
	v_mfma_f32_16x16x32_bf16 v[98:101], v[162:165], v[186:189], v[98:101]
	v_mfma_f32_16x16x32_bf16 v[98:101], v[166:169], v[190:193], v[98:101]
	v_mfma_f32_16x16x32_bf16 v[90:93], v[170:173], v[186:189], v[90:93]
	v_mfma_f32_16x16x32_bf16 v[90:93], v[174:177], v[190:193], v[90:93]
	v_mfma_f32_16x16x32_bf16 v[82:85], v[162:165], v[194:197], v[82:85]
	v_mfma_f32_16x16x32_bf16 v[82:85], v[166:169], v[198:201], v[82:85]
	v_mfma_f32_16x16x32_bf16 v[74:77], v[170:173], v[194:197], v[74:77]
	v_mfma_f32_16x16x32_bf16 v[74:77], v[174:177], v[198:201], v[74:77]
	v_mfma_f32_16x16x32_bf16 v[70:73], v[162:165], v[202:205], v[70:73]
	v_mfma_f32_16x16x32_bf16 v[70:73], v[166:169], v[206:209], v[70:73]
	v_mfma_f32_16x16x32_bf16 v[66:69], v[170:173], v[202:205], v[66:69]
	v_mfma_f32_16x16x32_bf16 v[66:69], v[174:177], v[206:209], v[66:69]
	s_barrier
; #define PG8_LDA(dst, b, h) do { _Pragma("unroll") for (int m = 0; m < 4; ++m) _Pragma("unroll") for (int k = 0; k < 2; ++k) dst[m][k] = *(const PG8_LAS bf16x8*)(lds + PG8_SA(b, h) + aoff + m * 2048 + k * 1024); } while (0)
; #define PG8_MMA(ai, bj, At, Bt) do { __builtin_amdgcn_s_setprio(1); _Pragma("unroll") for (int m = 0; m < 4; ++m) _Pragma("unroll") for (int n = 0; n < 2; ++n) _Pragma("unroll") for (int k = 0; k < 2; ++k) \
;         acc[ai][bj][m][n] = __builtin_amdgcn_mfma_f32_16x16x32_bf16(Bt[n][k], At[m][k], acc[ai][bj][m][n], 0, 0, 0); __builtin_amdgcn_s_setprio(0); } while (0)
; #define PG8_WAIT_V(n) asm volatile("s_waitcnt vmcnt(" #n ")" ::: "memory")
; #define PG8_WAIT_L(n) asm volatile("s_waitcnt lgkmcnt(" #n ")" ::: "memory")
; #define PG8_BAR __builtin_amdgcn_s_barrier()
; #define PG8_SCHED __builtin_amdgcn_sched_barrier(0)
; template <class Epi, class Sched, bool ALIGN_EPI = false, bool SP2 = false>
; __device__ __forceinline__ void gemm_phase(PG8_LAS unsigned char* lds, const Gemm g, const Sched& S, const Epi& E, const int tid) {
;     ...
;         for (int t = 0; t < nt; t += 2) {
;     ...
;             PG8_LDA(At, 1, 1); PG8_STAGE(PG8_SB(1, 0), b3, voffB); PG8_STAGE(PG8_SB(1, 1), b3 + hstepB, voffB); PG8_STAGE(PG8_SA(1, 0), a3, voffA);
;             PG8_WAIT_V(8); PG8_WAIT_L(0); PG8_BAR; PG8_MMA(1, 0, At, B0); PG8_MMA(1, 1, At, B1); PG8_BAR; PG8_SCHED;
	s_setprio 1
	ds_read_b128 v[178:181], v145 offset:49152
	ds_read_b128 v[182:185], v145 offset:50176
	ds_read_b128 v[186:189], v145 offset:51200
	ds_read_b128 v[190:193], v145 offset:52224
	ds_read_b128 v[194:197], v145 offset:53248
	ds_read_b128 v[198:201], v145 offset:54272
	ds_read_b128 v[202:205], v145 offset:55296
	ds_read_b128 v[206:209], v145 offset:56320
	s_mov_b32 m0, s57
	s_nop 0
	global_load_lds_dwordx4 v137, s[40:41]
	s_add_u32 s28, s30, 0x80080
	s_mov_b32 m0, s58
	s_nop 0
	global_load_lds_dwordx4 v139, s[40:41]
	s_addc_u32 s29, s31, 0
	s_mov_b32 m0, s65
	s_nop 0
	global_load_lds_dwordx4 v137, s[28:29]
	s_nop 0
	s_mov_b32 m0, s69
	s_nop 0
	global_load_lds_dwordx4 v139, s[28:29]
	s_nop 0
	s_mov_b32 m0, s61
	s_nop 0
	global_load_lds_dwordx4 v136, s[38:39]
	s_nop 0
	s_mov_b32 m0, s64
	s_nop 0
	global_load_lds_dwordx4 v138, s[38:39]
	s_waitcnt vmcnt(8)
	s_waitcnt lgkmcnt(0)
	s_setprio 0
	s_barrier
	v_mfma_f32_16x16x32_bf16 v[62:65], v[146:149], v[178:181], v[62:65]
	v_mfma_f32_16x16x32_bf16 v[62:65], v[150:153], v[182:185], v[62:65]
	v_mfma_f32_16x16x32_bf16 v[58:61], v[154:157], v[178:181], v[58:61]
	v_mfma_f32_16x16x32_bf16 v[58:61], v[158:161], v[182:185], v[58:61]
	v_mfma_f32_16x16x32_bf16 v[54:57], v[146:149], v[186:189], v[54:57]
	v_mfma_f32_16x16x32_bf16 v[54:57], v[150:153], v[190:193], v[54:57]
	v_mfma_f32_16x16x32_bf16 v[46:49], v[154:157], v[186:189], v[46:49]
	v_mfma_f32_16x16x32_bf16 v[46:49], v[158:161], v[190:193], v[46:49]
	v_mfma_f32_16x16x32_bf16 v[38:41], v[146:149], v[194:197], v[38:41]
	v_mfma_f32_16x16x32_bf16 v[38:41], v[150:153], v[198:201], v[38:41]
	v_mfma_f32_16x16x32_bf16 v[30:33], v[154:157], v[194:197], v[30:33]
	v_mfma_f32_16x16x32_bf16 v[30:33], v[158:161], v[198:201], v[30:33]
	v_mfma_f32_16x16x32_bf16 v[22:25], v[146:149], v[202:205], v[22:25]
	v_mfma_f32_16x16x32_bf16 v[22:25], v[150:153], v[206:209], v[22:25]
	v_mfma_f32_16x16x32_bf16 v[14:17], v[154:157], v[202:205], v[14:17]
	v_mfma_f32_16x16x32_bf16 v[14:17], v[158:161], v[206:209], v[14:17]
	v_mfma_f32_16x16x32_bf16 v[50:53], v[162:165], v[178:181], v[50:53]
	v_mfma_f32_16x16x32_bf16 v[50:53], v[166:169], v[182:185], v[50:53]
	v_mfma_f32_16x16x32_bf16 v[42:45], v[170:173], v[178:181], v[42:45]
	v_mfma_f32_16x16x32_bf16 v[42:45], v[174:177], v[182:185], v[42:45]
	v_mfma_f32_16x16x32_bf16 v[34:37], v[162:165], v[186:189], v[34:37]
	v_mfma_f32_16x16x32_bf16 v[34:37], v[166:169], v[190:193], v[34:37]
	v_mfma_f32_16x16x32_bf16 v[26:29], v[170:173], v[186:189], v[26:29]
	v_mfma_f32_16x16x32_bf16 v[26:29], v[174:177], v[190:193], v[26:29]
	v_mfma_f32_16x16x32_bf16 v[18:21], v[162:165], v[194:197], v[18:21]
	v_mfma_f32_16x16x32_bf16 v[18:21], v[166:169], v[198:201], v[18:21]
	v_mfma_f32_16x16x32_bf16 v[10:13], v[170:173], v[194:197], v[10:13]
	v_mfma_f32_16x16x32_bf16 v[10:13], v[174:177], v[198:201], v[10:13]
	v_mfma_f32_16x16x32_bf16 v[6:9], v[162:165], v[202:205], v[6:9]
	v_mfma_f32_16x16x32_bf16 v[6:9], v[166:169], v[206:209], v[6:9]
	v_mfma_f32_16x16x32_bf16 v[2:5], v[170:173], v[202:205], v[2:5]
	v_mfma_f32_16x16x32_bf16 v[2:5], v[174:177], v[206:209], v[2:5]
	s_barrier
	s_add_i32 s67, s67, 2
	s_add_u32 s97, s97, 0x100
	s_addc_u32 s59, s59, 0
	s_cmp_gt_u32 s67, 29
	s_mov_b64 s[28:29], s[34:35]
	s_cbranch_scc1 .LBB0_549

; #define PG8_LDA(dst, b, h) do { _Pragma("unroll") for (int m = 0; m < 4; ++m) _Pragma("unroll") for (int k = 0; k < 2; ++k) dst[m][k] = *(const PG8_LAS bf16x8*)(lds + PG8_SA(b, h) + aoff + m * 2048 + k * 1024); } while (0)
; #define PG8_LDB(dst, b, h) do { _Pragma("unroll") for (int n = 0; n < 2; ++n) _Pragma("unroll") for (int k = 0; k < 2; ++k) dst[n][k] = *(const PG8_LAS bf16x8*)(lds + PG8_SB(b, h) + boff + n * 2048 + k * 1024); } while (0)
; #define PG8_MMA(ai, bj, At, Bt) do { __builtin_amdgcn_s_setprio(1); _Pragma("unroll") for (int m = 0; m < 4; ++m) _Pragma("unroll") for (int n = 0; n < 2; ++n) _Pragma("unroll") for (int k = 0; k < 2; ++k) \
;         acc[ai][bj][m][n] = __builtin_amdgcn_mfma_f32_16x16x32_bf16(Bt[n][k], At[m][k], acc[ai][bj][m][n], 0, 0, 0); __builtin_amdgcn_s_setprio(0); } while (0)
; #define PG8_WAIT_V(n) asm volatile("s_waitcnt vmcnt(" #n ")" ::: "memory")
; #define PG8_WAIT_L(n) asm volatile("s_waitcnt lgkmcnt(" #n ")" ::: "memory")
; #define PG8_BAR __builtin_amdgcn_s_barrier()
; #define PG8_SCHED __builtin_amdgcn_sched_barrier(0)
; template <class Epi, class Sched, bool ALIGN_EPI = false, bool SP2 = false>
; __device__ __forceinline__ void gemm_phase(PG8_LAS unsigned char* lds, const Gemm g, const Sched& S, const Epi& E, const int tid) {
;     ...
;             const char* a2 = last ? nA : cA + (size_t)(t + 2) * kstepA; const char* b2 = last ? nB : cB + (size_t)(t + 2) * kstepB;
;             const char* a3 = a2 + kstepA; const char* b3 = b2 + kstepB;
;             if (last && has_next) S.a_ready(nxt);
;             if constexpr (SP2) {
;             PG8_LDB(B0, 0, 0); PG8_LDB(B1, 0, 1); PG8_SCHED; PG8_LDA(At, 0, 0); PG8_STAGE(PG8_SA(1, 1), a1 + hstepA, voffA);
;             PG8_WAIT_V(8); PG8_WAIT_L(0); PG8_BAR; PG8_MMA(0, 0, At, B0); PG8_MMA(0, 1, At, B1); PG8_BAR; PG8_SCHED;
;             PG8_LDA(At, 0, 1); PG8_STAGE(PG8_SB(0, 0), b2, voffB); PG8_STAGE(PG8_SB(0, 1), b2 + hstepB, voffB); PG8_STAGE(PG8_SA(0, 0), a2, voffA);
;             PG8_WAIT_V(8); PG8_WAIT_L(0); PG8_BAR; PG8_MMA(1, 0, At, B0); PG8_MMA(1, 1, At, B1); PG8_BAR; PG8_SCHED;
.LBB0_813:
	v_add_u32_e32 v0, 0x10000, v135
	s_setprio 1
	ds_read_b128 v[138:141], v0
	ds_read_b128 v[142:145], v0 offset:1024
	ds_read_b128 v[146:149], v0 offset:2048
	ds_read_b128 v[150:153], v0 offset:3072
	v_add_u32_e32 v0, 0x14000, v135
	ds_read_b128 v[154:157], v0
	ds_read_b128 v[158:161], v0 offset:1024
	ds_read_b128 v[162:165], v0 offset:2048
	ds_read_b128 v[166:169], v0 offset:3072
	s_add_u32 s4, s18, 0x100
	s_addc_u32 s5, s19, 0
	s_cmp_eq_u32 s61, 12
	s_cselect_b32 s24, s14, s4
	s_cselect_b32 s25, s15, s5
	s_cselect_b32 s22, s57, s58
	s_cselect_b32 s23, s13, s59
	s_add_u32 s20, s24, 0x80
	s_addc_u32 s21, s25, 0
	ds_read_b128 v[170:173], v136
	ds_read_b128 v[174:177], v136 offset:1024
	ds_read_b128 v[178:181], v136 offset:2048
	ds_read_b128 v[182:185], v136 offset:3072
	ds_read_b128 v[186:189], v136 offset:4096
	ds_read_b128 v[190:193], v136 offset:5120
	ds_read_b128 v[194:197], v136 offset:6144
	ds_read_b128 v[198:201], v136 offset:7168
	s_add_u32 s18, s18, 0xc0080
	s_addc_u32 s19, s19, 0
	s_mov_b32 m0, s49
	s_nop 0
	global_load_lds_dwordx4 v131, s[18:19]
	s_nop 0
	s_mov_b32 m0, s50
	s_nop 0
	global_load_lds_dwordx4 v133, s[18:19]
	s_waitcnt vmcnt(8)
	s_waitcnt lgkmcnt(0)
	s_setprio 0
	s_barrier
	v_mfma_f32_16x16x32_bf16 v[126:129], v[138:141], v[170:173], v[126:129]
	v_mfma_f32_16x16x32_bf16 v[126:129], v[142:145], v[174:177], v[126:129]
	v_mfma_f32_16x16x32_bf16 v[122:125], v[146:149], v[170:173], v[122:125]
	v_mfma_f32_16x16x32_bf16 v[122:125], v[150:153], v[174:177], v[122:125]
	v_mfma_f32_16x16x32_bf16 v[118:121], v[138:141], v[178:181], v[118:121]
	v_mfma_f32_16x16x32_bf16 v[118:121], v[142:145], v[182:185], v[118:121]
	v_mfma_f32_16x16x32_bf16 v[114:117], v[146:149], v[178:181], v[114:117]
	v_mfma_f32_16x16x32_bf16 v[114:117], v[150:153], v[182:185], v[114:117]
	v_mfma_f32_16x16x32_bf16 v[102:105], v[138:141], v[186:189], v[102:105]
	v_mfma_f32_16x16x32_bf16 v[102:105], v[142:145], v[190:193], v[102:105]
	v_mfma_f32_16x16x32_bf16 v[98:101], v[146:149], v[186:189], v[98:101]
	v_mfma_f32_16x16x32_bf16 v[98:101], v[150:153], v[190:193], v[98:101]
	v_mfma_f32_16x16x32_bf16 v[86:89], v[138:141], v[194:197], v[86:89]
	v_mfma_f32_16x16x32_bf16 v[86:89], v[142:145], v[198:201], v[86:89]
	v_mfma_f32_16x16x32_bf16 v[82:85], v[146:149], v[194:197], v[82:85]
	v_mfma_f32_16x16x32_bf16 v[82:85], v[150:153], v[198:201], v[82:85]
	v_mfma_f32_16x16x32_bf16 v[110:113], v[154:157], v[170:173], v[110:113]
	v_mfma_f32_16x16x32_bf16 v[110:113], v[158:161], v[174:177], v[110:113]
	v_mfma_f32_16x16x32_bf16 v[106:109], v[162:165], v[170:173], v[106:109]
	v_mfma_f32_16x16x32_bf16 v[106:109], v[166:169], v[174:177], v[106:109]
	v_mfma_f32_16x16x32_bf16 v[94:97], v[154:157], v[178:181], v[94:97]
	v_mfma_f32_16x16x32_bf16 v[94:97], v[158:161], v[182:185], v[94:97]
	v_mfma_f32_16x16x32_bf16 v[90:93], v[162:165], v[178:181], v[90:93]
	v_mfma_f32_16x16x32_bf16 v[90:93], v[166:169], v[182:185], v[90:93]
	v_mfma_f32_16x16x32_bf16 v[78:81], v[154:157], v[186:189], v[78:81]
	v_mfma_f32_16x16x32_bf16 v[78:81], v[158:161], v[190:193], v[78:81]
	v_mfma_f32_16x16x32_bf16 v[74:77], v[162:165], v[186:189], v[74:77]
	v_mfma_f32_16x16x32_bf16 v[74:77], v[166:169], v[190:193], v[74:77]
	v_mfma_f32_16x16x32_bf16 v[70:73], v[154:157], v[194:197], v[70:73]
	v_mfma_f32_16x16x32_bf16 v[70:73], v[158:161], v[198:201], v[70:73]
	v_mfma_f32_16x16x32_bf16 v[66:69], v[162:165], v[194:197], v[66:69]
	v_mfma_f32_16x16x32_bf16 v[66:69], v[166:169], v[198:201], v[66:69]
	s_barrier
	s_setprio 1
	ds_read_b128 v[170:173], v136 offset:16384
	ds_read_b128 v[174:177], v136 offset:17408
	ds_read_b128 v[178:181], v136 offset:18432
	ds_read_b128 v[182:185], v136 offset:19456
	ds_read_b128 v[186:189], v136 offset:20480
	ds_read_b128 v[190:193], v136 offset:21504
	ds_read_b128 v[194:197], v136 offset:22528
	ds_read_b128 v[198:201], v136 offset:23552
	s_mov_b32 m0, s31
	s_nop 0
	global_load_lds_dwordx4 v132, s[22:23]
	s_nop 0
	s_mov_b32 m0, s34
	s_nop 0
	global_load_lds_dwordx4 v134, s[22:23]
	s_add_u32 s18, s22, 0x40000
	s_addc_u32 s19, s23, 0
	s_mov_b32 m0, s35
	s_nop 0
	global_load_lds_dwordx4 v132, s[18:19]
	s_nop 0
	s_mov_b32 m0, s37
	s_nop 0
	global_load_lds_dwordx4 v134, s[18:19]
	s_mov_b32 m0, s10
	s_nop 0
	global_load_lds_dwordx4 v131, s[24:25]
	s_nop 0
	s_mov_b32 m0, s38
	s_nop 0
	global_load_lds_dwordx4 v133, s[24:25]
	s_waitcnt vmcnt(8)
	s_waitcnt lgkmcnt(0)
	s_setprio 0
	s_barrier
	v_mfma_f32_16x16x32_bf16 v[62:65], v[138:141], v[170:173], v[62:65]
	v_mfma_f32_16x16x32_bf16 v[62:65], v[142:145], v[174:177], v[62:65]
	v_mfma_f32_16x16x32_bf16 v[58:61], v[146:149], v[170:173], v[58:61]
	v_mfma_f32_16x16x32_bf16 v[58:61], v[150:153], v[174:177], v[58:61]
	v_mfma_f32_16x16x32_bf16 v[54:57], v[138:141], v[178:181], v[54:57]
	v_mfma_f32_16x16x32_bf16 v[54:57], v[142:145], v[182:185], v[54:57]
	v_mfma_f32_16x16x32_bf16 v[50:53], v[146:149], v[178:181], v[50:53]
	v_mfma_f32_16x16x32_bf16 v[50:53], v[150:153], v[182:185], v[50:53]
	v_mfma_f32_16x16x32_bf16 v[38:41], v[138:141], v[186:189], v[38:41]
	v_mfma_f32_16x16x32_bf16 v[38:41], v[142:145], v[190:193], v[38:41]
	v_mfma_f32_16x16x32_bf16 v[34:37], v[146:149], v[186:189], v[34:37]
	v_mfma_f32_16x16x32_bf16 v[34:37], v[150:153], v[190:193], v[34:37]
	v_mfma_f32_16x16x32_bf16 v[22:25], v[138:141], v[194:197], v[22:25]
	v_mfma_f32_16x16x32_bf16 v[22:25], v[142:145], v[198:201], v[22:25]
	v_mfma_f32_16x16x32_bf16 v[18:21], v[146:149], v[194:197], v[18:21]
	v_mfma_f32_16x16x32_bf16 v[18:21], v[150:153], v[198:201], v[18:21]
	v_mfma_f32_16x16x32_bf16 v[46:49], v[154:157], v[170:173], v[46:49]
	v_mfma_f32_16x16x32_bf16 v[46:49], v[158:161], v[174:177], v[46:49]
	v_mfma_f32_16x16x32_bf16 v[42:45], v[162:165], v[170:173], v[42:45]
	v_mfma_f32_16x16x32_bf16 v[42:45], v[166:169], v[174:177], v[42:45]
	v_mfma_f32_16x16x32_bf16 v[30:33], v[154:157], v[178:181], v[30:33]
	v_mfma_f32_16x16x32_bf16 v[30:33], v[158:161], v[182:185], v[30:33]
	v_mfma_f32_16x16x32_bf16 v[26:29], v[162:165], v[178:181], v[26:29]
	v_mfma_f32_16x16x32_bf16 v[26:29], v[166:169], v[182:185], v[26:29]
	v_mfma_f32_16x16x32_bf16 v[14:17], v[154:157], v[186:189], v[14:17]
	v_mfma_f32_16x16x32_bf16 v[14:17], v[158:161], v[190:193], v[14:17]
	v_mfma_f32_16x16x32_bf16 v[10:13], v[162:165], v[186:189], v[10:13]
	v_mfma_f32_16x16x32_bf16 v[10:13], v[166:169], v[190:193], v[10:13]
	v_mfma_f32_16x16x32_bf16 v[6:9], v[154:157], v[194:197], v[6:9]
	v_mfma_f32_16x16x32_bf16 v[6:9], v[158:161], v[198:201], v[6:9]
	v_mfma_f32_16x16x32_bf16 v[2:5], v[162:165], v[194:197], v[2:5]
	v_mfma_f32_16x16x32_bf16 v[2:5], v[166:169], v[198:201], v[2:5]
	s_barrier
; #define PG8_LDA(dst, b, h) do { _Pragma("unroll") for (int m = 0; m < 4; ++m) _Pragma("unroll") for (int k = 0; k < 2; ++k) dst[m][k] = *(const PG8_LAS bf16x8*)(lds + PG8_SA(b, h) + aoff + m * 2048 + k * 1024); } while (0)
; #define PG8_LDB(dst, b, h) do { _Pragma("unroll") for (int n = 0; n < 2; ++n) _Pragma("unroll") for (int k = 0; k < 2; ++k) dst[n][k] = *(const PG8_LAS bf16x8*)(lds + PG8_SB(b, h) + boff + n * 2048 + k * 1024); } while (0)
; #define PG8_MMA(ai, bj, At, Bt) do { __builtin_amdgcn_s_setprio(1); _Pragma("unroll") for (int m = 0; m < 4; ++m) _Pragma("unroll") for (int n = 0; n < 2; ++n) _Pragma("unroll") for (int k = 0; k < 2; ++k) \
;         acc[ai][bj][m][n] = __builtin_amdgcn_mfma_f32_16x16x32_bf16(Bt[n][k], At[m][k], acc[ai][bj][m][n], 0, 0, 0); __builtin_amdgcn_s_setprio(0); } while (0)
; #define PG8_WAIT_V(n) asm volatile("s_waitcnt vmcnt(" #n ")" ::: "memory")
; #define PG8_WAIT_L(n) asm volatile("s_waitcnt lgkmcnt(" #n ")" ::: "memory")
; #define PG8_BAR __builtin_amdgcn_s_barrier()
; #define PG8_SCHED __builtin_amdgcn_sched_barrier(0)
; template <class Epi, class Sched, bool ALIGN_EPI = false, bool SP2 = false>
; __device__ __forceinline__ void gemm_phase(PG8_LAS unsigned char* lds, const Gemm g, const Sched& S, const Epi& E, const int tid) {
;     ...
;         for (int t = 0; t < nt; t += 2) {
;     ...
;             PG8_LDB(B0, 1, 0); PG8_LDB(B1, 1, 1); PG8_SCHED; PG8_LDA(At, 1, 0); PG8_STAGE(PG8_SA(0, 1), a2 + hstepA, voffA);
;             PG8_WAIT_V(8); PG8_WAIT_L(0); PG8_BAR; PG8_MMA(0, 0, At, B0); PG8_MMA(0, 1, At, B1); PG8_BAR; PG8_SCHED;
;             PG8_LDA(At, 1, 1); PG8_STAGE(PG8_SB(1, 0), b3, voffB); PG8_STAGE(PG8_SB(1, 1), b3 + hstepB, voffB); PG8_STAGE(PG8_SA(1, 0), a3, voffA);
;             PG8_WAIT_V(8); PG8_WAIT_L(0); PG8_BAR; PG8_MMA(1, 0, At, B0); PG8_MMA(1, 1, At, B1); PG8_BAR; PG8_SCHED;
	v_add_u32_e32 v0, 0x18000, v135
	s_setprio 1
	ds_read_b128 v[138:141], v0
	ds_read_b128 v[142:145], v0 offset:1024
	ds_read_b128 v[146:149], v0 offset:2048
	ds_read_b128 v[150:153], v0 offset:3072
	v_add_u32_e32 v0, 0x1c000, v135
	ds_read_b128 v[154:157], v0
	ds_read_b128 v[158:161], v0 offset:1024
	ds_read_b128 v[162:165], v0 offset:2048
	ds_read_b128 v[166:169], v0 offset:3072
	ds_read_b128 v[170:173], v136 offset:32768
	ds_read_b128 v[174:177], v136 offset:33792
	ds_read_b128 v[178:181], v136 offset:34816
	ds_read_b128 v[182:185], v136 offset:35840
	ds_read_b128 v[186:189], v136 offset:36864
	ds_read_b128 v[190:193], v136 offset:37888
	ds_read_b128 v[194:197], v136 offset:38912
	ds_read_b128 v[198:201], v136 offset:39936
	s_add_u32 s18, s24, 0xc0000
	s_addc_u32 s19, s25, 0
	s_mov_b32 m0, s39
	s_nop 0
	global_load_lds_dwordx4 v131, s[18:19]
	s_nop 0
	s_mov_b32 m0, s40
	s_nop 0
	global_load_lds_dwordx4 v133, s[18:19]
	s_waitcnt vmcnt(8)
	s_waitcnt lgkmcnt(0)
	s_setprio 0
	s_barrier
	v_mfma_f32_16x16x32_bf16 v[126:129], v[138:141], v[170:173], v[126:129]
	v_mfma_f32_16x16x32_bf16 v[126:129], v[142:145], v[174:177], v[126:129]
	v_mfma_f32_16x16x32_bf16 v[122:125], v[146:149], v[170:173], v[122:125]
	v_mfma_f32_16x16x32_bf16 v[122:125], v[150:153], v[174:177], v[122:125]
	v_mfma_f32_16x16x32_bf16 v[118:121], v[138:141], v[178:181], v[118:121]
	v_mfma_f32_16x16x32_bf16 v[118:121], v[142:145], v[182:185], v[118:121]
	v_mfma_f32_16x16x32_bf16 v[114:117], v[146:149], v[178:181], v[114:117]
	v_mfma_f32_16x16x32_bf16 v[114:117], v[150:153], v[182:185], v[114:117]
	v_mfma_f32_16x16x32_bf16 v[102:105], v[138:141], v[186:189], v[102:105]
	v_mfma_f32_16x16x32_bf16 v[102:105], v[142:145], v[190:193], v[102:105]
	v_mfma_f32_16x16x32_bf16 v[98:101], v[146:149], v[186:189], v[98:101]
	v_mfma_f32_16x16x32_bf16 v[98:101], v[150:153], v[190:193], v[98:101]
	v_mfma_f32_16x16x32_bf16 v[86:89], v[138:141], v[194:197], v[86:89]
	v_mfma_f32_16x16x32_bf16 v[86:89], v[142:145], v[198:201], v[86:89]
	v_mfma_f32_16x16x32_bf16 v[82:85], v[146:149], v[194:197], v[82:85]
	v_mfma_f32_16x16x32_bf16 v[82:85], v[150:153], v[198:201], v[82:85]
	v_mfma_f32_16x16x32_bf16 v[110:113], v[154:157], v[170:173], v[110:113]
	v_mfma_f32_16x16x32_bf16 v[110:113], v[158:161], v[174:177], v[110:113]
	v_mfma_f32_16x16x32_bf16 v[106:109], v[162:165], v[170:173], v[106:109]
	v_mfma_f32_16x16x32_bf16 v[106:109], v[166:169], v[174:177], v[106:109]
	v_mfma_f32_16x16x32_bf16 v[94:97], v[154:157], v[178:181], v[94:97]
	v_mfma_f32_16x16x32_bf16 v[94:97], v[158:161], v[182:185], v[94:97]
	v_mfma_f32_16x16x32_bf16 v[90:93], v[162:165], v[178:181], v[90:93]
	v_mfma_f32_16x16x32_bf16 v[90:93], v[166:169], v[182:185], v[90:93]
	v_mfma_f32_16x16x32_bf16 v[78:81], v[154:157], v[186:189], v[78:81]
	v_mfma_f32_16x16x32_bf16 v[78:81], v[158:161], v[190:193], v[78:81]
	v_mfma_f32_16x16x32_bf16 v[74:77], v[162:165], v[186:189], v[74:77]
	v_mfma_f32_16x16x32_bf16 v[74:77], v[166:169], v[190:193], v[74:77]
	v_mfma_f32_16x16x32_bf16 v[70:73], v[154:157], v[194:197], v[70:73]
	v_mfma_f32_16x16x32_bf16 v[70:73], v[158:161], v[198:201], v[70:73]
	v_mfma_f32_16x16x32_bf16 v[66:69], v[162:165], v[194:197], v[66:69]
	v_mfma_f32_16x16x32_bf16 v[66:69], v[166:169], v[198:201], v[66:69]
	s_barrier
	s_setprio 1
	ds_read_b128 v[170:173], v136 offset:49152
	ds_read_b128 v[174:177], v136 offset:50176
	ds_read_b128 v[178:181], v136 offset:51200
	ds_read_b128 v[182:185], v136 offset:52224
	ds_read_b128 v[186:189], v136 offset:53248
	ds_read_b128 v[190:193], v136 offset:54272
	ds_read_b128 v[194:197], v136 offset:55296
	ds_read_b128 v[198:201], v136 offset:56320
	s_add_u32 s18, s22, 0x80
	s_addc_u32 s19, s23, 0
	s_mov_b32 m0, s43
	s_nop 0
	global_load_lds_dwordx4 v132, s[18:19]
	s_nop 0
	s_mov_b32 m0, s44
	s_nop 0
	global_load_lds_dwordx4 v134, s[18:19]
	s_add_u32 s18, s22, 0x40080
	s_addc_u32 s19, s23, 0
	s_mov_b32 m0, s47
	s_nop 0
	global_load_lds_dwordx4 v132, s[18:19]
	s_nop 0
	s_mov_b32 m0, s48
	s_nop 0
	global_load_lds_dwordx4 v134, s[18:19]
	s_mov_b32 m0, s45
	s_nop 0
	global_load_lds_dwordx4 v131, s[20:21]
	s_nop 0
	s_mov_b32 m0, s46
	s_nop 0
	global_load_lds_dwordx4 v133, s[20:21]
	s_waitcnt vmcnt(8)
	s_waitcnt lgkmcnt(0)
	s_setprio 0
	s_barrier
	v_mfma_f32_16x16x32_bf16 v[62:65], v[138:141], v[170:173], v[62:65]
	v_mfma_f32_16x16x32_bf16 v[62:65], v[142:145], v[174:177], v[62:65]
	v_mfma_f32_16x16x32_bf16 v[58:61], v[146:149], v[170:173], v[58:61]
	v_mfma_f32_16x16x32_bf16 v[58:61], v[150:153], v[174:177], v[58:61]
	v_mfma_f32_16x16x32_bf16 v[54:57], v[138:141], v[178:181], v[54:57]
	v_mfma_f32_16x16x32_bf16 v[54:57], v[142:145], v[182:185], v[54:57]
	v_mfma_f32_16x16x32_bf16 v[50:53], v[146:149], v[178:181], v[50:53]
	v_mfma_f32_16x16x32_bf16 v[50:53], v[150:153], v[182:185], v[50:53]
	v_mfma_f32_16x16x32_bf16 v[38:41], v[138:141], v[186:189], v[38:41]
	v_mfma_f32_16x16x32_bf16 v[38:41], v[142:145], v[190:193], v[38:41]
	v_mfma_f32_16x16x32_bf16 v[34:37], v[146:149], v[186:189], v[34:37]
	v_mfma_f32_16x16x32_bf16 v[34:37], v[150:153], v[190:193], v[34:37]
	v_mfma_f32_16x16x32_bf16 v[22:25], v[138:141], v[194:197], v[22:25]
	v_mfma_f32_16x16x32_bf16 v[22:25], v[142:145], v[198:201], v[22:25]
	v_mfma_f32_16x16x32_bf16 v[18:21], v[146:149], v[194:197], v[18:21]
	v_mfma_f32_16x16x32_bf16 v[18:21], v[150:153], v[198:201], v[18:21]
	v_mfma_f32_16x16x32_bf16 v[46:49], v[154:157], v[170:173], v[46:49]
	v_mfma_f32_16x16x32_bf16 v[46:49], v[158:161], v[174:177], v[46:49]
	v_mfma_f32_16x16x32_bf16 v[42:45], v[162:165], v[170:173], v[42:45]
	v_mfma_f32_16x16x32_bf16 v[42:45], v[166:169], v[174:177], v[42:45]
	v_mfma_f32_16x16x32_bf16 v[30:33], v[154:157], v[178:181], v[30:33]
	v_mfma_f32_16x16x32_bf16 v[30:33], v[158:161], v[182:185], v[30:33]
	v_mfma_f32_16x16x32_bf16 v[26:29], v[162:165], v[178:181], v[26:29]
	v_mfma_f32_16x16x32_bf16 v[26:29], v[166:169], v[182:185], v[26:29]
	v_mfma_f32_16x16x32_bf16 v[14:17], v[154:157], v[186:189], v[14:17]
	v_mfma_f32_16x16x32_bf16 v[14:17], v[158:161], v[190:193], v[14:17]
	v_mfma_f32_16x16x32_bf16 v[10:13], v[162:165], v[186:189], v[10:13]
	v_mfma_f32_16x16x32_bf16 v[10:13], v[166:169], v[190:193], v[10:13]
	v_mfma_f32_16x16x32_bf16 v[6:9], v[154:157], v[194:197], v[6:9]
	v_mfma_f32_16x16x32_bf16 v[6:9], v[158:161], v[198:201], v[6:9]
	v_mfma_f32_16x16x32_bf16 v[2:5], v[162:165], v[194:197], v[2:5]
	v_mfma_f32_16x16x32_bf16 v[2:5], v[166:169], v[198:201], v[2:5]
	s_barrier
	s_add_i32 s61, s61, 2
	s_add_u32 s58, s58, 0x100
	s_addc_u32 s59, s59, 0
	s_cmp_gt_u32 s61, 13
	s_mov_b64 s[18:19], s[4:5]
	s_cbranch_scc0 .LBB0_813
	s_and_b64 vcc, exec, s[8:9]
	s_cbranch_vccz .LBB0_816
	s_barrier

; #define PG8_LDA(dst, b, h) do { _Pragma("unroll") for (int m = 0; m < 4; ++m) _Pragma("unroll") for (int k = 0; k < 2; ++k) dst[m][k] = *(const PG8_LAS bf16x8*)(lds + PG8_SA(b, h) + aoff + m * 2048 + k * 1024); } while (0)
; #define PG8_LDB(dst, b, h) do { _Pragma("unroll") for (int n = 0; n < 2; ++n) _Pragma("unroll") for (int k = 0; k < 2; ++k) dst[n][k] = *(const PG8_LAS bf16x8*)(lds + PG8_SB(b, h) + boff + n * 2048 + k * 1024); } while (0)
; #define PG8_MMA(ai, bj, At, Bt) do { __builtin_amdgcn_s_setprio(1); _Pragma("unroll") for (int m = 0; m < 4; ++m) _Pragma("unroll") for (int n = 0; n < 2; ++n) _Pragma("unroll") for (int k = 0; k < 2; ++k) \
;         acc[ai][bj][m][n] = __builtin_amdgcn_mfma_f32_16x16x32_bf16(Bt[n][k], At[m][k], acc[ai][bj][m][n], 0, 0, 0); __builtin_amdgcn_s_setprio(0); } while (0)
; #define PG8_WAIT_V(n) asm volatile("s_waitcnt vmcnt(" #n ")" ::: "memory")
; #define PG8_WAIT_L(n) asm volatile("s_waitcnt lgkmcnt(" #n ")" ::: "memory")
; #define PG8_BAR __builtin_amdgcn_s_barrier()
; #define PG8_SCHED __builtin_amdgcn_sched_barrier(0)
; template <class Epi, class Sched, bool ALIGN_EPI = false, bool SP2 = false>
; __device__ __forceinline__ void gemm_phase(PG8_LAS unsigned char* lds, const Gemm g, const Sched& S, const Epi& E, const int tid) {
;     ...
;             const char* a2 = last ? nA : cA + (size_t)(t + 2) * kstepA; const char* b2 = last ? nB : cB + (size_t)(t + 2) * kstepB;
;             const char* a3 = a2 + kstepA; const char* b3 = b2 + kstepB;
;             if (last && has_next) S.a_ready(nxt);
;             if constexpr (SP2) {
;             PG8_LDB(B0, 0, 0); PG8_LDB(B1, 0, 1); PG8_SCHED; PG8_LDA(At, 0, 0); PG8_STAGE(PG8_SA(1, 1), a1 + hstepA, voffA);
;             PG8_WAIT_V(8); PG8_WAIT_L(0); PG8_BAR; PG8_MMA(0, 0, At, B0); PG8_MMA(0, 1, At, B1); PG8_BAR; PG8_SCHED;
;             PG8_LDA(At, 0, 1); PG8_STAGE(PG8_SB(0, 0), b2, voffB); PG8_STAGE(PG8_SB(0, 1), b2 + hstepB, voffB); PG8_STAGE(PG8_SA(0, 0), a2, voffA);
.LBB0_899:
	s_or_b64 exec, exec, s[42:43]
	v_add_u32_e32 v144, 0x10000, v200
	v_add_u32_e32 v160, 0x14000, v200
	s_add_u32 s42, s34, 0x100
	s_setprio 1
	ds_read_b128 v[132:135], v144
	ds_read_b128 v[136:139], v144 offset:1024
	ds_read_b128 v[140:143], v144 offset:2048
	ds_read_b128 v[144:147], v144 offset:3072
	ds_read_b128 v[148:151], v160
	ds_read_b128 v[152:155], v160 offset:1024
	ds_read_b128 v[156:159], v160 offset:2048
	ds_read_b128 v[160:163], v160 offset:3072
	s_addc_u32 s43, s35, 0
	s_and_b64 s[40:41], s[40:41], exec
	s_cselect_b32 s48, vcc_lo, s42
	s_cselect_b32 s49, s21, s43
	s_cselect_b32 s41, s23, s67
	s_cselect_b32 s40, vcc_hi, s59
	s_add_u32 s44, s48, 0x80
	s_addc_u32 s45, s49, 0
	s_add_u32 s46, s40, 0x80
	s_addc_u32 s47, s41, 0
	ds_read_b128 v[164:167], v201
	ds_read_b128 v[168:171], v201 offset:1024
	ds_read_b128 v[172:175], v201 offset:2048
	ds_read_b128 v[176:179], v201 offset:3072
	ds_read_b128 v[180:183], v201 offset:4096
	ds_read_b128 v[184:187], v201 offset:5120
	ds_read_b128 v[202:205], v201 offset:6144
	ds_read_b128 v[206:209], v201 offset:7168
	s_add_u32 s34, s34, 0x80080
	s_addc_u32 s35, s35, 0
	s_mov_b32 m0, s96
	s_nop 0
	global_load_lds_dwordx4 v192, s[34:35]
	s_nop 0
	s_mov_b32 m0, s97
	s_nop 0
	global_load_lds_dwordx4 v194, s[34:35]
	s_waitcnt vmcnt(8)
	s_waitcnt lgkmcnt(0)
	s_setprio 0
	s_barrier
	v_mfma_f32_16x16x32_bf16 v[126:129], v[132:135], v[164:167], v[126:129]
	v_mfma_f32_16x16x32_bf16 v[126:129], v[136:139], v[168:171], v[126:129]
	v_mfma_f32_16x16x32_bf16 v[122:125], v[140:143], v[164:167], v[122:125]
	v_mfma_f32_16x16x32_bf16 v[122:125], v[144:147], v[168:171], v[122:125]
	v_mfma_f32_16x16x32_bf16 v[118:121], v[132:135], v[172:175], v[118:121]
	v_mfma_f32_16x16x32_bf16 v[118:121], v[136:139], v[176:179], v[118:121]
	v_mfma_f32_16x16x32_bf16 v[114:117], v[140:143], v[172:175], v[114:117]
	v_mfma_f32_16x16x32_bf16 v[114:117], v[144:147], v[176:179], v[114:117]
	v_mfma_f32_16x16x32_bf16 v[94:97], v[132:135], v[180:183], v[94:97]
	v_mfma_f32_16x16x32_bf16 v[94:97], v[136:139], v[184:187], v[94:97]
	v_mfma_f32_16x16x32_bf16 v[90:93], v[140:143], v[180:183], v[90:93]
	v_mfma_f32_16x16x32_bf16 v[90:93], v[144:147], v[184:187], v[90:93]
	v_mfma_f32_16x16x32_bf16 v[78:81], v[132:135], v[202:205], v[78:81]
	v_mfma_f32_16x16x32_bf16 v[78:81], v[136:139], v[206:209], v[78:81]
	v_mfma_f32_16x16x32_bf16 v[74:77], v[140:143], v[202:205], v[74:77]
	v_mfma_f32_16x16x32_bf16 v[74:77], v[144:147], v[206:209], v[74:77]
	v_mfma_f32_16x16x32_bf16 v[110:113], v[148:151], v[164:167], v[110:113]
	v_mfma_f32_16x16x32_bf16 v[110:113], v[152:155], v[168:171], v[110:113]
	v_mfma_f32_16x16x32_bf16 v[106:109], v[156:159], v[164:167], v[106:109]
	v_mfma_f32_16x16x32_bf16 v[106:109], v[160:163], v[168:171], v[106:109]
	v_mfma_f32_16x16x32_bf16 v[102:105], v[148:151], v[172:175], v[102:105]
	v_mfma_f32_16x16x32_bf16 v[102:105], v[152:155], v[176:179], v[102:105]
	v_mfma_f32_16x16x32_bf16 v[98:101], v[156:159], v[172:175], v[98:101]
	v_mfma_f32_16x16x32_bf16 v[98:101], v[160:163], v[176:179], v[98:101]
	v_mfma_f32_16x16x32_bf16 v[86:89], v[148:151], v[180:183], v[86:89]
	v_mfma_f32_16x16x32_bf16 v[86:89], v[152:155], v[184:187], v[86:89]
	v_mfma_f32_16x16x32_bf16 v[82:85], v[156:159], v[180:183], v[82:85]
	v_mfma_f32_16x16x32_bf16 v[82:85], v[160:163], v[184:187], v[82:85]
	v_mfma_f32_16x16x32_bf16 v[70:73], v[148:151], v[202:205], v[70:73]
	v_mfma_f32_16x16x32_bf16 v[70:73], v[152:155], v[206:209], v[70:73]
	v_mfma_f32_16x16x32_bf16 v[66:69], v[156:159], v[202:205], v[66:69]
	v_mfma_f32_16x16x32_bf16 v[66:69], v[160:163], v[206:209], v[66:69]
	s_barrier
	s_setprio 1
	ds_read_b128 v[164:167], v201 offset:16384
	ds_read_b128 v[168:171], v201 offset:17408
	ds_read_b128 v[172:175], v201 offset:18432
	ds_read_b128 v[176:179], v201 offset:19456
	ds_read_b128 v[180:183], v201 offset:20480
	ds_read_b128 v[184:187], v201 offset:21504
	ds_read_b128 v[202:205], v201 offset:22528
	ds_read_b128 v[206:209], v201 offset:23552
	s_mov_b32 m0, s29
	s_nop 0
	global_load_lds_dwordx4 v193, s[40:41]
	s_nop 0
	s_mov_b32 m0, s31
	s_nop 0
	global_load_lds_dwordx4 v195, s[40:41]
	s_add_u32 s34, s40, 0x80000
	s_addc_u32 s35, s41, 0
	s_mov_b32 m0, s54
	s_nop 0
	global_load_lds_dwordx4 v193, s[34:35]
	s_nop 0
	s_mov_b32 m0, s55
	s_nop 0
	global_load_lds_dwordx4 v195, s[34:35]
	s_mov_b32 m0, s10
	s_nop 0
	global_load_lds_dwordx4 v192, s[48:49]
	s_nop 0
	s_mov_b32 m0, s56
	s_nop 0
	global_load_lds_dwordx4 v194, s[48:49]
	s_waitcnt vmcnt(8)
	s_waitcnt lgkmcnt(0)
	s_setprio 0
	s_barrier
; #define PG8_LDA(dst, b, h) do { _Pragma("unroll") for (int m = 0; m < 4; ++m) _Pragma("unroll") for (int k = 0; k < 2; ++k) dst[m][k] = *(const PG8_LAS bf16x8*)(lds + PG8_SA(b, h) + aoff + m * 2048 + k * 1024); } while (0)
; #define PG8_LDB(dst, b, h) do { _Pragma("unroll") for (int n = 0; n < 2; ++n) _Pragma("unroll") for (int k = 0; k < 2; ++k) dst[n][k] = *(const PG8_LAS bf16x8*)(lds + PG8_SB(b, h) + boff + n * 2048 + k * 1024); } while (0)
; #define PG8_MMA(ai, bj, At, Bt) do { __builtin_amdgcn_s_setprio(1); _Pragma("unroll") for (int m = 0; m < 4; ++m) _Pragma("unroll") for (int n = 0; n < 2; ++n) _Pragma("unroll") for (int k = 0; k < 2; ++k) \
;         acc[ai][bj][m][n] = __builtin_amdgcn_mfma_f32_16x16x32_bf16(Bt[n][k], At[m][k], acc[ai][bj][m][n], 0, 0, 0); __builtin_amdgcn_s_setprio(0); } while (0)
; #define PG8_WAIT_V(n) asm volatile("s_waitcnt vmcnt(" #n ")" ::: "memory")
; #define PG8_WAIT_L(n) asm volatile("s_waitcnt lgkmcnt(" #n ")" ::: "memory")
; #define PG8_BAR __builtin_amdgcn_s_barrier()
; #define PG8_SCHED __builtin_amdgcn_sched_barrier(0)
; template <class Epi, class Sched, bool ALIGN_EPI = false, bool SP2 = false>
; __device__ __forceinline__ void gemm_phase(PG8_LAS unsigned char* lds, const Gemm g, const Sched& S, const Epi& E, const int tid) {
;     ...
;             PG8_WAIT_V(8); PG8_WAIT_L(0); PG8_BAR; PG8_MMA(1, 0, At, B0); PG8_MMA(1, 1, At, B1); PG8_BAR; PG8_SCHED;
;             PG8_LDB(B0, 1, 0); PG8_LDB(B1, 1, 1); PG8_SCHED; PG8_LDA(At, 1, 0); PG8_STAGE(PG8_SA(0, 1), a2 + hstepA, voffA);
;             PG8_WAIT_V(8); PG8_WAIT_L(0); PG8_BAR; PG8_MMA(0, 0, At, B0); PG8_MMA(0, 1, At, B1); PG8_BAR; PG8_SCHED;
	v_mfma_f32_16x16x32_bf16 v[62:65], v[132:135], v[164:167], v[62:65]
	v_mfma_f32_16x16x32_bf16 v[62:65], v[136:139], v[168:171], v[62:65]
	v_mfma_f32_16x16x32_bf16 v[58:61], v[140:143], v[164:167], v[58:61]
	v_mfma_f32_16x16x32_bf16 v[58:61], v[144:147], v[168:171], v[58:61]
	v_mfma_f32_16x16x32_bf16 v[46:49], v[132:135], v[172:175], v[46:49]
	v_mfma_f32_16x16x32_bf16 v[46:49], v[136:139], v[176:179], v[46:49]
	v_mfma_f32_16x16x32_bf16 v[42:45], v[140:143], v[172:175], v[42:45]
	v_mfma_f32_16x16x32_bf16 v[42:45], v[144:147], v[176:179], v[42:45]
	v_mfma_f32_16x16x32_bf16 v[30:33], v[132:135], v[180:183], v[30:33]
	v_mfma_f32_16x16x32_bf16 v[30:33], v[136:139], v[184:187], v[30:33]
	v_mfma_f32_16x16x32_bf16 v[26:29], v[140:143], v[180:183], v[26:29]
	v_mfma_f32_16x16x32_bf16 v[26:29], v[144:147], v[184:187], v[26:29]
	v_mfma_f32_16x16x32_bf16 v[14:17], v[132:135], v[202:205], v[14:17]
	v_mfma_f32_16x16x32_bf16 v[14:17], v[136:139], v[206:209], v[14:17]
	v_mfma_f32_16x16x32_bf16 v[10:13], v[140:143], v[202:205], v[10:13]
	v_mfma_f32_16x16x32_bf16 v[10:13], v[144:147], v[206:209], v[10:13]
	v_mfma_f32_16x16x32_bf16 v[54:57], v[148:151], v[164:167], v[54:57]
	v_mfma_f32_16x16x32_bf16 v[54:57], v[152:155], v[168:171], v[54:57]
	v_mfma_f32_16x16x32_bf16 v[50:53], v[156:159], v[164:167], v[50:53]
	v_mfma_f32_16x16x32_bf16 v[50:53], v[160:163], v[168:171], v[50:53]
	v_mfma_f32_16x16x32_bf16 v[38:41], v[148:151], v[172:175], v[38:41]
	v_mfma_f32_16x16x32_bf16 v[38:41], v[152:155], v[176:179], v[38:41]
	v_mfma_f32_16x16x32_bf16 v[34:37], v[156:159], v[172:175], v[34:37]
	v_mfma_f32_16x16x32_bf16 v[34:37], v[160:163], v[176:179], v[34:37]
	v_mfma_f32_16x16x32_bf16 v[22:25], v[148:151], v[180:183], v[22:25]
	v_mfma_f32_16x16x32_bf16 v[22:25], v[152:155], v[184:187], v[22:25]
	v_mfma_f32_16x16x32_bf16 v[18:21], v[156:159], v[180:183], v[18:21]
	v_mfma_f32_16x16x32_bf16 v[18:21], v[160:163], v[184:187], v[18:21]
	v_mfma_f32_16x16x32_bf16 v[6:9], v[148:151], v[202:205], v[6:9]
	v_mfma_f32_16x16x32_bf16 v[6:9], v[152:155], v[206:209], v[6:9]
	v_mfma_f32_16x16x32_bf16 v[2:5], v[156:159], v[202:205], v[2:5]
	v_mfma_f32_16x16x32_bf16 v[2:5], v[160:163], v[206:209], v[2:5]
	s_barrier
	v_add_u32_e32 v144, 0x18000, v200
	v_add_u32_e32 v160, 0x1c000, v200
	s_setprio 1
	ds_read_b128 v[132:135], v144
	ds_read_b128 v[136:139], v144 offset:1024
	ds_read_b128 v[140:143], v144 offset:2048
	ds_read_b128 v[144:147], v144 offset:3072
	ds_read_b128 v[148:151], v160
	ds_read_b128 v[152:155], v160 offset:1024
	ds_read_b128 v[156:159], v160 offset:2048
	ds_read_b128 v[160:163], v160 offset:3072
	ds_read_b128 v[164:167], v201 offset:32768
	ds_read_b128 v[168:171], v201 offset:33792
	ds_read_b128 v[172:175], v201 offset:34816
	ds_read_b128 v[176:179], v201 offset:35840
	ds_read_b128 v[180:183], v201 offset:36864
	ds_read_b128 v[184:187], v201 offset:37888
	ds_read_b128 v[202:205], v201 offset:38912
	ds_read_b128 v[206:209], v201 offset:39936
	s_add_u32 s34, s48, 0x80000
	s_addc_u32 s35, s49, 0
	s_mov_b32 m0, s57
	s_nop 0
	global_load_lds_dwordx4 v192, s[34:35]
	s_nop 0
	s_mov_b32 m0, s64
	s_nop 0
	global_load_lds_dwordx4 v194, s[34:35]
	s_waitcnt vmcnt(8)
	s_waitcnt lgkmcnt(0)
	s_setprio 0
	s_barrier
	v_mfma_f32_16x16x32_bf16 v[126:129], v[132:135], v[164:167], v[126:129]
	v_mfma_f32_16x16x32_bf16 v[126:129], v[136:139], v[168:171], v[126:129]
	v_mfma_f32_16x16x32_bf16 v[122:125], v[140:143], v[164:167], v[122:125]
	v_mfma_f32_16x16x32_bf16 v[122:125], v[144:147], v[168:171], v[122:125]
	v_mfma_f32_16x16x32_bf16 v[118:121], v[132:135], v[172:175], v[118:121]
	v_mfma_f32_16x16x32_bf16 v[118:121], v[136:139], v[176:179], v[118:121]
	v_mfma_f32_16x16x32_bf16 v[114:117], v[140:143], v[172:175], v[114:117]
	v_mfma_f32_16x16x32_bf16 v[114:117], v[144:147], v[176:179], v[114:117]
	v_mfma_f32_16x16x32_bf16 v[94:97], v[132:135], v[180:183], v[94:97]
	v_mfma_f32_16x16x32_bf16 v[94:97], v[136:139], v[184:187], v[94:97]
	v_mfma_f32_16x16x32_bf16 v[90:93], v[140:143], v[180:183], v[90:93]
	v_mfma_f32_16x16x32_bf16 v[90:93], v[144:147], v[184:187], v[90:93]
	v_mfma_f32_16x16x32_bf16 v[78:81], v[132:135], v[202:205], v[78:81]
	v_mfma_f32_16x16x32_bf16 v[78:81], v[136:139], v[206:209], v[78:81]
	v_mfma_f32_16x16x32_bf16 v[74:77], v[140:143], v[202:205], v[74:77]
	v_mfma_f32_16x16x32_bf16 v[74:77], v[144:147], v[206:209], v[74:77]
	v_mfma_f32_16x16x32_bf16 v[110:113], v[148:151], v[164:167], v[110:113]
	v_mfma_f32_16x16x32_bf16 v[110:113], v[152:155], v[168:171], v[110:113]
	v_mfma_f32_16x16x32_bf16 v[106:109], v[156:159], v[164:167], v[106:109]
	v_mfma_f32_16x16x32_bf16 v[106:109], v[160:163], v[168:171], v[106:109]
	v_mfma_f32_16x16x32_bf16 v[102:105], v[148:151], v[172:175], v[102:105]
	v_mfma_f32_16x16x32_bf16 v[102:105], v[152:155], v[176:179], v[102:105]
	v_mfma_f32_16x16x32_bf16 v[98:101], v[156:159], v[172:175], v[98:101]
	v_mfma_f32_16x16x32_bf16 v[98:101], v[160:163], v[176:179], v[98:101]
	v_mfma_f32_16x16x32_bf16 v[86:89], v[148:151], v[180:183], v[86:89]
	v_mfma_f32_16x16x32_bf16 v[86:89], v[152:155], v[184:187], v[86:89]
	v_mfma_f32_16x16x32_bf16 v[82:85], v[156:159], v[180:183], v[82:85]
	v_mfma_f32_16x16x32_bf16 v[82:85], v[160:163], v[184:187], v[82:85]
	v_mfma_f32_16x16x32_bf16 v[70:73], v[148:151], v[202:205], v[70:73]
	v_mfma_f32_16x16x32_bf16 v[70:73], v[152:155], v[206:209], v[70:73]
	v_mfma_f32_16x16x32_bf16 v[66:69], v[156:159], v[202:205], v[66:69]
	v_mfma_f32_16x16x32_bf16 v[66:69], v[160:163], v[206:209], v[66:69]
	s_barrier
; #define PG8_LDA(dst, b, h) do { _Pragma("unroll") for (int m = 0; m < 4; ++m) _Pragma("unroll") for (int k = 0; k < 2; ++k) dst[m][k] = *(const PG8_LAS bf16x8*)(lds + PG8_SA(b, h) + aoff + m * 2048 + k * 1024); } while (0)
; #define PG8_MMA(ai, bj, At, Bt) do { __builtin_amdgcn_s_setprio(1); _Pragma("unroll") for (int m = 0; m < 4; ++m) _Pragma("unroll") for (int n = 0; n < 2; ++n) _Pragma("unroll") for (int k = 0; k < 2; ++k) \
;         acc[ai][bj][m][n] = __builtin_amdgcn_mfma_f32_16x16x32_bf16(Bt[n][k], At[m][k], acc[ai][bj][m][n], 0, 0, 0); __builtin_amdgcn_s_setprio(0); } while (0)
; #define PG8_WAIT_V(n) asm volatile("s_waitcnt vmcnt(" #n ")" ::: "memory")
; #define PG8_WAIT_L(n) asm volatile("s_waitcnt lgkmcnt(" #n ")" ::: "memory")
; #define PG8_BAR __builtin_amdgcn_s_barrier()
; #define PG8_SCHED __builtin_amdgcn_sched_barrier(0)
; template <class Epi, class Sched, bool ALIGN_EPI = false, bool SP2 = false>
; __device__ __forceinline__ void gemm_phase(PG8_LAS unsigned char* lds, const Gemm g, const Sched& S, const Epi& E, const int tid) {
;     ...
;         for (int t = 0; t < nt; t += 2) {
;     ...
;             PG8_LDA(At, 1, 1); PG8_STAGE(PG8_SB(1, 0), b3, voffB); PG8_STAGE(PG8_SB(1, 1), b3 + hstepB, voffB); PG8_STAGE(PG8_SA(1, 0), a3, voffA);
;             PG8_WAIT_V(8); PG8_WAIT_L(0); PG8_BAR; PG8_MMA(1, 0, At, B0); PG8_MMA(1, 1, At, B1); PG8_BAR; PG8_SCHED;
	s_setprio 1
	ds_read_b128 v[164:167], v201 offset:49152
	ds_read_b128 v[168:171], v201 offset:50176
	ds_read_b128 v[172:175], v201 offset:51200
	ds_read_b128 v[176:179], v201 offset:52224
	ds_read_b128 v[180:183], v201 offset:53248
	ds_read_b128 v[184:187], v201 offset:54272
	ds_read_b128 v[202:205], v201 offset:55296
	ds_read_b128 v[206:209], v201 offset:56320
	s_mov_b32 m0, s87
	s_nop 0
	global_load_lds_dwordx4 v193, s[46:47]
	s_nop 0
	s_mov_b32 m0, s89
	s_nop 0
	global_load_lds_dwordx4 v195, s[46:47]
	s_add_u32 s34, s40, 0x80080
	s_addc_u32 s35, s41, 0
	s_mov_b32 m0, s83
	s_nop 0
	global_load_lds_dwordx4 v193, s[34:35]
	s_nop 0
	s_mov_b32 m0, s95
	s_nop 0
	global_load_lds_dwordx4 v195, s[34:35]
	s_mov_b32 m0, s90
	s_nop 0
	global_load_lds_dwordx4 v192, s[44:45]
	s_nop 0
	s_mov_b32 m0, s91
	s_nop 0
	global_load_lds_dwordx4 v194, s[44:45]
	s_waitcnt vmcnt(8)
	s_waitcnt lgkmcnt(0)
	s_setprio 0
	s_barrier
	v_mfma_f32_16x16x32_bf16 v[62:65], v[132:135], v[164:167], v[62:65]
	v_mfma_f32_16x16x32_bf16 v[62:65], v[136:139], v[168:171], v[62:65]
	v_mfma_f32_16x16x32_bf16 v[58:61], v[140:143], v[164:167], v[58:61]
	v_mfma_f32_16x16x32_bf16 v[58:61], v[144:147], v[168:171], v[58:61]
	v_mfma_f32_16x16x32_bf16 v[46:49], v[132:135], v[172:175], v[46:49]
	v_mfma_f32_16x16x32_bf16 v[46:49], v[136:139], v[176:179], v[46:49]
	v_mfma_f32_16x16x32_bf16 v[42:45], v[140:143], v[172:175], v[42:45]
	v_mfma_f32_16x16x32_bf16 v[42:45], v[144:147], v[176:179], v[42:45]
	v_mfma_f32_16x16x32_bf16 v[30:33], v[132:135], v[180:183], v[30:33]
	v_mfma_f32_16x16x32_bf16 v[30:33], v[136:139], v[184:187], v[30:33]
	v_mfma_f32_16x16x32_bf16 v[26:29], v[140:143], v[180:183], v[26:29]
	v_mfma_f32_16x16x32_bf16 v[26:29], v[144:147], v[184:187], v[26:29]
	v_mfma_f32_16x16x32_bf16 v[14:17], v[132:135], v[202:205], v[14:17]
	v_mfma_f32_16x16x32_bf16 v[14:17], v[136:139], v[206:209], v[14:17]
	v_mfma_f32_16x16x32_bf16 v[10:13], v[140:143], v[202:205], v[10:13]
	v_mfma_f32_16x16x32_bf16 v[10:13], v[144:147], v[206:209], v[10:13]
	v_mfma_f32_16x16x32_bf16 v[54:57], v[148:151], v[164:167], v[54:57]
	v_mfma_f32_16x16x32_bf16 v[54:57], v[152:155], v[168:171], v[54:57]
	v_mfma_f32_16x16x32_bf16 v[50:53], v[156:159], v[164:167], v[50:53]
	v_mfma_f32_16x16x32_bf16 v[50:53], v[160:163], v[168:171], v[50:53]
	v_mfma_f32_16x16x32_bf16 v[38:41], v[148:151], v[172:175], v[38:41]
	v_mfma_f32_16x16x32_bf16 v[38:41], v[152:155], v[176:179], v[38:41]
	v_mfma_f32_16x16x32_bf16 v[34:37], v[156:159], v[172:175], v[34:37]
	v_mfma_f32_16x16x32_bf16 v[34:37], v[160:163], v[176:179], v[34:37]
	v_mfma_f32_16x16x32_bf16 v[22:25], v[148:151], v[180:183], v[22:25]
	v_mfma_f32_16x16x32_bf16 v[22:25], v[152:155], v[184:187], v[22:25]
	v_mfma_f32_16x16x32_bf16 v[18:21], v[156:159], v[180:183], v[18:21]
	v_mfma_f32_16x16x32_bf16 v[18:21], v[160:163], v[184:187], v[18:21]
	v_mfma_f32_16x16x32_bf16 v[6:9], v[148:151], v[202:205], v[6:9]
	v_mfma_f32_16x16x32_bf16 v[6:9], v[152:155], v[206:209], v[6:9]
	v_mfma_f32_16x16x32_bf16 v[2:5], v[156:159], v[202:205], v[2:5]
	v_mfma_f32_16x16x32_bf16 v[2:5], v[160:163], v[206:209], v[2:5]
	s_barrier
	s_add_i32 s11, s11, 2
	s_add_u32 s59, s59, 0x100
	s_addc_u32 s67, s67, 0
	s_cmp_gt_u32 s11, 29
	s_mov_b64 s[34:35], s[42:43]
	s_cbranch_scc1 .LBB0_902

; #define PG8_LDA(dst, b, h) do { _Pragma("unroll") for (int m = 0; m < 4; ++m) _Pragma("unroll") for (int k = 0; k < 2; ++k) dst[m][k] = *(const PG8_LAS bf16x8*)(lds + PG8_SA(b, h) + aoff + m * 2048 + k * 1024); } while (0)
; #define PG8_LDB(dst, b, h) do { _Pragma("unroll") for (int n = 0; n < 2; ++n) _Pragma("unroll") for (int k = 0; k < 2; ++k) dst[n][k] = *(const PG8_LAS bf16x8*)(lds + PG8_SB(b, h) + boff + n * 2048 + k * 1024); } while (0)
; #define PG8_MMA(ai, bj, At, Bt) do { __builtin_amdgcn_s_setprio(1); _Pragma("unroll") for (int m = 0; m < 4; ++m) _Pragma("unroll") for (int n = 0; n < 2; ++n) _Pragma("unroll") for (int k = 0; k < 2; ++k) \
;         acc[ai][bj][m][n] = __builtin_amdgcn_mfma_f32_16x16x32_bf16(Bt[n][k], At[m][k], acc[ai][bj][m][n], 0, 0, 0); __builtin_amdgcn_s_setprio(0); } while (0)
; #define PG8_WAIT_V(n) asm volatile("s_waitcnt vmcnt(" #n ")" ::: "memory")
; #define PG8_WAIT_L(n) asm volatile("s_waitcnt lgkmcnt(" #n ")" ::: "memory")
; #define PG8_BAR __builtin_amdgcn_s_barrier()
; #define PG8_SCHED __builtin_amdgcn_sched_barrier(0)
; template <class Epi, class Sched, bool ALIGN_EPI = false, bool SP2 = false>
; __device__ __forceinline__ void gemm_phase(PG8_LAS unsigned char* lds, const Gemm g, const Sched& S, const Epi& E, const int tid) {
;     ...
;             const char* a2 = last ? nA : cA + (size_t)(t + 2) * kstepA; const char* b2 = last ? nB : cB + (size_t)(t + 2) * kstepB;
;             const char* a3 = a2 + kstepA; const char* b3 = b2 + kstepB;
;             if (last && has_next) S.a_ready(nxt);
;             if constexpr (SP2) {
;             PG8_LDB(B0, 0, 0); PG8_LDB(B1, 0, 1); PG8_SCHED; PG8_LDA(At, 0, 0); PG8_STAGE(PG8_SA(1, 1), a1 + hstepA, voffA);
;             PG8_WAIT_V(8); PG8_WAIT_L(0); PG8_BAR; PG8_MMA(0, 0, At, B0); PG8_MMA(0, 1, At, B1); PG8_BAR; PG8_SCHED;
;             PG8_LDA(At, 0, 1); PG8_STAGE(PG8_SB(0, 0), b2, voffB); PG8_STAGE(PG8_SB(0, 1), b2 + hstepB, voffB); PG8_STAGE(PG8_SA(0, 0), a2, voffA);
;             PG8_WAIT_V(8); PG8_WAIT_L(0); PG8_BAR; PG8_MMA(1, 0, At, B0); PG8_MMA(1, 1, At, B1); PG8_BAR; PG8_SCHED;
.LBB0_986:
	v_add_u32_e32 v142, 0x10000, v181
	v_add_u32_e32 v158, 0x14000, v181
	s_setprio 1
	ds_read_b128 v[130:133], v142
	ds_read_b128 v[134:137], v142 offset:1024
	ds_read_b128 v[138:141], v142 offset:2048
	ds_read_b128 v[142:145], v142 offset:3072
	ds_read_b128 v[146:149], v158
	ds_read_b128 v[150:153], v158 offset:1024
	ds_read_b128 v[154:157], v158 offset:2048
	ds_read_b128 v[158:161], v158 offset:3072
	s_cmp_eq_u32 s83, 28
	s_cselect_b32 s38, s21, s67
	s_cselect_b32 s39, s11, s78
	s_cselect_b32 s34, s27, s58
	s_cselect_b32 s35, s19, s59
	s_add_u32 s30, s38, 0x80
	s_addc_u32 s31, s39, 0
	ds_read_b128 v[162:165], v182
	ds_read_b128 v[166:169], v182 offset:1024
	ds_read_b128 v[170:173], v182 offset:2048
	ds_read_b128 v[184:187], v182 offset:3072
	ds_read_b128 v[188:191], v182 offset:4096
	ds_read_b128 v[192:195], v182 offset:5120
	ds_read_b128 v[196:199], v182 offset:6144
	ds_read_b128 v[200:203], v182 offset:7168
	s_mov_b32 m0, s61
	s_nop 0
	global_load_lds_dwordx4 v0, s[28:29]
	s_nop 0
	s_mov_b32 m0, s65
	s_nop 0
	global_load_lds_dwordx4 v177, s[28:29]
	s_waitcnt vmcnt(8)
	s_waitcnt lgkmcnt(0)
	s_setprio 0
	s_barrier
	v_mfma_f32_16x16x32_bf16 v[126:129], v[130:133], v[162:165], v[126:129]
	v_mfma_f32_16x16x32_bf16 v[126:129], v[134:137], v[166:169], v[126:129]
	v_mfma_f32_16x16x32_bf16 v[122:125], v[138:141], v[162:165], v[122:125]
	v_mfma_f32_16x16x32_bf16 v[122:125], v[142:145], v[166:169], v[122:125]
	v_mfma_f32_16x16x32_bf16 v[110:113], v[130:133], v[170:173], v[110:113]
	v_mfma_f32_16x16x32_bf16 v[110:113], v[134:137], v[184:187], v[110:113]
	v_mfma_f32_16x16x32_bf16 v[106:109], v[138:141], v[170:173], v[106:109]
	v_mfma_f32_16x16x32_bf16 v[106:109], v[142:145], v[184:187], v[106:109]
	v_mfma_f32_16x16x32_bf16 v[94:97], v[130:133], v[188:191], v[94:97]
	v_mfma_f32_16x16x32_bf16 v[94:97], v[134:137], v[192:195], v[94:97]
	v_mfma_f32_16x16x32_bf16 v[90:93], v[138:141], v[188:191], v[90:93]
	v_mfma_f32_16x16x32_bf16 v[90:93], v[142:145], v[192:195], v[90:93]
	v_mfma_f32_16x16x32_bf16 v[78:81], v[130:133], v[196:199], v[78:81]
	v_mfma_f32_16x16x32_bf16 v[78:81], v[134:137], v[200:203], v[78:81]
	v_mfma_f32_16x16x32_bf16 v[74:77], v[138:141], v[196:199], v[74:77]
	v_mfma_f32_16x16x32_bf16 v[74:77], v[142:145], v[200:203], v[74:77]
	v_mfma_f32_16x16x32_bf16 v[118:121], v[146:149], v[162:165], v[118:121]
	v_mfma_f32_16x16x32_bf16 v[118:121], v[150:153], v[166:169], v[118:121]
	v_mfma_f32_16x16x32_bf16 v[114:117], v[154:157], v[162:165], v[114:117]
	v_mfma_f32_16x16x32_bf16 v[114:117], v[158:161], v[166:169], v[114:117]
	v_mfma_f32_16x16x32_bf16 v[102:105], v[146:149], v[170:173], v[102:105]
	v_mfma_f32_16x16x32_bf16 v[102:105], v[150:153], v[184:187], v[102:105]
	v_mfma_f32_16x16x32_bf16 v[98:101], v[154:157], v[170:173], v[98:101]
	v_mfma_f32_16x16x32_bf16 v[98:101], v[158:161], v[184:187], v[98:101]
	v_mfma_f32_16x16x32_bf16 v[86:89], v[146:149], v[188:191], v[86:89]
	v_mfma_f32_16x16x32_bf16 v[86:89], v[150:153], v[192:195], v[86:89]
	v_mfma_f32_16x16x32_bf16 v[82:85], v[154:157], v[188:191], v[82:85]
	v_mfma_f32_16x16x32_bf16 v[82:85], v[158:161], v[192:195], v[82:85]
	v_mfma_f32_16x16x32_bf16 v[70:73], v[146:149], v[196:199], v[70:73]
	v_mfma_f32_16x16x32_bf16 v[70:73], v[150:153], v[200:203], v[70:73]
	v_mfma_f32_16x16x32_bf16 v[66:69], v[154:157], v[196:199], v[66:69]
	v_mfma_f32_16x16x32_bf16 v[66:69], v[158:161], v[200:203], v[66:69]
	s_barrier
	s_setprio 1
	ds_read_b128 v[162:165], v182 offset:16384
	ds_read_b128 v[166:169], v182 offset:17408
	ds_read_b128 v[170:173], v182 offset:18432
	ds_read_b128 v[184:187], v182 offset:19456
	ds_read_b128 v[188:191], v182 offset:20480
	ds_read_b128 v[192:195], v182 offset:21504
	ds_read_b128 v[196:199], v182 offset:22528
	ds_read_b128 v[200:203], v182 offset:23552
	s_mov_b32 m0, s7
	s_nop 0
	global_load_lds_dwordx4 v176, s[34:35]
	s_add_u32 s90, s34, 0x80000
	s_mov_b32 m0, s43
	s_nop 0
	global_load_lds_dwordx4 v178, s[34:35]
	s_addc_u32 s91, s35, 0
	s_mov_b32 m0, s44
	s_nop 0
	global_load_lds_dwordx4 v176, s[90:91]
	s_nop 0
	s_mov_b32 m0, s45
	s_nop 0
	global_load_lds_dwordx4 v178, s[90:91]
	s_nop 0
	s_mov_b32 m0, s10
	s_nop 0
	global_load_lds_dwordx4 v0, s[38:39]
	s_nop 0
	s_mov_b32 m0, s46
	s_nop 0
	global_load_lds_dwordx4 v177, s[38:39]
	s_waitcnt vmcnt(8)
	s_waitcnt lgkmcnt(0)
	s_setprio 0
	s_barrier
	v_mfma_f32_16x16x32_bf16 v[62:65], v[130:133], v[162:165], v[62:65]
	v_mfma_f32_16x16x32_bf16 v[62:65], v[134:137], v[166:169], v[62:65]
	v_mfma_f32_16x16x32_bf16 v[58:61], v[138:141], v[162:165], v[58:61]
	v_mfma_f32_16x16x32_bf16 v[58:61], v[142:145], v[166:169], v[58:61]
	v_mfma_f32_16x16x32_bf16 v[46:49], v[130:133], v[170:173], v[46:49]
	v_mfma_f32_16x16x32_bf16 v[46:49], v[134:137], v[184:187], v[46:49]
	v_mfma_f32_16x16x32_bf16 v[42:45], v[138:141], v[170:173], v[42:45]
	v_mfma_f32_16x16x32_bf16 v[42:45], v[142:145], v[184:187], v[42:45]
	v_mfma_f32_16x16x32_bf16 v[30:33], v[130:133], v[188:191], v[30:33]
	v_mfma_f32_16x16x32_bf16 v[30:33], v[134:137], v[192:195], v[30:33]
	v_mfma_f32_16x16x32_bf16 v[26:29], v[138:141], v[188:191], v[26:29]
	v_mfma_f32_16x16x32_bf16 v[26:29], v[142:145], v[192:195], v[26:29]
	v_mfma_f32_16x16x32_bf16 v[14:17], v[130:133], v[196:199], v[14:17]
	v_mfma_f32_16x16x32_bf16 v[14:17], v[134:137], v[200:203], v[14:17]
	v_mfma_f32_16x16x32_bf16 v[10:13], v[138:141], v[196:199], v[10:13]
	v_mfma_f32_16x16x32_bf16 v[10:13], v[142:145], v[200:203], v[10:13]
	v_mfma_f32_16x16x32_bf16 v[54:57], v[146:149], v[162:165], v[54:57]
	v_mfma_f32_16x16x32_bf16 v[54:57], v[150:153], v[166:169], v[54:57]
	v_mfma_f32_16x16x32_bf16 v[50:53], v[154:157], v[162:165], v[50:53]
	v_mfma_f32_16x16x32_bf16 v[50:53], v[158:161], v[166:169], v[50:53]
	v_mfma_f32_16x16x32_bf16 v[38:41], v[146:149], v[170:173], v[38:41]
	v_mfma_f32_16x16x32_bf16 v[38:41], v[150:153], v[184:187], v[38:41]
	v_mfma_f32_16x16x32_bf16 v[34:37], v[154:157], v[170:173], v[34:37]
	v_mfma_f32_16x16x32_bf16 v[34:37], v[158:161], v[184:187], v[34:37]
	v_mfma_f32_16x16x32_bf16 v[22:25], v[146:149], v[188:191], v[22:25]
	v_mfma_f32_16x16x32_bf16 v[22:25], v[150:153], v[192:195], v[22:25]
	v_mfma_f32_16x16x32_bf16 v[18:21], v[154:157], v[188:191], v[18:21]
	v_mfma_f32_16x16x32_bf16 v[18:21], v[158:161], v[192:195], v[18:21]
	v_mfma_f32_16x16x32_bf16 v[6:9], v[146:149], v[196:199], v[6:9]
	v_mfma_f32_16x16x32_bf16 v[6:9], v[150:153], v[200:203], v[6:9]
	v_mfma_f32_16x16x32_bf16 v[2:5], v[154:157], v[196:199], v[2:5]
	v_mfma_f32_16x16x32_bf16 v[2:5], v[158:161], v[200:203], v[2:5]
	s_barrier
; #define PG8_LDA(dst, b, h) do { _Pragma("unroll") for (int m = 0; m < 4; ++m) _Pragma("unroll") for (int k = 0; k < 2; ++k) dst[m][k] = *(const PG8_LAS bf16x8*)(lds + PG8_SA(b, h) + aoff + m * 2048 + k * 1024); } while (0)
; #define PG8_LDB(dst, b, h) do { _Pragma("unroll") for (int n = 0; n < 2; ++n) _Pragma("unroll") for (int k = 0; k < 2; ++k) dst[n][k] = *(const PG8_LAS bf16x8*)(lds + PG8_SB(b, h) + boff + n * 2048 + k * 1024); } while (0)
; #define PG8_MMA(ai, bj, At, Bt) do { __builtin_amdgcn_s_setprio(1); _Pragma("unroll") for (int m = 0; m < 4; ++m) _Pragma("unroll") for (int n = 0; n < 2; ++n) _Pragma("unroll") for (int k = 0; k < 2; ++k) \
;         acc[ai][bj][m][n] = __builtin_amdgcn_mfma_f32_16x16x32_bf16(Bt[n][k], At[m][k], acc[ai][bj][m][n], 0, 0, 0); __builtin_amdgcn_s_setprio(0); } while (0)
; #define PG8_WAIT_V(n) asm volatile("s_waitcnt vmcnt(" #n ")" ::: "memory")
; #define PG8_WAIT_L(n) asm volatile("s_waitcnt lgkmcnt(" #n ")" ::: "memory")
; #define PG8_BAR __builtin_amdgcn_s_barrier()
; #define PG8_SCHED __builtin_amdgcn_sched_barrier(0)
; template <class Epi, class Sched, bool ALIGN_EPI = false, bool SP2 = false>
; __device__ __forceinline__ void gemm_phase(PG8_LAS unsigned char* lds, const Gemm g, const Sched& S, const Epi& E, const int tid) {
;     ...
;         for (int t = 0; t < nt; t += 2) {
;     ...
;             PG8_LDB(B0, 1, 0); PG8_LDB(B1, 1, 1); PG8_SCHED; PG8_LDA(At, 1, 0); PG8_STAGE(PG8_SA(0, 1), a2 + hstepA, voffA);
;             PG8_WAIT_V(8); PG8_WAIT_L(0); PG8_BAR; PG8_MMA(0, 0, At, B0); PG8_MMA(0, 1, At, B1); PG8_BAR; PG8_SCHED;
;             PG8_LDA(At, 1, 1); PG8_STAGE(PG8_SB(1, 0), b3, voffB); PG8_STAGE(PG8_SB(1, 1), b3 + hstepB, voffB); PG8_STAGE(PG8_SA(1, 0), a3, voffA);
;             PG8_WAIT_V(8); PG8_WAIT_L(0); PG8_BAR; PG8_MMA(1, 0, At, B0); PG8_MMA(1, 1, At, B1); PG8_BAR; PG8_SCHED;
	v_add_u32_e32 v142, 0x18000, v181
	v_add_u32_e32 v158, 0x1c000, v181
	s_setprio 1
	ds_read_b128 v[130:133], v142
	ds_read_b128 v[134:137], v142 offset:1024
	ds_read_b128 v[138:141], v142 offset:2048
	ds_read_b128 v[142:145], v142 offset:3072
	ds_read_b128 v[146:149], v158
	ds_read_b128 v[150:153], v158 offset:1024
	ds_read_b128 v[154:157], v158 offset:2048
	ds_read_b128 v[158:161], v158 offset:3072
	ds_read_b128 v[162:165], v182 offset:32768
	ds_read_b128 v[166:169], v182 offset:33792
	ds_read_b128 v[170:173], v182 offset:34816
	ds_read_b128 v[184:187], v182 offset:35840
	ds_read_b128 v[188:191], v182 offset:36864
	ds_read_b128 v[192:195], v182 offset:37888
	ds_read_b128 v[196:199], v182 offset:38912
	ds_read_b128 v[200:203], v182 offset:39936
	s_add_u32 s38, s38, 0x80000
	s_addc_u32 s39, s39, 0
	s_mov_b32 m0, s47
	s_nop 0
	global_load_lds_dwordx4 v0, s[38:39]
	s_nop 0
	s_mov_b32 m0, s48
	s_nop 0
	global_load_lds_dwordx4 v177, s[38:39]
	s_waitcnt vmcnt(8)
	s_waitcnt lgkmcnt(0)
	s_setprio 0
	s_barrier
	v_mfma_f32_16x16x32_bf16 v[126:129], v[130:133], v[162:165], v[126:129]
	v_mfma_f32_16x16x32_bf16 v[126:129], v[134:137], v[166:169], v[126:129]
	v_mfma_f32_16x16x32_bf16 v[122:125], v[138:141], v[162:165], v[122:125]
	v_mfma_f32_16x16x32_bf16 v[122:125], v[142:145], v[166:169], v[122:125]
	v_mfma_f32_16x16x32_bf16 v[110:113], v[130:133], v[170:173], v[110:113]
	v_mfma_f32_16x16x32_bf16 v[110:113], v[134:137], v[184:187], v[110:113]
	v_mfma_f32_16x16x32_bf16 v[106:109], v[138:141], v[170:173], v[106:109]
	v_mfma_f32_16x16x32_bf16 v[106:109], v[142:145], v[184:187], v[106:109]
	v_mfma_f32_16x16x32_bf16 v[94:97], v[130:133], v[188:191], v[94:97]
	v_mfma_f32_16x16x32_bf16 v[94:97], v[134:137], v[192:195], v[94:97]
	v_mfma_f32_16x16x32_bf16 v[90:93], v[138:141], v[188:191], v[90:93]
	v_mfma_f32_16x16x32_bf16 v[90:93], v[142:145], v[192:195], v[90:93]
	v_mfma_f32_16x16x32_bf16 v[78:81], v[130:133], v[196:199], v[78:81]
	v_mfma_f32_16x16x32_bf16 v[78:81], v[134:137], v[200:203], v[78:81]
	v_mfma_f32_16x16x32_bf16 v[74:77], v[138:141], v[196:199], v[74:77]
	v_mfma_f32_16x16x32_bf16 v[74:77], v[142:145], v[200:203], v[74:77]
	v_mfma_f32_16x16x32_bf16 v[118:121], v[146:149], v[162:165], v[118:121]
	v_mfma_f32_16x16x32_bf16 v[118:121], v[150:153], v[166:169], v[118:121]
	v_mfma_f32_16x16x32_bf16 v[114:117], v[154:157], v[162:165], v[114:117]
	v_mfma_f32_16x16x32_bf16 v[114:117], v[158:161], v[166:169], v[114:117]
	v_mfma_f32_16x16x32_bf16 v[102:105], v[146:149], v[170:173], v[102:105]
	v_mfma_f32_16x16x32_bf16 v[102:105], v[150:153], v[184:187], v[102:105]
	v_mfma_f32_16x16x32_bf16 v[98:101], v[154:157], v[170:173], v[98:101]
	v_mfma_f32_16x16x32_bf16 v[98:101], v[158:161], v[184:187], v[98:101]
	v_mfma_f32_16x16x32_bf16 v[86:89], v[146:149], v[188:191], v[86:89]
	v_mfma_f32_16x16x32_bf16 v[86:89], v[150:153], v[192:195], v[86:89]
	v_mfma_f32_16x16x32_bf16 v[82:85], v[154:157], v[188:191], v[82:85]
	v_mfma_f32_16x16x32_bf16 v[82:85], v[158:161], v[192:195], v[82:85]
	v_mfma_f32_16x16x32_bf16 v[70:73], v[146:149], v[196:199], v[70:73]
	v_mfma_f32_16x16x32_bf16 v[70:73], v[150:153], v[200:203], v[70:73]
	v_mfma_f32_16x16x32_bf16 v[66:69], v[154:157], v[196:199], v[66:69]
	v_mfma_f32_16x16x32_bf16 v[66:69], v[158:161], v[200:203], v[66:69]
	s_barrier
	s_setprio 1
	ds_read_b128 v[162:165], v182 offset:49152
	ds_read_b128 v[166:169], v182 offset:50176
	ds_read_b128 v[170:173], v182 offset:51200
	ds_read_b128 v[184:187], v182 offset:52224
	ds_read_b128 v[188:191], v182 offset:53248
	ds_read_b128 v[192:195], v182 offset:54272
	ds_read_b128 v[196:199], v182 offset:55296
	ds_read_b128 v[200:203], v182 offset:56320
	s_add_u32 s38, s34, 0x80
	s_addc_u32 s39, s35, 0
	s_mov_b32 m0, s50
	s_nop 0
	global_load_lds_dwordx4 v176, s[38:39]
	s_add_u32 s34, s34, 0x80080
	s_mov_b32 m0, s51
	s_nop 0
	global_load_lds_dwordx4 v178, s[38:39]
	s_addc_u32 s35, s35, 0
	s_mov_b32 m0, s56
	s_nop 0
	global_load_lds_dwordx4 v176, s[34:35]
	s_nop 0
	s_mov_b32 m0, s57
	s_nop 0
	global_load_lds_dwordx4 v178, s[34:35]
	s_mov_b32 m0, s54
	s_nop 0
	global_load_lds_dwordx4 v0, s[30:31]
	s_nop 0
	s_mov_b32 m0, s55
	s_nop 0
	global_load_lds_dwordx4 v177, s[30:31]
	s_waitcnt vmcnt(8)
	s_waitcnt lgkmcnt(0)
	s_setprio 0
	s_barrier
	v_mfma_f32_16x16x32_bf16 v[62:65], v[130:133], v[162:165], v[62:65]
	v_mfma_f32_16x16x32_bf16 v[62:65], v[134:137], v[166:169], v[62:65]
	v_mfma_f32_16x16x32_bf16 v[58:61], v[138:141], v[162:165], v[58:61]
	v_mfma_f32_16x16x32_bf16 v[58:61], v[142:145], v[166:169], v[58:61]
	v_mfma_f32_16x16x32_bf16 v[46:49], v[130:133], v[170:173], v[46:49]
	v_mfma_f32_16x16x32_bf16 v[46:49], v[134:137], v[184:187], v[46:49]
	v_mfma_f32_16x16x32_bf16 v[42:45], v[138:141], v[170:173], v[42:45]
	v_mfma_f32_16x16x32_bf16 v[42:45], v[142:145], v[184:187], v[42:45]
	v_mfma_f32_16x16x32_bf16 v[30:33], v[130:133], v[188:191], v[30:33]
	v_mfma_f32_16x16x32_bf16 v[30:33], v[134:137], v[192:195], v[30:33]
	v_mfma_f32_16x16x32_bf16 v[26:29], v[138:141], v[188:191], v[26:29]
	v_mfma_f32_16x16x32_bf16 v[26:29], v[142:145], v[192:195], v[26:29]
	v_mfma_f32_16x16x32_bf16 v[14:17], v[130:133], v[196:199], v[14:17]
	v_mfma_f32_16x16x32_bf16 v[14:17], v[134:137], v[200:203], v[14:17]
	v_mfma_f32_16x16x32_bf16 v[10:13], v[138:141], v[196:199], v[10:13]
	v_mfma_f32_16x16x32_bf16 v[10:13], v[142:145], v[200:203], v[10:13]
	v_mfma_f32_16x16x32_bf16 v[54:57], v[146:149], v[162:165], v[54:57]
	v_mfma_f32_16x16x32_bf16 v[54:57], v[150:153], v[166:169], v[54:57]
	v_mfma_f32_16x16x32_bf16 v[50:53], v[154:157], v[162:165], v[50:53]
	v_mfma_f32_16x16x32_bf16 v[50:53], v[158:161], v[166:169], v[50:53]
	v_mfma_f32_16x16x32_bf16 v[38:41], v[146:149], v[170:173], v[38:41]
	v_mfma_f32_16x16x32_bf16 v[38:41], v[150:153], v[184:187], v[38:41]
	v_mfma_f32_16x16x32_bf16 v[34:37], v[154:157], v[170:173], v[34:37]
	v_mfma_f32_16x16x32_bf16 v[34:37], v[158:161], v[184:187], v[34:37]
	v_mfma_f32_16x16x32_bf16 v[22:25], v[146:149], v[188:191], v[22:25]
	v_mfma_f32_16x16x32_bf16 v[22:25], v[150:153], v[192:195], v[22:25]
	v_mfma_f32_16x16x32_bf16 v[18:21], v[154:157], v[188:191], v[18:21]
	v_mfma_f32_16x16x32_bf16 v[18:21], v[158:161], v[192:195], v[18:21]
	v_mfma_f32_16x16x32_bf16 v[6:9], v[146:149], v[196:199], v[6:9]
	v_mfma_f32_16x16x32_bf16 v[6:9], v[150:153], v[200:203], v[6:9]
	v_mfma_f32_16x16x32_bf16 v[2:5], v[154:157], v[196:199], v[2:5]
	v_mfma_f32_16x16x32_bf16 v[2:5], v[158:161], v[200:203], v[2:5]
	s_barrier
	s_add_i32 s83, s83, 2
	s_add_u32 s58, s58, 0x100
	s_addc_u32 s59, s59, 0
	s_add_u32 s67, s67, 0x100
	s_addc_u32 s78, s78, 0
	s_add_u32 s28, s28, 0x100
	s_addc_u32 s29, s29, 0
	s_cmp_gt_u32 s83, 29
	s_cbranch_scc0 .LBB0_986
	s_and_b64 vcc, exec, s[16:17]
	s_cbranch_vccz .LBB0_989
	s_barrier

; #define PG8_LDA(dst, b, h) do { _Pragma("unroll") for (int m = 0; m < 4; ++m) _Pragma("unroll") for (int k = 0; k < 2; ++k) dst[m][k] = *(const PG8_LAS bf16x8*)(lds + PG8_SA(b, h) + aoff + m * 2048 + k * 1024); } while (0)
; #define PG8_LDB(dst, b, h) do { _Pragma("unroll") for (int n = 0; n < 2; ++n) _Pragma("unroll") for (int k = 0; k < 2; ++k) dst[n][k] = *(const PG8_LAS bf16x8*)(lds + PG8_SB(b, h) + boff + n * 2048 + k * 1024); } while (0)
; #define PG8_MMA(ai, bj, At, Bt) do { __builtin_amdgcn_s_setprio(1); _Pragma("unroll") for (int m = 0; m < 4; ++m) _Pragma("unroll") for (int n = 0; n < 2; ++n) _Pragma("unroll") for (int k = 0; k < 2; ++k) \
;         acc[ai][bj][m][n] = __builtin_amdgcn_mfma_f32_16x16x32_bf16(Bt[n][k], At[m][k], acc[ai][bj][m][n], 0, 0, 0); __builtin_amdgcn_s_setprio(0); } while (0)
; #define PG8_WAIT_V(n) asm volatile("s_waitcnt vmcnt(" #n ")" ::: "memory")
; #define PG8_WAIT_L(n) asm volatile("s_waitcnt lgkmcnt(" #n ")" ::: "memory")
; #define PG8_BAR __builtin_amdgcn_s_barrier()
; #define PG8_SCHED __builtin_amdgcn_sched_barrier(0)
; template <class Epi, class Sched, bool ALIGN_EPI = false, bool SP2 = false>
; __device__ __forceinline__ void gemm_phase(PG8_LAS unsigned char* lds, const Gemm g, const Sched& S, const Epi& E, const int tid) {
;     ...
;             const char* a2 = last ? nA : cA + (size_t)(t + 2) * kstepA; const char* b2 = last ? nB : cB + (size_t)(t + 2) * kstepB;
;             const char* a3 = a2 + kstepA; const char* b3 = b2 + kstepB;
;             if (last && has_next) S.a_ready(nxt);
;             if constexpr (SP2) {
;             PG8_LDB(B0, 0, 0); PG8_LDB(B1, 0, 1); PG8_SCHED; PG8_LDA(At, 0, 0); PG8_STAGE(PG8_SA(1, 1), a1 + hstepA, voffA);
;             PG8_WAIT_V(8); PG8_WAIT_L(0); PG8_BAR; PG8_MMA(0, 0, At, B0); PG8_MMA(0, 1, At, B1); PG8_BAR; PG8_SCHED;
;             PG8_LDA(At, 0, 1); PG8_STAGE(PG8_SB(0, 0), b2, voffB); PG8_STAGE(PG8_SB(0, 1), b2 + hstepB, voffB); PG8_STAGE(PG8_SA(0, 0), a2, voffA);
.LBB0_1070:
	s_or_b64 exec, exec, s[34:35]
	v_add_u32_e32 v145, 0x10000, v154
	s_setprio 1
	ds_read_b128 v[156:159], v145
	ds_read_b128 v[160:163], v145 offset:1024
	ds_read_b128 v[164:167], v145 offset:2048
	ds_read_b128 v[168:171], v145 offset:3072
	v_add_u32_e32 v145, 0x14000, v154
	s_add_u32 s34, s26, 0x100
	ds_read_b128 v[172:175], v145
	ds_read_b128 v[176:179], v145 offset:1024
	ds_read_b128 v[180:183], v145 offset:2048
	ds_read_b128 v[184:187], v145 offset:3072
	s_addc_u32 s35, s27, 0
	s_and_b64 s[30:31], s[30:31], exec
	s_cselect_b32 s42, s91, s34
	s_cselect_b32 s43, s19, s35
	s_cselect_b32 s31, s17, s67
	s_cselect_b32 s30, s95, s59
	s_add_u32 s38, s42, 0x80
	s_addc_u32 s39, s43, 0
	s_add_u32 s40, s30, 0x80
	s_addc_u32 s41, s31, 0
	ds_read_b128 v[188:191], v155
	ds_read_b128 v[192:195], v155 offset:1024
	ds_read_b128 v[196:199], v155 offset:2048
	ds_read_b128 v[200:203], v155 offset:3072
	ds_read_b128 v[204:207], v155 offset:4096
	ds_read_b128 v[208:211], v155 offset:5120
	ds_read_b128 v[212:215], v155 offset:6144
	ds_read_b128 v[216:219], v155 offset:7168
	s_add_u32 s26, s26, 0x80080
	s_addc_u32 s27, s27, 0
	s_mov_b32 m0, s69
	s_nop 0
	global_load_lds_dwordx4 v149, s[26:27]
	s_nop 0
	s_mov_b32 m0, s58
	s_nop 0
	global_load_lds_dwordx4 v151, s[26:27]
	s_waitcnt vmcnt(8)
	s_waitcnt lgkmcnt(0)
	s_setprio 0
	s_barrier
	v_mfma_f32_16x16x32_bf16 v[126:129], v[156:159], v[188:191], v[126:129]
	v_mfma_f32_16x16x32_bf16 v[126:129], v[160:163], v[192:195], v[126:129]
	v_mfma_f32_16x16x32_bf16 v[122:125], v[164:167], v[188:191], v[122:125]
	v_mfma_f32_16x16x32_bf16 v[122:125], v[168:171], v[192:195], v[122:125]
	v_mfma_f32_16x16x32_bf16 v[110:113], v[156:159], v[196:199], v[110:113]
	v_mfma_f32_16x16x32_bf16 v[110:113], v[160:163], v[200:203], v[110:113]
	v_mfma_f32_16x16x32_bf16 v[106:109], v[164:167], v[196:199], v[106:109]
	v_mfma_f32_16x16x32_bf16 v[106:109], v[168:171], v[200:203], v[106:109]
	v_mfma_f32_16x16x32_bf16 v[94:97], v[156:159], v[204:207], v[94:97]
	v_mfma_f32_16x16x32_bf16 v[94:97], v[160:163], v[208:211], v[94:97]
	v_mfma_f32_16x16x32_bf16 v[90:93], v[164:167], v[204:207], v[90:93]
	v_mfma_f32_16x16x32_bf16 v[90:93], v[168:171], v[208:211], v[90:93]
	v_mfma_f32_16x16x32_bf16 v[78:81], v[156:159], v[212:215], v[78:81]
	v_mfma_f32_16x16x32_bf16 v[78:81], v[160:163], v[216:219], v[78:81]
	v_mfma_f32_16x16x32_bf16 v[74:77], v[164:167], v[212:215], v[74:77]
	v_mfma_f32_16x16x32_bf16 v[74:77], v[168:171], v[216:219], v[74:77]
	v_mfma_f32_16x16x32_bf16 v[118:121], v[172:175], v[188:191], v[118:121]
	v_mfma_f32_16x16x32_bf16 v[118:121], v[176:179], v[192:195], v[118:121]
	v_mfma_f32_16x16x32_bf16 v[114:117], v[180:183], v[188:191], v[114:117]
	v_mfma_f32_16x16x32_bf16 v[114:117], v[184:187], v[192:195], v[114:117]
	v_mfma_f32_16x16x32_bf16 v[102:105], v[172:175], v[196:199], v[102:105]
	v_mfma_f32_16x16x32_bf16 v[102:105], v[176:179], v[200:203], v[102:105]
	v_mfma_f32_16x16x32_bf16 v[98:101], v[180:183], v[196:199], v[98:101]
	v_mfma_f32_16x16x32_bf16 v[98:101], v[184:187], v[200:203], v[98:101]
	v_mfma_f32_16x16x32_bf16 v[86:89], v[172:175], v[204:207], v[86:89]
	v_mfma_f32_16x16x32_bf16 v[86:89], v[176:179], v[208:211], v[86:89]
	v_mfma_f32_16x16x32_bf16 v[82:85], v[180:183], v[204:207], v[82:85]
	v_mfma_f32_16x16x32_bf16 v[82:85], v[184:187], v[208:211], v[82:85]
	v_mfma_f32_16x16x32_bf16 v[70:73], v[172:175], v[212:215], v[70:73]
	v_mfma_f32_16x16x32_bf16 v[70:73], v[176:179], v[216:219], v[70:73]
	v_mfma_f32_16x16x32_bf16 v[66:69], v[180:183], v[212:215], v[66:69]
	v_mfma_f32_16x16x32_bf16 v[66:69], v[184:187], v[216:219], v[66:69]
	s_barrier
	s_setprio 1
	ds_read_b128 v[188:191], v155 offset:16384
	ds_read_b128 v[192:195], v155 offset:17408
	ds_read_b128 v[196:199], v155 offset:18432
	ds_read_b128 v[200:203], v155 offset:19456
	ds_read_b128 v[204:207], v155 offset:20480
	ds_read_b128 v[208:211], v155 offset:21504
	ds_read_b128 v[212:215], v155 offset:22528
	ds_read_b128 v[216:219], v155 offset:23552
	s_mov_b32 m0, s15
	s_nop 0
	global_load_lds_dwordx4 v150, s[30:31]
	s_nop 0
	s_mov_b32 m0, s25
	s_nop 0
	global_load_lds_dwordx4 v152, s[30:31]
	s_add_u32 s26, s30, 0x80000
	s_addc_u32 s27, s31, 0
	s_mov_b32 m0, s48
	s_nop 0
	global_load_lds_dwordx4 v150, s[26:27]
	s_nop 0
	s_mov_b32 m0, s49
	s_nop 0
	global_load_lds_dwordx4 v152, s[26:27]
	s_mov_b32 m0, s10
	s_nop 0
	global_load_lds_dwordx4 v149, s[42:43]
	s_nop 0
	s_mov_b32 m0, s50
	s_nop 0
	global_load_lds_dwordx4 v151, s[42:43]
	s_waitcnt vmcnt(8)
	s_waitcnt lgkmcnt(0)
	s_setprio 0
	s_barrier
; #define PG8_LDA(dst, b, h) do { _Pragma("unroll") for (int m = 0; m < 4; ++m) _Pragma("unroll") for (int k = 0; k < 2; ++k) dst[m][k] = *(const PG8_LAS bf16x8*)(lds + PG8_SA(b, h) + aoff + m * 2048 + k * 1024); } while (0)
; #define PG8_LDB(dst, b, h) do { _Pragma("unroll") for (int n = 0; n < 2; ++n) _Pragma("unroll") for (int k = 0; k < 2; ++k) dst[n][k] = *(const PG8_LAS bf16x8*)(lds + PG8_SB(b, h) + boff + n * 2048 + k * 1024); } while (0)
; #define PG8_MMA(ai, bj, At, Bt) do { __builtin_amdgcn_s_setprio(1); _Pragma("unroll") for (int m = 0; m < 4; ++m) _Pragma("unroll") for (int n = 0; n < 2; ++n) _Pragma("unroll") for (int k = 0; k < 2; ++k) \
;         acc[ai][bj][m][n] = __builtin_amdgcn_mfma_f32_16x16x32_bf16(Bt[n][k], At[m][k], acc[ai][bj][m][n], 0, 0, 0); __builtin_amdgcn_s_setprio(0); } while (0)
; #define PG8_WAIT_V(n) asm volatile("s_waitcnt vmcnt(" #n ")" ::: "memory")
; #define PG8_WAIT_L(n) asm volatile("s_waitcnt lgkmcnt(" #n ")" ::: "memory")
; #define PG8_BAR __builtin_amdgcn_s_barrier()
; #define PG8_SCHED __builtin_amdgcn_sched_barrier(0)
; template <class Epi, class Sched, bool ALIGN_EPI = false, bool SP2 = false>
; __device__ __forceinline__ void gemm_phase(PG8_LAS unsigned char* lds, const Gemm g, const Sched& S, const Epi& E, const int tid) {
;     ...
;             PG8_WAIT_V(8); PG8_WAIT_L(0); PG8_BAR; PG8_MMA(1, 0, At, B0); PG8_MMA(1, 1, At, B1); PG8_BAR; PG8_SCHED;
;             PG8_LDB(B0, 1, 0); PG8_LDB(B1, 1, 1); PG8_SCHED; PG8_LDA(At, 1, 0); PG8_STAGE(PG8_SA(0, 1), a2 + hstepA, voffA);
;             PG8_WAIT_V(8); PG8_WAIT_L(0); PG8_BAR; PG8_MMA(0, 0, At, B0); PG8_MMA(0, 1, At, B1); PG8_BAR; PG8_SCHED;
	v_mfma_f32_16x16x32_bf16 v[62:65], v[156:159], v[188:191], v[62:65]
	v_mfma_f32_16x16x32_bf16 v[62:65], v[160:163], v[192:195], v[62:65]
	v_mfma_f32_16x16x32_bf16 v[58:61], v[164:167], v[188:191], v[58:61]
	v_mfma_f32_16x16x32_bf16 v[58:61], v[168:171], v[192:195], v[58:61]
	v_mfma_f32_16x16x32_bf16 v[46:49], v[156:159], v[196:199], v[46:49]
	v_mfma_f32_16x16x32_bf16 v[46:49], v[160:163], v[200:203], v[46:49]
	v_mfma_f32_16x16x32_bf16 v[42:45], v[164:167], v[196:199], v[42:45]
	v_mfma_f32_16x16x32_bf16 v[42:45], v[168:171], v[200:203], v[42:45]
	v_mfma_f32_16x16x32_bf16 v[30:33], v[156:159], v[204:207], v[30:33]
	v_mfma_f32_16x16x32_bf16 v[30:33], v[160:163], v[208:211], v[30:33]
	v_mfma_f32_16x16x32_bf16 v[26:29], v[164:167], v[204:207], v[26:29]
	v_mfma_f32_16x16x32_bf16 v[26:29], v[168:171], v[208:211], v[26:29]
	v_mfma_f32_16x16x32_bf16 v[14:17], v[156:159], v[212:215], v[14:17]
	v_mfma_f32_16x16x32_bf16 v[14:17], v[160:163], v[216:219], v[14:17]
	v_mfma_f32_16x16x32_bf16 v[10:13], v[164:167], v[212:215], v[10:13]
	v_mfma_f32_16x16x32_bf16 v[10:13], v[168:171], v[216:219], v[10:13]
	v_mfma_f32_16x16x32_bf16 v[54:57], v[172:175], v[188:191], v[54:57]
	v_mfma_f32_16x16x32_bf16 v[54:57], v[176:179], v[192:195], v[54:57]
	v_mfma_f32_16x16x32_bf16 v[50:53], v[180:183], v[188:191], v[50:53]
	v_mfma_f32_16x16x32_bf16 v[50:53], v[184:187], v[192:195], v[50:53]
	v_mfma_f32_16x16x32_bf16 v[38:41], v[172:175], v[196:199], v[38:41]
	v_mfma_f32_16x16x32_bf16 v[38:41], v[176:179], v[200:203], v[38:41]
	v_mfma_f32_16x16x32_bf16 v[34:37], v[180:183], v[196:199], v[34:37]
	v_mfma_f32_16x16x32_bf16 v[34:37], v[184:187], v[200:203], v[34:37]
	v_mfma_f32_16x16x32_bf16 v[22:25], v[172:175], v[204:207], v[22:25]
	v_mfma_f32_16x16x32_bf16 v[22:25], v[176:179], v[208:211], v[22:25]
	v_mfma_f32_16x16x32_bf16 v[18:21], v[180:183], v[204:207], v[18:21]
	v_mfma_f32_16x16x32_bf16 v[18:21], v[184:187], v[208:211], v[18:21]
	v_mfma_f32_16x16x32_bf16 v[6:9], v[172:175], v[212:215], v[6:9]
	v_mfma_f32_16x16x32_bf16 v[6:9], v[176:179], v[216:219], v[6:9]
	v_mfma_f32_16x16x32_bf16 v[2:5], v[180:183], v[212:215], v[2:5]
	v_mfma_f32_16x16x32_bf16 v[2:5], v[184:187], v[216:219], v[2:5]
	s_barrier
	v_add_u32_e32 v145, 0x18000, v154
	s_setprio 1
	ds_read_b128 v[156:159], v145
	ds_read_b128 v[160:163], v145 offset:1024
	ds_read_b128 v[164:167], v145 offset:2048
	ds_read_b128 v[168:171], v145 offset:3072
	v_add_u32_e32 v145, 0x1c000, v154
	ds_read_b128 v[172:175], v145
	ds_read_b128 v[176:179], v145 offset:1024
	ds_read_b128 v[180:183], v145 offset:2048
	ds_read_b128 v[184:187], v145 offset:3072
	ds_read_b128 v[188:191], v155 offset:32768
	ds_read_b128 v[192:195], v155 offset:33792
	ds_read_b128 v[196:199], v155 offset:34816
	ds_read_b128 v[200:203], v155 offset:35840
	ds_read_b128 v[204:207], v155 offset:36864
	ds_read_b128 v[208:211], v155 offset:37888
	ds_read_b128 v[212:215], v155 offset:38912
	ds_read_b128 v[216:219], v155 offset:39936
	s_add_u32 s26, s42, 0x80000
	s_addc_u32 s27, s43, 0
	s_mov_b32 m0, s51
	s_nop 0
	global_load_lds_dwordx4 v149, s[26:27]
	s_nop 0
	s_mov_b32 m0, s54
	s_nop 0
	global_load_lds_dwordx4 v151, s[26:27]
	s_waitcnt vmcnt(8)
	s_waitcnt lgkmcnt(0)
	s_setprio 0
	s_barrier
	v_mfma_f32_16x16x32_bf16 v[126:129], v[156:159], v[188:191], v[126:129]
	v_mfma_f32_16x16x32_bf16 v[126:129], v[160:163], v[192:195], v[126:129]
	v_mfma_f32_16x16x32_bf16 v[122:125], v[164:167], v[188:191], v[122:125]
	v_mfma_f32_16x16x32_bf16 v[122:125], v[168:171], v[192:195], v[122:125]
	v_mfma_f32_16x16x32_bf16 v[110:113], v[156:159], v[196:199], v[110:113]
	v_mfma_f32_16x16x32_bf16 v[110:113], v[160:163], v[200:203], v[110:113]
	v_mfma_f32_16x16x32_bf16 v[106:109], v[164:167], v[196:199], v[106:109]
	v_mfma_f32_16x16x32_bf16 v[106:109], v[168:171], v[200:203], v[106:109]
	v_mfma_f32_16x16x32_bf16 v[94:97], v[156:159], v[204:207], v[94:97]
	v_mfma_f32_16x16x32_bf16 v[94:97], v[160:163], v[208:211], v[94:97]
	v_mfma_f32_16x16x32_bf16 v[90:93], v[164:167], v[204:207], v[90:93]
	v_mfma_f32_16x16x32_bf16 v[90:93], v[168:171], v[208:211], v[90:93]
	v_mfma_f32_16x16x32_bf16 v[78:81], v[156:159], v[212:215], v[78:81]
	v_mfma_f32_16x16x32_bf16 v[78:81], v[160:163], v[216:219], v[78:81]
	v_mfma_f32_16x16x32_bf16 v[74:77], v[164:167], v[212:215], v[74:77]
	v_mfma_f32_16x16x32_bf16 v[74:77], v[168:171], v[216:219], v[74:77]
	v_mfma_f32_16x16x32_bf16 v[118:121], v[172:175], v[188:191], v[118:121]
	v_mfma_f32_16x16x32_bf16 v[118:121], v[176:179], v[192:195], v[118:121]
	v_mfma_f32_16x16x32_bf16 v[114:117], v[180:183], v[188:191], v[114:117]
	v_mfma_f32_16x16x32_bf16 v[114:117], v[184:187], v[192:195], v[114:117]
	v_mfma_f32_16x16x32_bf16 v[102:105], v[172:175], v[196:199], v[102:105]
	v_mfma_f32_16x16x32_bf16 v[102:105], v[176:179], v[200:203], v[102:105]
	v_mfma_f32_16x16x32_bf16 v[98:101], v[180:183], v[196:199], v[98:101]
	v_mfma_f32_16x16x32_bf16 v[98:101], v[184:187], v[200:203], v[98:101]
	v_mfma_f32_16x16x32_bf16 v[86:89], v[172:175], v[204:207], v[86:89]
	v_mfma_f32_16x16x32_bf16 v[86:89], v[176:179], v[208:211], v[86:89]
	v_mfma_f32_16x16x32_bf16 v[82:85], v[180:183], v[204:207], v[82:85]
	v_mfma_f32_16x16x32_bf16 v[82:85], v[184:187], v[208:211], v[82:85]
	v_mfma_f32_16x16x32_bf16 v[70:73], v[172:175], v[212:215], v[70:73]
	v_mfma_f32_16x16x32_bf16 v[70:73], v[176:179], v[216:219], v[70:73]
	v_mfma_f32_16x16x32_bf16 v[66:69], v[180:183], v[212:215], v[66:69]
	v_mfma_f32_16x16x32_bf16 v[66:69], v[184:187], v[216:219], v[66:69]
	s_barrier
; #define PG8_LDA(dst, b, h) do { _Pragma("unroll") for (int m = 0; m < 4; ++m) _Pragma("unroll") for (int k = 0; k < 2; ++k) dst[m][k] = *(const PG8_LAS bf16x8*)(lds + PG8_SA(b, h) + aoff + m * 2048 + k * 1024); } while (0)
; #define PG8_MMA(ai, bj, At, Bt) do { __builtin_amdgcn_s_setprio(1); _Pragma("unroll") for (int m = 0; m < 4; ++m) _Pragma("unroll") for (int n = 0; n < 2; ++n) _Pragma("unroll") for (int k = 0; k < 2; ++k) \
;         acc[ai][bj][m][n] = __builtin_amdgcn_mfma_f32_16x16x32_bf16(Bt[n][k], At[m][k], acc[ai][bj][m][n], 0, 0, 0); __builtin_amdgcn_s_setprio(0); } while (0)
; #define PG8_WAIT_V(n) asm volatile("s_waitcnt vmcnt(" #n ")" ::: "memory")
; #define PG8_WAIT_L(n) asm volatile("s_waitcnt lgkmcnt(" #n ")" ::: "memory")
; #define PG8_BAR __builtin_amdgcn_s_barrier()
; #define PG8_SCHED __builtin_amdgcn_sched_barrier(0)
; template <class Epi, class Sched, bool ALIGN_EPI = false, bool SP2 = false>
; __device__ __forceinline__ void gemm_phase(PG8_LAS unsigned char* lds, const Gemm g, const Sched& S, const Epi& E, const int tid) {
;     ...
;         for (int t = 0; t < nt; t += 2) {
;     ...
;             PG8_LDA(At, 1, 1); PG8_STAGE(PG8_SB(1, 0), b3, voffB); PG8_STAGE(PG8_SB(1, 1), b3 + hstepB, voffB); PG8_STAGE(PG8_SA(1, 0), a3, voffA);
;             PG8_WAIT_V(8); PG8_WAIT_L(0); PG8_BAR; PG8_MMA(1, 0, At, B0); PG8_MMA(1, 1, At, B1); PG8_BAR; PG8_SCHED;
	s_setprio 1
	ds_read_b128 v[188:191], v155 offset:49152
	ds_read_b128 v[192:195], v155 offset:50176
	ds_read_b128 v[196:199], v155 offset:51200
	ds_read_b128 v[200:203], v155 offset:52224
	ds_read_b128 v[204:207], v155 offset:53248
	ds_read_b128 v[208:211], v155 offset:54272
	ds_read_b128 v[212:215], v155 offset:55296
	ds_read_b128 v[216:219], v155 offset:56320
	s_mov_b32 m0, s55
	s_nop 0
	global_load_lds_dwordx4 v150, s[40:41]
	s_nop 0
	s_mov_b32 m0, s56
	s_nop 0
	global_load_lds_dwordx4 v152, s[40:41]
	s_add_u32 s26, s30, 0x80080
	s_addc_u32 s27, s31, 0
	s_mov_b32 m0, s64
	s_nop 0
	global_load_lds_dwordx4 v150, s[26:27]
	s_nop 0
	s_mov_b32 m0, s65
	s_nop 0
	global_load_lds_dwordx4 v152, s[26:27]
	s_mov_b32 m0, s57
	s_nop 0
	global_load_lds_dwordx4 v149, s[38:39]
	s_nop 0
	s_mov_b32 m0, s61
	s_nop 0
	global_load_lds_dwordx4 v151, s[38:39]
	s_waitcnt vmcnt(8)
	s_waitcnt lgkmcnt(0)
	s_setprio 0
	s_barrier
	v_mfma_f32_16x16x32_bf16 v[62:65], v[156:159], v[188:191], v[62:65]
	v_mfma_f32_16x16x32_bf16 v[62:65], v[160:163], v[192:195], v[62:65]
	v_mfma_f32_16x16x32_bf16 v[58:61], v[164:167], v[188:191], v[58:61]
	v_mfma_f32_16x16x32_bf16 v[58:61], v[168:171], v[192:195], v[58:61]
	v_mfma_f32_16x16x32_bf16 v[46:49], v[156:159], v[196:199], v[46:49]
	v_mfma_f32_16x16x32_bf16 v[46:49], v[160:163], v[200:203], v[46:49]
	v_mfma_f32_16x16x32_bf16 v[42:45], v[164:167], v[196:199], v[42:45]
	v_mfma_f32_16x16x32_bf16 v[42:45], v[168:171], v[200:203], v[42:45]
	v_mfma_f32_16x16x32_bf16 v[30:33], v[156:159], v[204:207], v[30:33]
	v_mfma_f32_16x16x32_bf16 v[30:33], v[160:163], v[208:211], v[30:33]
	v_mfma_f32_16x16x32_bf16 v[26:29], v[164:167], v[204:207], v[26:29]
	v_mfma_f32_16x16x32_bf16 v[26:29], v[168:171], v[208:211], v[26:29]
	v_mfma_f32_16x16x32_bf16 v[14:17], v[156:159], v[212:215], v[14:17]
	v_mfma_f32_16x16x32_bf16 v[14:17], v[160:163], v[216:219], v[14:17]
	v_mfma_f32_16x16x32_bf16 v[10:13], v[164:167], v[212:215], v[10:13]
	v_mfma_f32_16x16x32_bf16 v[10:13], v[168:171], v[216:219], v[10:13]
	v_mfma_f32_16x16x32_bf16 v[54:57], v[172:175], v[188:191], v[54:57]
	v_mfma_f32_16x16x32_bf16 v[54:57], v[176:179], v[192:195], v[54:57]
	v_mfma_f32_16x16x32_bf16 v[50:53], v[180:183], v[188:191], v[50:53]
	v_mfma_f32_16x16x32_bf16 v[50:53], v[184:187], v[192:195], v[50:53]
	v_mfma_f32_16x16x32_bf16 v[38:41], v[172:175], v[196:199], v[38:41]
	v_mfma_f32_16x16x32_bf16 v[38:41], v[176:179], v[200:203], v[38:41]
	v_mfma_f32_16x16x32_bf16 v[34:37], v[180:183], v[196:199], v[34:37]
	v_mfma_f32_16x16x32_bf16 v[34:37], v[184:187], v[200:203], v[34:37]
	v_mfma_f32_16x16x32_bf16 v[22:25], v[172:175], v[204:207], v[22:25]
	v_mfma_f32_16x16x32_bf16 v[22:25], v[176:179], v[208:211], v[22:25]
	v_mfma_f32_16x16x32_bf16 v[18:21], v[180:183], v[204:207], v[18:21]
	v_mfma_f32_16x16x32_bf16 v[18:21], v[184:187], v[208:211], v[18:21]
	v_mfma_f32_16x16x32_bf16 v[6:9], v[172:175], v[212:215], v[6:9]
	v_mfma_f32_16x16x32_bf16 v[6:9], v[176:179], v[216:219], v[6:9]
	v_mfma_f32_16x16x32_bf16 v[2:5], v[180:183], v[212:215], v[2:5]
	v_mfma_f32_16x16x32_bf16 v[2:5], v[184:187], v[216:219], v[2:5]
	s_barrier
	s_add_i32 s11, s11, 2
	s_add_u32 s59, s59, 0x100
	s_addc_u32 s67, s67, 0
	s_cmp_gt_u32 s11, 29
	s_mov_b64 s[26:27], s[34:35]
	s_cbranch_scc1 .LBB0_1073

; #define PG8_LDA(dst, b, h) do { _Pragma("unroll") for (int m = 0; m < 4; ++m) _Pragma("unroll") for (int k = 0; k < 2; ++k) dst[m][k] = *(const PG8_LAS bf16x8*)(lds + PG8_SA(b, h) + aoff + m * 2048 + k * 1024); } while (0)
; #define PG8_LDB(dst, b, h) do { _Pragma("unroll") for (int n = 0; n < 2; ++n) _Pragma("unroll") for (int k = 0; k < 2; ++k) dst[n][k] = *(const PG8_LAS bf16x8*)(lds + PG8_SB(b, h) + boff + n * 2048 + k * 1024); } while (0)
; #define PG8_MMA(ai, bj, At, Bt) do { __builtin_amdgcn_s_setprio(1); _Pragma("unroll") for (int m = 0; m < 4; ++m) _Pragma("unroll") for (int n = 0; n < 2; ++n) _Pragma("unroll") for (int k = 0; k < 2; ++k) \
;         acc[ai][bj][m][n] = __builtin_amdgcn_mfma_f32_16x16x32_bf16(Bt[n][k], At[m][k], acc[ai][bj][m][n], 0, 0, 0); __builtin_amdgcn_s_setprio(0); } while (0)
; #define PG8_WAIT_V(n) asm volatile("s_waitcnt vmcnt(" #n ")" ::: "memory")
; #define PG8_WAIT_L(n) asm volatile("s_waitcnt lgkmcnt(" #n ")" ::: "memory")
; #define PG8_BAR __builtin_amdgcn_s_barrier()
; #define PG8_SCHED __builtin_amdgcn_sched_barrier(0)
; template <class Epi, class Sched, bool ALIGN_EPI = false, bool SP2 = false>
; __device__ __forceinline__ void gemm_phase(PG8_LAS unsigned char* lds, const Gemm g, const Sched& S, const Epi& E, const int tid) {
;     ...
;             const char* a2 = last ? nA : cA + (size_t)(t + 2) * kstepA; const char* b2 = last ? nB : cB + (size_t)(t + 2) * kstepB;
;             const char* a3 = a2 + kstepA; const char* b3 = b2 + kstepB;
;             if (last && has_next) S.a_ready(nxt);
;             if constexpr (SP2) {
;             PG8_LDB(B0, 0, 0); PG8_LDB(B1, 0, 1); PG8_SCHED; PG8_LDA(At, 0, 0); PG8_STAGE(PG8_SA(1, 1), a1 + hstepA, voffA);
;             PG8_WAIT_V(8); PG8_WAIT_L(0); PG8_BAR; PG8_MMA(0, 0, At, B0); PG8_MMA(0, 1, At, B1); PG8_BAR; PG8_SCHED;
;             PG8_LDA(At, 0, 1); PG8_STAGE(PG8_SB(0, 0), b2, voffB); PG8_STAGE(PG8_SB(0, 1), b2 + hstepB, voffB); PG8_STAGE(PG8_SA(0, 0), a2, voffA);
;             PG8_WAIT_V(8); PG8_WAIT_L(0); PG8_BAR; PG8_MMA(1, 0, At, B0); PG8_MMA(1, 1, At, B1); PG8_BAR; PG8_SCHED;
.LBB0_1151:
	v_add_u32_e32 v142, 0x10000, v185
	v_add_u32_e32 v158, 0x14000, v185
	s_setprio 1
	ds_read_b128 v[122:125], v142
	ds_read_b128 v[130:133], v142 offset:1024
	ds_read_b128 v[138:141], v142 offset:2048
	ds_read_b128 v[142:145], v142 offset:3072
	ds_read_b128 v[146:149], v158
	ds_read_b128 v[150:153], v158 offset:1024
	ds_read_b128 v[154:157], v158 offset:2048
	ds_read_b128 v[158:161], v158 offset:3072
	s_cmpk_eq_i32 s89, 0x54
	s_cselect_b32 s34, s26, s83
	s_cselect_b32 s35, s27, s87
	s_cselect_b32 s30, s28, s59
	s_cselect_b32 s31, s29, s67
	s_add_u32 s8, s34, 0x8000
	s_addc_u32 s9, s35, 0
	ds_read_b128 v[162:165], v186
	ds_read_b128 v[166:169], v186 offset:1024
	ds_read_b128 v[170:173], v186 offset:2048
	ds_read_b128 v[174:177], v186 offset:3072
	ds_read_b128 v[188:191], v186 offset:4096
	ds_read_b128 v[192:195], v186 offset:5120
	ds_read_b128 v[196:199], v186 offset:6144
	ds_read_b128 v[200:203], v186 offset:7168
	s_mov_b32 m0, s61
	s_nop 0
	global_load_lds_dwordx4 v0, s[6:7]
	s_nop 0
	s_mov_b32 m0, s64
	s_nop 0
	global_load_lds_dwordx4 v181, s[6:7]
	s_waitcnt vmcnt(8)
	s_waitcnt lgkmcnt(0)
	s_setprio 0
	s_barrier
	v_mfma_f32_16x16x32_bf16 v[134:137], v[122:125], v[162:165], v[134:137]
	v_mfma_f32_16x16x32_bf16 v[134:137], v[130:133], v[166:169], v[134:137]
	v_mfma_f32_16x16x32_bf16 v[126:129], v[138:141], v[162:165], v[126:129]
	v_mfma_f32_16x16x32_bf16 v[126:129], v[142:145], v[166:169], v[126:129]
	v_mfma_f32_16x16x32_bf16 v[110:113], v[122:125], v[170:173], v[110:113]
	v_mfma_f32_16x16x32_bf16 v[110:113], v[130:133], v[174:177], v[110:113]
	v_mfma_f32_16x16x32_bf16 v[106:109], v[138:141], v[170:173], v[106:109]
	v_mfma_f32_16x16x32_bf16 v[106:109], v[142:145], v[174:177], v[106:109]
	v_mfma_f32_16x16x32_bf16 v[94:97], v[122:125], v[188:191], v[94:97]
	v_mfma_f32_16x16x32_bf16 v[94:97], v[130:133], v[192:195], v[94:97]
	v_mfma_f32_16x16x32_bf16 v[90:93], v[138:141], v[188:191], v[90:93]
	v_mfma_f32_16x16x32_bf16 v[90:93], v[142:145], v[192:195], v[90:93]
	v_mfma_f32_16x16x32_bf16 v[78:81], v[122:125], v[196:199], v[78:81]
	v_mfma_f32_16x16x32_bf16 v[78:81], v[130:133], v[200:203], v[78:81]
	v_mfma_f32_16x16x32_bf16 v[74:77], v[138:141], v[196:199], v[74:77]
	v_mfma_f32_16x16x32_bf16 v[74:77], v[142:145], v[200:203], v[74:77]
	v_mfma_f32_16x16x32_bf16 v[118:121], v[146:149], v[162:165], v[118:121]
	v_mfma_f32_16x16x32_bf16 v[118:121], v[150:153], v[166:169], v[118:121]
	v_mfma_f32_16x16x32_bf16 v[114:117], v[154:157], v[162:165], v[114:117]
	v_mfma_f32_16x16x32_bf16 v[114:117], v[158:161], v[166:169], v[114:117]
	v_mfma_f32_16x16x32_bf16 v[102:105], v[146:149], v[170:173], v[102:105]
	v_mfma_f32_16x16x32_bf16 v[102:105], v[150:153], v[174:177], v[102:105]
	v_mfma_f32_16x16x32_bf16 v[98:101], v[154:157], v[170:173], v[98:101]
	v_mfma_f32_16x16x32_bf16 v[98:101], v[158:161], v[174:177], v[98:101]
	v_mfma_f32_16x16x32_bf16 v[86:89], v[146:149], v[188:191], v[86:89]
	v_mfma_f32_16x16x32_bf16 v[86:89], v[150:153], v[192:195], v[86:89]
	v_mfma_f32_16x16x32_bf16 v[82:85], v[154:157], v[188:191], v[82:85]
	v_mfma_f32_16x16x32_bf16 v[82:85], v[158:161], v[192:195], v[82:85]
	v_mfma_f32_16x16x32_bf16 v[70:73], v[146:149], v[196:199], v[70:73]
	v_mfma_f32_16x16x32_bf16 v[70:73], v[150:153], v[200:203], v[70:73]
	v_mfma_f32_16x16x32_bf16 v[66:69], v[154:157], v[196:199], v[66:69]
	v_mfma_f32_16x16x32_bf16 v[66:69], v[158:161], v[200:203], v[66:69]
	s_barrier
	s_setprio 1
	ds_read_b128 v[162:165], v186 offset:16384
	ds_read_b128 v[166:169], v186 offset:17408
	ds_read_b128 v[170:173], v186 offset:18432
	ds_read_b128 v[174:177], v186 offset:19456
	ds_read_b128 v[188:191], v186 offset:20480
	ds_read_b128 v[192:195], v186 offset:21504
	ds_read_b128 v[196:199], v186 offset:22528
	ds_read_b128 v[200:203], v186 offset:23552
	s_mov_b32 m0, s41
	s_nop 0
	global_load_lds_dwordx4 v180, s[30:31]
	s_add_u32 s90, s30, 0x4000
	s_mov_b32 m0, s42
	s_nop 0
	global_load_lds_dwordx4 v182, s[30:31]
	s_addc_u32 s91, s31, 0
	s_mov_b32 m0, s43
	s_nop 0
	global_load_lds_dwordx4 v180, s[90:91]
	s_nop 0
	s_mov_b32 m0, s44
	s_nop 0
	global_load_lds_dwordx4 v182, s[90:91]
	s_nop 0
	s_mov_b32 m0, s10
	s_nop 0
	global_load_lds_dwordx4 v0, s[34:35]
	s_nop 0
	s_mov_b32 m0, s45
	s_nop 0
	global_load_lds_dwordx4 v181, s[34:35]
	s_waitcnt vmcnt(8)
	s_waitcnt lgkmcnt(0)
	s_setprio 0
	s_barrier
	v_mfma_f32_16x16x32_bf16 v[62:65], v[122:125], v[162:165], v[62:65]
	v_mfma_f32_16x16x32_bf16 v[62:65], v[130:133], v[166:169], v[62:65]
	v_mfma_f32_16x16x32_bf16 v[58:61], v[138:141], v[162:165], v[58:61]
	v_mfma_f32_16x16x32_bf16 v[58:61], v[142:145], v[166:169], v[58:61]
	v_mfma_f32_16x16x32_bf16 v[46:49], v[122:125], v[170:173], v[46:49]
	v_mfma_f32_16x16x32_bf16 v[46:49], v[130:133], v[174:177], v[46:49]
	v_mfma_f32_16x16x32_bf16 v[42:45], v[138:141], v[170:173], v[42:45]
	v_mfma_f32_16x16x32_bf16 v[42:45], v[142:145], v[174:177], v[42:45]
	v_mfma_f32_16x16x32_bf16 v[30:33], v[122:125], v[188:191], v[30:33]
	v_mfma_f32_16x16x32_bf16 v[30:33], v[130:133], v[192:195], v[30:33]
	v_mfma_f32_16x16x32_bf16 v[26:29], v[138:141], v[188:191], v[26:29]
	v_mfma_f32_16x16x32_bf16 v[26:29], v[142:145], v[192:195], v[26:29]
	v_mfma_f32_16x16x32_bf16 v[14:17], v[122:125], v[196:199], v[14:17]
	v_mfma_f32_16x16x32_bf16 v[14:17], v[130:133], v[200:203], v[14:17]
	v_mfma_f32_16x16x32_bf16 v[10:13], v[138:141], v[196:199], v[10:13]
	v_mfma_f32_16x16x32_bf16 v[10:13], v[142:145], v[200:203], v[10:13]
	v_mfma_f32_16x16x32_bf16 v[54:57], v[146:149], v[162:165], v[54:57]
	v_mfma_f32_16x16x32_bf16 v[54:57], v[150:153], v[166:169], v[54:57]
	v_mfma_f32_16x16x32_bf16 v[50:53], v[154:157], v[162:165], v[50:53]
	v_mfma_f32_16x16x32_bf16 v[50:53], v[158:161], v[166:169], v[50:53]
	v_mfma_f32_16x16x32_bf16 v[38:41], v[146:149], v[170:173], v[38:41]
	v_mfma_f32_16x16x32_bf16 v[38:41], v[150:153], v[174:177], v[38:41]
	v_mfma_f32_16x16x32_bf16 v[34:37], v[154:157], v[170:173], v[34:37]
	v_mfma_f32_16x16x32_bf16 v[34:37], v[158:161], v[174:177], v[34:37]
	v_mfma_f32_16x16x32_bf16 v[22:25], v[146:149], v[188:191], v[22:25]
	v_mfma_f32_16x16x32_bf16 v[22:25], v[150:153], v[192:195], v[22:25]
	v_mfma_f32_16x16x32_bf16 v[18:21], v[154:157], v[188:191], v[18:21]
	v_mfma_f32_16x16x32_bf16 v[18:21], v[158:161], v[192:195], v[18:21]
	v_mfma_f32_16x16x32_bf16 v[6:9], v[146:149], v[196:199], v[6:9]
	v_mfma_f32_16x16x32_bf16 v[6:9], v[150:153], v[200:203], v[6:9]
	v_mfma_f32_16x16x32_bf16 v[2:5], v[154:157], v[196:199], v[2:5]
	v_mfma_f32_16x16x32_bf16 v[2:5], v[158:161], v[200:203], v[2:5]
	s_barrier
; #define PG8_LDA(dst, b, h) do { _Pragma("unroll") for (int m = 0; m < 4; ++m) _Pragma("unroll") for (int k = 0; k < 2; ++k) dst[m][k] = *(const PG8_LAS bf16x8*)(lds + PG8_SA(b, h) + aoff + m * 2048 + k * 1024); } while (0)
; #define PG8_LDB(dst, b, h) do { _Pragma("unroll") for (int n = 0; n < 2; ++n) _Pragma("unroll") for (int k = 0; k < 2; ++k) dst[n][k] = *(const PG8_LAS bf16x8*)(lds + PG8_SB(b, h) + boff + n * 2048 + k * 1024); } while (0)
; #define PG8_MMA(ai, bj, At, Bt) do { __builtin_amdgcn_s_setprio(1); _Pragma("unroll") for (int m = 0; m < 4; ++m) _Pragma("unroll") for (int n = 0; n < 2; ++n) _Pragma("unroll") for (int k = 0; k < 2; ++k) \
;         acc[ai][bj][m][n] = __builtin_amdgcn_mfma_f32_16x16x32_bf16(Bt[n][k], At[m][k], acc[ai][bj][m][n], 0, 0, 0); __builtin_amdgcn_s_setprio(0); } while (0)
; #define PG8_WAIT_V(n) asm volatile("s_waitcnt vmcnt(" #n ")" ::: "memory")
; #define PG8_WAIT_L(n) asm volatile("s_waitcnt lgkmcnt(" #n ")" ::: "memory")
; #define PG8_BAR __builtin_amdgcn_s_barrier()
; #define PG8_SCHED __builtin_amdgcn_sched_barrier(0)
; template <class Epi, class Sched, bool ALIGN_EPI = false, bool SP2 = false>
; __device__ __forceinline__ void gemm_phase(PG8_LAS unsigned char* lds, const Gemm g, const Sched& S, const Epi& E, const int tid) {
;     ...
;         for (int t = 0; t < nt; t += 2) {
;     ...
;             PG8_LDB(B0, 1, 0); PG8_LDB(B1, 1, 1); PG8_SCHED; PG8_LDA(At, 1, 0); PG8_STAGE(PG8_SA(0, 1), a2 + hstepA, voffA);
;             PG8_WAIT_V(8); PG8_WAIT_L(0); PG8_BAR; PG8_MMA(0, 0, At, B0); PG8_MMA(0, 1, At, B1); PG8_BAR; PG8_SCHED;
;             PG8_LDA(At, 1, 1); PG8_STAGE(PG8_SB(1, 0), b3, voffB); PG8_STAGE(PG8_SB(1, 1), b3 + hstepB, voffB); PG8_STAGE(PG8_SA(1, 0), a3, voffA);
;             PG8_WAIT_V(8); PG8_WAIT_L(0); PG8_BAR; PG8_MMA(1, 0, At, B0); PG8_MMA(1, 1, At, B1); PG8_BAR; PG8_SCHED;
	v_add_u32_e32 v142, 0x18000, v185
	v_add_u32_e32 v158, 0x1c000, v185
	s_setprio 1
	ds_read_b128 v[122:125], v142
	ds_read_b128 v[130:133], v142 offset:1024
	ds_read_b128 v[138:141], v142 offset:2048
	ds_read_b128 v[142:145], v142 offset:3072
	ds_read_b128 v[146:149], v158
	ds_read_b128 v[150:153], v158 offset:1024
	ds_read_b128 v[154:157], v158 offset:2048
	ds_read_b128 v[158:161], v158 offset:3072
	ds_read_b128 v[162:165], v186 offset:32768
	ds_read_b128 v[166:169], v186 offset:33792
	ds_read_b128 v[170:173], v186 offset:34816
	ds_read_b128 v[174:177], v186 offset:35840
	ds_read_b128 v[188:191], v186 offset:36864
	ds_read_b128 v[192:195], v186 offset:37888
	ds_read_b128 v[196:199], v186 offset:38912
	ds_read_b128 v[200:203], v186 offset:39936
	s_add_u32 s34, s34, 0x4000
	s_addc_u32 s35, s35, 0
	s_mov_b32 m0, s46
	s_nop 0
	global_load_lds_dwordx4 v0, s[34:35]
	s_nop 0
	s_mov_b32 m0, s47
	s_nop 0
	global_load_lds_dwordx4 v181, s[34:35]
	s_waitcnt vmcnt(8)
	s_waitcnt lgkmcnt(0)
	s_setprio 0
	s_barrier
	v_mfma_f32_16x16x32_bf16 v[134:137], v[122:125], v[162:165], v[134:137]
	v_mfma_f32_16x16x32_bf16 v[134:137], v[130:133], v[166:169], v[134:137]
	v_mfma_f32_16x16x32_bf16 v[126:129], v[138:141], v[162:165], v[126:129]
	v_mfma_f32_16x16x32_bf16 v[126:129], v[142:145], v[166:169], v[126:129]
	v_mfma_f32_16x16x32_bf16 v[110:113], v[122:125], v[170:173], v[110:113]
	v_mfma_f32_16x16x32_bf16 v[110:113], v[130:133], v[174:177], v[110:113]
	v_mfma_f32_16x16x32_bf16 v[106:109], v[138:141], v[170:173], v[106:109]
	v_mfma_f32_16x16x32_bf16 v[106:109], v[142:145], v[174:177], v[106:109]
	v_mfma_f32_16x16x32_bf16 v[94:97], v[122:125], v[188:191], v[94:97]
	v_mfma_f32_16x16x32_bf16 v[94:97], v[130:133], v[192:195], v[94:97]
	v_mfma_f32_16x16x32_bf16 v[90:93], v[138:141], v[188:191], v[90:93]
	v_mfma_f32_16x16x32_bf16 v[90:93], v[142:145], v[192:195], v[90:93]
	v_mfma_f32_16x16x32_bf16 v[78:81], v[122:125], v[196:199], v[78:81]
	v_mfma_f32_16x16x32_bf16 v[78:81], v[130:133], v[200:203], v[78:81]
	v_mfma_f32_16x16x32_bf16 v[74:77], v[138:141], v[196:199], v[74:77]
	v_mfma_f32_16x16x32_bf16 v[74:77], v[142:145], v[200:203], v[74:77]
	v_mfma_f32_16x16x32_bf16 v[118:121], v[146:149], v[162:165], v[118:121]
	v_mfma_f32_16x16x32_bf16 v[118:121], v[150:153], v[166:169], v[118:121]
	v_mfma_f32_16x16x32_bf16 v[114:117], v[154:157], v[162:165], v[114:117]
	v_mfma_f32_16x16x32_bf16 v[114:117], v[158:161], v[166:169], v[114:117]
	v_mfma_f32_16x16x32_bf16 v[102:105], v[146:149], v[170:173], v[102:105]
	v_mfma_f32_16x16x32_bf16 v[102:105], v[150:153], v[174:177], v[102:105]
	v_mfma_f32_16x16x32_bf16 v[98:101], v[154:157], v[170:173], v[98:101]
	v_mfma_f32_16x16x32_bf16 v[98:101], v[158:161], v[174:177], v[98:101]
	v_mfma_f32_16x16x32_bf16 v[86:89], v[146:149], v[188:191], v[86:89]
	v_mfma_f32_16x16x32_bf16 v[86:89], v[150:153], v[192:195], v[86:89]
	v_mfma_f32_16x16x32_bf16 v[82:85], v[154:157], v[188:191], v[82:85]
	v_mfma_f32_16x16x32_bf16 v[82:85], v[158:161], v[192:195], v[82:85]
	v_mfma_f32_16x16x32_bf16 v[70:73], v[146:149], v[196:199], v[70:73]
	v_mfma_f32_16x16x32_bf16 v[70:73], v[150:153], v[200:203], v[70:73]
	v_mfma_f32_16x16x32_bf16 v[66:69], v[154:157], v[196:199], v[66:69]
	v_mfma_f32_16x16x32_bf16 v[66:69], v[158:161], v[200:203], v[66:69]
	s_barrier
	s_setprio 1
	ds_read_b128 v[162:165], v186 offset:49152
	ds_read_b128 v[166:169], v186 offset:50176
	ds_read_b128 v[170:173], v186 offset:51200
	ds_read_b128 v[174:177], v186 offset:52224
	ds_read_b128 v[188:191], v186 offset:53248
	ds_read_b128 v[192:195], v186 offset:54272
	ds_read_b128 v[196:199], v186 offset:55296
	ds_read_b128 v[200:203], v186 offset:56320
	s_add_u32 s34, s30, 0x8000
	s_addc_u32 s35, s31, 0
	s_mov_b32 m0, s50
	s_nop 0
	global_load_lds_dwordx4 v180, s[34:35]
	s_add_u32 s30, s30, 0xc000
	s_mov_b32 m0, s51
	s_nop 0
	global_load_lds_dwordx4 v182, s[34:35]
	s_addc_u32 s31, s31, 0
	s_mov_b32 m0, s56
	s_nop 0
	global_load_lds_dwordx4 v180, s[30:31]
	s_nop 0
	s_mov_b32 m0, s57
	s_nop 0
	global_load_lds_dwordx4 v182, s[30:31]
	s_mov_b32 m0, s54
	s_nop 0
	global_load_lds_dwordx4 v0, s[8:9]
	s_nop 0
	s_mov_b32 m0, s55
	s_nop 0
	global_load_lds_dwordx4 v181, s[8:9]
	s_waitcnt vmcnt(8)
	s_waitcnt lgkmcnt(0)
	s_setprio 0
	s_barrier
	v_mfma_f32_16x16x32_bf16 v[62:65], v[122:125], v[162:165], v[62:65]
	v_mfma_f32_16x16x32_bf16 v[62:65], v[130:133], v[166:169], v[62:65]
	v_mfma_f32_16x16x32_bf16 v[58:61], v[138:141], v[162:165], v[58:61]
	v_mfma_f32_16x16x32_bf16 v[58:61], v[142:145], v[166:169], v[58:61]
	v_mfma_f32_16x16x32_bf16 v[46:49], v[122:125], v[170:173], v[46:49]
	v_mfma_f32_16x16x32_bf16 v[46:49], v[130:133], v[174:177], v[46:49]
	v_mfma_f32_16x16x32_bf16 v[42:45], v[138:141], v[170:173], v[42:45]
	v_mfma_f32_16x16x32_bf16 v[42:45], v[142:145], v[174:177], v[42:45]
	v_mfma_f32_16x16x32_bf16 v[30:33], v[122:125], v[188:191], v[30:33]
	v_mfma_f32_16x16x32_bf16 v[30:33], v[130:133], v[192:195], v[30:33]
	v_mfma_f32_16x16x32_bf16 v[26:29], v[138:141], v[188:191], v[26:29]
	v_mfma_f32_16x16x32_bf16 v[26:29], v[142:145], v[192:195], v[26:29]
	v_mfma_f32_16x16x32_bf16 v[14:17], v[122:125], v[196:199], v[14:17]
	v_mfma_f32_16x16x32_bf16 v[14:17], v[130:133], v[200:203], v[14:17]
	v_mfma_f32_16x16x32_bf16 v[10:13], v[138:141], v[196:199], v[10:13]
	v_mfma_f32_16x16x32_bf16 v[10:13], v[142:145], v[200:203], v[10:13]
	v_mfma_f32_16x16x32_bf16 v[54:57], v[146:149], v[162:165], v[54:57]
	v_mfma_f32_16x16x32_bf16 v[54:57], v[150:153], v[166:169], v[54:57]
	v_mfma_f32_16x16x32_bf16 v[50:53], v[154:157], v[162:165], v[50:53]
	v_mfma_f32_16x16x32_bf16 v[50:53], v[158:161], v[166:169], v[50:53]
	v_mfma_f32_16x16x32_bf16 v[38:41], v[146:149], v[170:173], v[38:41]
	v_mfma_f32_16x16x32_bf16 v[38:41], v[150:153], v[174:177], v[38:41]
	v_mfma_f32_16x16x32_bf16 v[34:37], v[154:157], v[170:173], v[34:37]
	v_mfma_f32_16x16x32_bf16 v[34:37], v[158:161], v[174:177], v[34:37]
	v_mfma_f32_16x16x32_bf16 v[22:25], v[146:149], v[188:191], v[22:25]
	v_mfma_f32_16x16x32_bf16 v[22:25], v[150:153], v[192:195], v[22:25]
	v_mfma_f32_16x16x32_bf16 v[18:21], v[154:157], v[188:191], v[18:21]
	v_mfma_f32_16x16x32_bf16 v[18:21], v[158:161], v[192:195], v[18:21]
	v_mfma_f32_16x16x32_bf16 v[6:9], v[146:149], v[196:199], v[6:9]
	v_mfma_f32_16x16x32_bf16 v[6:9], v[150:153], v[200:203], v[6:9]
	v_mfma_f32_16x16x32_bf16 v[2:5], v[154:157], v[196:199], v[2:5]
	v_mfma_f32_16x16x32_bf16 v[2:5], v[158:161], v[200:203], v[2:5]
	s_barrier
	s_add_i32 s89, s89, 2
	s_add_u32 s59, s59, 0x10000
	s_addc_u32 s67, s67, 0
	s_add_u32 s83, s83, 0x10000
	s_addc_u32 s87, s87, 0
	s_add_u32 s6, s6, 0x10000
	s_addc_u32 s7, s7, 0
	s_cmpk_gt_u32 s89, 0x55
	s_cbranch_scc0 .LBB0_1151
	s_and_b64 vcc, exec, s[20:21]
	s_cbranch_vccz .LBB0_1154
	s_barrier
